# residual-stream (XB) stores in the five residual epilogues without the nt hint (cacheable for the next phase's reads); on top of v77
# baseline (speedup 1.0000x reference)
.LBB0_150:
	s_mov_b32 s6, -1
	s_lshl_b32 s5, s5, 8
	v_mbcnt_lo_u32_b32 v128, s6, 0
	v_mbcnt_hi_u32_b32 v128, s6, v128
	s_getreg_b32 s6, hwreg(HW_REG_HW_ID, 0, 6)
	s_and_b32 s6, s6, 63
	s_lshl_b32 s6, s6, 2
	s_add_i32 s6, s6, 0
	s_add_i32 s6, s6, 0x20200
	v_mov_b32_e32 v129, s6
	ds_read_b32 v129, v129
	v_bfrev_b32_e32 v130, 0.5
	s_movk_i32 s84, 0x80
	s_lshl_b32 s74, s4, 2
	s_ashr_i32 s75, s74, 31
	s_waitcnt lgkmcnt(0)
	v_readfirstlane_b32 s6, v129
	s_nop 1
	v_lshl_add_u32 v128, s6, 6, v128
	s_nop 0
	v_readfirstlane_b32 s6, v128
	s_bfe_u32 s8, s6, 0x20006
	s_ashr_i32 s6, s6, 2
	s_andn2_b32 s6, s6, 63
	s_add_i32 s6, s6, s5
	v_and_or_b32 v170, v128, 15, s6
	s_lshl_b32 s5, s4, 8
	s_lshl_b32 s6, s8, 5
	v_bfe_u32 v129, v128, 4, 2
	s_or_b32 s5, s6, s5
	v_lshl_or_b32 v168, v129, 3, s5
	v_ashrrev_i32_e32 v169, 31, v168
	v_lshlrev_b64 v[146:147], 1, v[168:169]
	v_ashrrev_i32_e32 v171, 31, v170
	v_lshlrev_b32_e32 v128, 2, v128
	v_lshl_add_u64 v[172:173], s[68:69], 0, v[146:147]
	v_lshlrev_b64 v[148:149], 11, v[170:171]
	v_bitop3_b32 v180, v128, 64, v130 bitop3:0x6c
	v_bitop3_b32 v181, v128, s84, v130 bitop3:0x6c
	v_cmp_eq_u32_e32 vcc, 0, v129
	v_lshl_add_u64 v[128:129], v[172:173], 0, v[148:149]
	global_load_dwordx4 v[142:145], v[128:129], off
	global_load_dwordx4 v[136:139], v[128:129], off offset:256
	v_or_b32_e32 v174, 16, v170
	v_ashrrev_i32_e32 v175, 31, v174
	v_lshlrev_b64 v[176:177], 11, v[174:175]
	v_lshl_add_u64 v[128:129], v[172:173], 0, v[176:177]
	global_load_dwordx4 v[132:135], v[128:129], off
	s_nop 0
	global_load_dwordx4 v[128:131], v[128:129], off offset:256
	s_waitcnt vmcnt(0)
	v_lshlrev_b32_e32 v150, 16, v142
	v_and_b32_e32 v151, 0xffff0000, v142
	v_lshlrev_b32_e32 v142, 16, v143
	v_and_b32_e32 v143, 0xffff0000, v143
	v_lshlrev_b32_e32 v152, 16, v144
	v_and_b32_e32 v153, 0xffff0000, v144
	v_lshlrev_b32_e32 v144, 16, v145
	v_and_b32_e32 v145, 0xffff0000, v145
	v_pk_add_f32 v[124:125], v[124:125], v[150:151]
	v_pk_add_f32 v[126:127], v[126:127], v[142:143]
	v_pk_add_f32 v[142:143], v[122:123], v[144:145]
	v_pk_add_f32 v[122:123], v[120:121], v[152:153]
	v_cvt_pk_bf16_f32 v120, v124, v125
	v_lshl_add_u64 v[124:125], s[68:69], 0, v[148:149]
	v_lshl_add_u64 v[124:125], v[124:125], 0, v[146:147]
	v_cvt_pk_bf16_f32 v121, v126, v127
	v_cvt_pk_bf16_f32 v122, v122, v123
	v_cvt_pk_bf16_f32 v123, v142, v143
	global_store_dwordx4 v[124:125], v[120:123], off
	v_lshlrev_b32_e32 v126, 16, v120
	v_and_b32_e32 v127, 0xffff0000, v138
	v_and_b32_e32 v120, 0xffff0000, v120
	v_mul_f32_e32 v120, v120, v120
	v_fmac_f32_e32 v120, v126, v126
	v_lshlrev_b32_e32 v126, 16, v121
	v_and_b32_e32 v121, 0xffff0000, v121
	v_mul_f32_e32 v121, v121, v121
	v_fmac_f32_e32 v121, v126, v126
	v_add_f32_e32 v120, v120, v121
	v_lshlrev_b32_e32 v121, 16, v122
	v_and_b32_e32 v122, 0xffff0000, v122
	v_mul_f32_e32 v122, v122, v122
	v_fmac_f32_e32 v122, v121, v121
	v_add_f32_e32 v120, v120, v122
	v_and_b32_e32 v122, 0xffff0000, v123
	v_lshlrev_b32_e32 v121, 16, v123
	v_mul_f32_e32 v122, v122, v122
	v_fmac_f32_e32 v122, v121, v121
	v_add_f32_e32 v142, v120, v122
	v_lshlrev_b32_e32 v120, 16, v136
	v_and_b32_e32 v121, 0xffff0000, v136
	v_lshlrev_b32_e32 v122, 16, v137
	v_and_b32_e32 v123, 0xffff0000, v137
	v_lshlrev_b32_e32 v126, 16, v138
	v_lshlrev_b32_e32 v136, 16, v139
	v_and_b32_e32 v137, 0xffff0000, v139
	v_pk_add_f32 v[116:117], v[116:117], v[120:121]
	v_pk_add_f32 v[120:121], v[114:115], v[136:137]
	v_pk_add_f32 v[114:115], v[112:113], v[126:127]
	v_cvt_pk_bf16_f32 v112, v116, v117
	v_pk_add_f32 v[118:119], v[118:119], v[122:123]
	v_lshlrev_b32_e32 v116, 16, v112
	v_cvt_pk_bf16_f32 v113, v118, v119
	v_cvt_pk_bf16_f32 v114, v114, v115
	v_cvt_pk_bf16_f32 v115, v120, v121
	global_store_dwordx4 v[124:125], v[112:115], off offset:256
	s_nop 1
	v_and_b32_e32 v112, 0xffff0000, v112
	v_mul_f32_e32 v112, v112, v112
	v_fmac_f32_e32 v112, v116, v116
	v_lshlrev_b32_e32 v116, 16, v113
	v_and_b32_e32 v113, 0xffff0000, v113
	v_mul_f32_e32 v113, v113, v113
	v_add_f32_e32 v112, v142, v112
	v_fmac_f32_e32 v113, v116, v116
	v_add_f32_e32 v112, v112, v113
	v_lshlrev_b32_e32 v113, 16, v114
	v_and_b32_e32 v114, 0xffff0000, v114
	v_mul_f32_e32 v114, v114, v114
	v_fmac_f32_e32 v114, v113, v113
	v_add_f32_e32 v112, v112, v114
	v_and_b32_e32 v114, 0xffff0000, v115
	v_lshlrev_b32_e32 v113, 16, v115
	v_mul_f32_e32 v114, v114, v114
	v_fmac_f32_e32 v114, v113, v113
	v_add_f32_e32 v112, v112, v114
	v_mov_b32_e32 v113, v112
	s_nop 1
	v_permlane16_swap_b32_e32 v113, v112
	s_waitcnt lgkmcnt(0)
	v_add_f32_e32 v112, v112, v113
	v_mov_b32_e32 v113, v112
	s_nop 1
	v_permlane32_swap_b32_e32 v113, v112
	s_and_saveexec_b64 s[6:7], vcc
	s_cbranch_execz .LBB0_152
	s_waitcnt lgkmcnt(0)
	v_add_f32_e32 v114, v112, v113
	v_lshlrev_b64 v[112:113], 6, v[170:171]
	v_lshl_add_u64 v[112:113], s[48:49], 0, v[112:113]
	v_lshl_add_u64 v[112:113], s[74:75], 2, v[112:113]
	s_lshl_b32 s38, s8, 2
	v_lshl_add_u64 v[112:113], v[112:113], 0, s[38:39]
	flat_store_dword v[112:113], v114
.LBB0_152:
	s_or_b64 exec, exec, s[6:7]
	v_lshlrev_b32_e32 v112, 16, v132
	s_waitcnt lgkmcnt(0)
	v_and_b32_e32 v113, 0xffff0000, v132
	v_lshlrev_b32_e32 v116, 16, v134
	v_and_b32_e32 v117, 0xffff0000, v134
	v_lshlrev_b32_e32 v118, 16, v135
	v_and_b32_e32 v119, 0xffff0000, v135
	v_pk_add_f32 v[108:109], v[108:109], v[112:113]
	v_lshlrev_b32_e32 v114, 16, v133
	v_and_b32_e32 v115, 0xffff0000, v133
	v_pk_add_f32 v[112:113], v[106:107], v[118:119]
	v_pk_add_f32 v[106:107], v[104:105], v[116:117]
	v_cvt_pk_bf16_f32 v104, v108, v109
	v_lshl_add_u64 v[108:109], s[68:69], 0, v[176:177]
	v_pk_add_f32 v[110:111], v[110:111], v[114:115]
	v_lshl_add_u64 v[108:109], v[168:169], 1, v[108:109]
	v_cvt_pk_bf16_f32 v105, v110, v111
	v_cvt_pk_bf16_f32 v106, v106, v107
	v_cvt_pk_bf16_f32 v107, v112, v113
	global_store_dwordx4 v[108:109], v[104:107], off
	v_lshlrev_b32_e32 v110, 16, v104
	v_and_b32_e32 v111, 0xffff0000, v130
	v_and_b32_e32 v104, 0xffff0000, v104
	v_mul_f32_e32 v104, v104, v104
	v_fmac_f32_e32 v104, v110, v110
	v_lshlrev_b32_e32 v110, 16, v105
	v_and_b32_e32 v105, 0xffff0000, v105
	v_mul_f32_e32 v105, v105, v105
	v_fmac_f32_e32 v105, v110, v110
	v_add_f32_e32 v104, v104, v105
	v_lshlrev_b32_e32 v105, 16, v106
	v_and_b32_e32 v106, 0xffff0000, v106
	v_mul_f32_e32 v106, v106, v106
	v_fmac_f32_e32 v106, v105, v105
	v_add_f32_e32 v104, v104, v106
	v_and_b32_e32 v106, 0xffff0000, v107
	v_lshlrev_b32_e32 v105, 16, v107
	v_mul_f32_e32 v106, v106, v106
	v_fmac_f32_e32 v106, v105, v105
	v_add_f32_e32 v114, v104, v106
	v_lshlrev_b32_e32 v104, 16, v128
	v_and_b32_e32 v105, 0xffff0000, v128
	v_lshlrev_b32_e32 v110, 16, v130
	v_lshlrev_b32_e32 v106, 16, v129
	v_and_b32_e32 v107, 0xffff0000, v129
	v_lshlrev_b32_e32 v112, 16, v131
	v_and_b32_e32 v113, 0xffff0000, v131
	v_pk_add_f32 v[100:101], v[100:101], v[104:105]
	v_pk_add_f32 v[96:97], v[96:97], v[110:111]
	v_pk_add_f32 v[102:103], v[102:103], v[106:107]
	v_pk_add_f32 v[104:105], v[98:99], v[112:113]
	v_cvt_pk_bf16_f32 v98, v100, v101
	v_cvt_pk_bf16_f32 v99, v102, v103
	v_cvt_pk_bf16_f32 v100, v96, v97
	s_nop 0
	v_and_b32_e32 v97, 0xffff0000, v98
	v_lshlrev_b32_e32 v96, 16, v98
	v_mul_f32_e32 v97, v97, v97
	v_fmac_f32_e32 v97, v96, v96
	v_and_b32_e32 v102, 0xffff0000, v99
	v_add_f32_e32 v96, v114, v97
	v_lshlrev_b32_e32 v97, 16, v99
	v_mul_f32_e32 v102, v102, v102
	v_fmac_f32_e32 v102, v97, v97
	v_add_f32_e32 v96, v96, v102
	v_and_b32_e32 v102, 0xffff0000, v100
	v_lshlrev_b32_e32 v97, 16, v100
	v_mul_f32_e32 v102, v102, v102
	v_fmac_f32_e32 v102, v97, v97
	v_cvt_pk_bf16_f32 v101, v104, v105
	v_add_f32_e32 v96, v96, v102
	v_and_b32_e32 v102, 0xffff0000, v101
	v_lshlrev_b32_e32 v97, 16, v101
	v_mul_f32_e32 v102, v102, v102
	v_fmac_f32_e32 v102, v97, v97
	v_add_f32_e32 v96, v96, v102
	v_mov_b32_e32 v97, v96
	s_nop 1
	v_permlane16_swap_b32_e32 v97, v96
	global_store_dwordx4 v[108:109], v[98:101], off offset:256
	s_waitcnt lgkmcnt(0)
	v_add_f32_e32 v96, v96, v97
	v_mov_b32_e32 v97, v96
	s_nop 1
	v_permlane32_swap_b32_e32 v97, v96
	s_and_saveexec_b64 s[6:7], vcc
	s_cbranch_execz .LBB0_154
	s_waitcnt lgkmcnt(0)
	v_add_f32_e32 v98, v96, v97
	v_lshlrev_b64 v[96:97], 6, v[174:175]
	v_lshl_add_u64 v[96:97], s[48:49], 0, v[96:97]
	v_lshl_add_u64 v[96:97], s[74:75], 2, v[96:97]
	s_lshl_b32 s38, s8, 2
	v_lshl_add_u64 v[96:97], v[96:97], 0, s[38:39]
	flat_store_dword v[96:97], v98
.LBB0_154:
	s_or_b64 exec, exec, s[6:7]
	v_or_b32_e32 v112, 32, v170
	v_ashrrev_i32_e32 v113, 31, v112
	v_lshlrev_b64 v[118:119], 11, v[112:113]
	s_waitcnt lgkmcnt(0)
	v_lshl_add_u64 v[96:97], v[172:173], 0, v[118:119]
	global_load_dwordx4 v[114:117], v[96:97], off
	global_load_dwordx4 v[104:107], v[96:97], off offset:256
	v_or_b32_e32 v108, 48, v170
	v_ashrrev_i32_e32 v109, 31, v108
	v_lshlrev_b64 v[110:111], 11, v[108:109]
	v_lshl_add_u64 v[96:97], v[172:173], 0, v[110:111]
	global_load_dwordx4 v[100:103], v[96:97], off
	s_nop 0
	global_load_dwordx4 v[96:99], v[96:97], off offset:256
	s_waitcnt vmcnt(0)
	v_lshlrev_b32_e32 v120, 16, v114
	v_and_b32_e32 v121, 0xffff0000, v114
	v_lshlrev_b32_e32 v114, 16, v115
	v_and_b32_e32 v115, 0xffff0000, v115
	v_lshlrev_b32_e32 v122, 16, v116
	v_and_b32_e32 v123, 0xffff0000, v116
	v_lshlrev_b32_e32 v116, 16, v117
	v_and_b32_e32 v117, 0xffff0000, v117
	v_pk_add_f32 v[92:93], v[92:93], v[120:121]
	v_pk_add_f32 v[94:95], v[94:95], v[114:115]
	v_pk_add_f32 v[114:115], v[90:91], v[116:117]
	v_pk_add_f32 v[90:91], v[88:89], v[122:123]
	v_cvt_pk_bf16_f32 v88, v92, v93
	v_lshl_add_u64 v[92:93], s[68:69], 0, v[118:119]
	v_lshl_add_u64 v[92:93], v[168:169], 1, v[92:93]
	v_cvt_pk_bf16_f32 v89, v94, v95
	v_cvt_pk_bf16_f32 v90, v90, v91
	v_cvt_pk_bf16_f32 v91, v114, v115
	global_store_dwordx4 v[92:93], v[88:91], off
	v_lshlrev_b32_e32 v94, 16, v88
	v_and_b32_e32 v95, 0xffff0000, v106
	v_and_b32_e32 v88, 0xffff0000, v88
	v_mul_f32_e32 v88, v88, v88
	v_fmac_f32_e32 v88, v94, v94
	v_lshlrev_b32_e32 v94, 16, v89
	v_and_b32_e32 v89, 0xffff0000, v89
	v_mul_f32_e32 v89, v89, v89
	v_fmac_f32_e32 v89, v94, v94
	v_add_f32_e32 v88, v88, v89
	v_lshlrev_b32_e32 v89, 16, v90
	v_and_b32_e32 v90, 0xffff0000, v90
	v_mul_f32_e32 v90, v90, v90
	v_fmac_f32_e32 v90, v89, v89
	v_add_f32_e32 v88, v88, v90
	v_and_b32_e32 v90, 0xffff0000, v91
	v_lshlrev_b32_e32 v89, 16, v91
	v_mul_f32_e32 v90, v90, v90
	v_fmac_f32_e32 v90, v89, v89
	v_add_f32_e32 v114, v88, v90
	v_lshlrev_b32_e32 v88, 16, v104
	v_and_b32_e32 v89, 0xffff0000, v104
	v_lshlrev_b32_e32 v90, 16, v105
	v_and_b32_e32 v91, 0xffff0000, v105
	v_lshlrev_b32_e32 v94, 16, v106
	v_lshlrev_b32_e32 v104, 16, v107
	v_and_b32_e32 v105, 0xffff0000, v107
	v_pk_add_f32 v[84:85], v[84:85], v[88:89]
	v_pk_add_f32 v[88:89], v[82:83], v[104:105]
	v_pk_add_f32 v[82:83], v[80:81], v[94:95]
	v_cvt_pk_bf16_f32 v80, v84, v85
	v_pk_add_f32 v[86:87], v[86:87], v[90:91]
	v_lshlrev_b32_e32 v84, 16, v80
	v_cvt_pk_bf16_f32 v81, v86, v87
	v_cvt_pk_bf16_f32 v82, v82, v83
	v_cvt_pk_bf16_f32 v83, v88, v89
	global_store_dwordx4 v[92:93], v[80:83], off offset:256
	s_nop 1
	v_and_b32_e32 v80, 0xffff0000, v80
	v_mul_f32_e32 v80, v80, v80
	v_fmac_f32_e32 v80, v84, v84
	v_lshlrev_b32_e32 v84, 16, v81
	v_and_b32_e32 v81, 0xffff0000, v81
	v_mul_f32_e32 v81, v81, v81
	v_add_f32_e32 v80, v114, v80
	v_fmac_f32_e32 v81, v84, v84
	v_add_f32_e32 v80, v80, v81
	v_lshlrev_b32_e32 v81, 16, v82
	v_and_b32_e32 v82, 0xffff0000, v82
	v_mul_f32_e32 v82, v82, v82
	v_fmac_f32_e32 v82, v81, v81
	v_add_f32_e32 v80, v80, v82
	v_and_b32_e32 v82, 0xffff0000, v83
	v_lshlrev_b32_e32 v81, 16, v83
	v_mul_f32_e32 v82, v82, v82
	v_fmac_f32_e32 v82, v81, v81
	v_add_f32_e32 v80, v80, v82
	v_mov_b32_e32 v81, v80
	s_nop 1
	v_permlane16_swap_b32_e32 v81, v80
	s_waitcnt lgkmcnt(0)
	v_add_f32_e32 v80, v80, v81
	v_mov_b32_e32 v81, v80
	s_nop 1
	v_permlane32_swap_b32_e32 v81, v80
	s_mov_b64 s[6:7], exec
	s_and_b64 s[4:5], s[6:7], vcc
	v_mov_b32_e32 v198, v216
	v_mov_b32_e32 v199, v217
	v_mov_b32_e32 v248, v218
	v_mov_b32_e32 v205, v219
	v_mov_b32_e32 v196, v220
	s_mov_b64 exec, s[4:5]
	s_cbranch_execz .LBB0_156
	s_waitcnt lgkmcnt(0)
	v_add_f32_e32 v82, v80, v81
	v_lshlrev_b64 v[80:81], 6, v[112:113]
	v_lshl_add_u64 v[80:81], s[48:49], 0, v[80:81]
	v_lshl_add_u64 v[80:81], s[74:75], 2, v[80:81]
	s_lshl_b32 s38, s8, 2
	v_lshl_add_u64 v[80:81], v[80:81], 0, s[38:39]
	flat_store_dword v[80:81], v82
.LBB0_156:
	s_or_b64 exec, exec, s[6:7]
	v_lshlrev_b32_e32 v80, 16, v100
	s_waitcnt lgkmcnt(0)
	v_and_b32_e32 v81, 0xffff0000, v100
	v_lshlrev_b32_e32 v84, 16, v102
	v_and_b32_e32 v85, 0xffff0000, v102
	v_lshlrev_b32_e32 v86, 16, v103
	v_and_b32_e32 v87, 0xffff0000, v103
	v_pk_add_f32 v[76:77], v[76:77], v[80:81]
	v_lshlrev_b32_e32 v82, 16, v101
	v_and_b32_e32 v83, 0xffff0000, v101
	v_pk_add_f32 v[80:81], v[74:75], v[86:87]
	v_pk_add_f32 v[74:75], v[72:73], v[84:85]
	v_cvt_pk_bf16_f32 v72, v76, v77
	v_lshl_add_u64 v[76:77], s[68:69], 0, v[110:111]
	v_pk_add_f32 v[78:79], v[78:79], v[82:83]
	v_lshl_add_u64 v[76:77], v[168:169], 1, v[76:77]
	v_cvt_pk_bf16_f32 v73, v78, v79
	v_cvt_pk_bf16_f32 v74, v74, v75
	v_cvt_pk_bf16_f32 v75, v80, v81
	global_store_dwordx4 v[76:77], v[72:75], off
	v_lshlrev_b32_e32 v78, 16, v72
	v_and_b32_e32 v79, 0xffff0000, v98
	v_and_b32_e32 v72, 0xffff0000, v72
	v_mul_f32_e32 v72, v72, v72
	v_fmac_f32_e32 v72, v78, v78
	v_lshlrev_b32_e32 v78, 16, v73
	v_and_b32_e32 v73, 0xffff0000, v73
	v_mul_f32_e32 v73, v73, v73
	v_fmac_f32_e32 v73, v78, v78
	v_add_f32_e32 v72, v72, v73
	v_lshlrev_b32_e32 v73, 16, v74
	v_and_b32_e32 v74, 0xffff0000, v74
	v_mul_f32_e32 v74, v74, v74
	v_fmac_f32_e32 v74, v73, v73
	v_add_f32_e32 v72, v72, v74
	v_and_b32_e32 v74, 0xffff0000, v75
	v_lshlrev_b32_e32 v73, 16, v75
	v_mul_f32_e32 v74, v74, v74
	v_fmac_f32_e32 v74, v73, v73
	v_add_f32_e32 v82, v72, v74
	v_lshlrev_b32_e32 v72, 16, v96
	v_and_b32_e32 v73, 0xffff0000, v96
	v_lshlrev_b32_e32 v78, 16, v98
	v_lshlrev_b32_e32 v74, 16, v97
	v_and_b32_e32 v75, 0xffff0000, v97
	v_lshlrev_b32_e32 v80, 16, v99
	v_and_b32_e32 v81, 0xffff0000, v99
	v_pk_add_f32 v[68:69], v[68:69], v[72:73]
	v_pk_add_f32 v[64:65], v[64:65], v[78:79]
	v_pk_add_f32 v[70:71], v[70:71], v[74:75]
	v_pk_add_f32 v[72:73], v[66:67], v[80:81]
	v_cvt_pk_bf16_f32 v66, v68, v69
	v_cvt_pk_bf16_f32 v67, v70, v71
	v_cvt_pk_bf16_f32 v68, v64, v65
	s_nop 0
	v_and_b32_e32 v65, 0xffff0000, v66
	v_lshlrev_b32_e32 v64, 16, v66
	v_mul_f32_e32 v65, v65, v65
	v_fmac_f32_e32 v65, v64, v64
	v_and_b32_e32 v70, 0xffff0000, v67
	v_add_f32_e32 v64, v82, v65
	v_lshlrev_b32_e32 v65, 16, v67
	v_mul_f32_e32 v70, v70, v70
	v_fmac_f32_e32 v70, v65, v65
	v_add_f32_e32 v64, v64, v70
	v_and_b32_e32 v70, 0xffff0000, v68
	v_lshlrev_b32_e32 v65, 16, v68
	v_mul_f32_e32 v70, v70, v70
	v_fmac_f32_e32 v70, v65, v65
	v_cvt_pk_bf16_f32 v69, v72, v73
	v_add_f32_e32 v64, v64, v70
	v_and_b32_e32 v70, 0xffff0000, v69
	v_lshlrev_b32_e32 v65, 16, v69
	v_mul_f32_e32 v70, v70, v70
	v_fmac_f32_e32 v70, v65, v65
	v_add_f32_e32 v64, v64, v70
	v_mov_b32_e32 v65, v64
	s_nop 1
	v_permlane16_swap_b32_e32 v65, v64
	global_store_dwordx4 v[76:77], v[66:69], off offset:256
	s_waitcnt lgkmcnt(0)
	v_add_f32_e32 v64, v64, v65
	v_mov_b32_e32 v65, v64
	s_nop 1
	v_permlane32_swap_b32_e32 v65, v64
	s_and_saveexec_b64 s[6:7], vcc
	s_cbranch_execz .LBB0_158
	s_waitcnt lgkmcnt(0)
	v_add_f32_e32 v66, v64, v65
	v_lshlrev_b64 v[64:65], 6, v[108:109]
	v_lshl_add_u64 v[64:65], s[48:49], 0, v[64:65]
	v_lshl_add_u64 v[64:65], s[74:75], 2, v[64:65]
	s_lshl_b32 s38, s8, 2
	v_lshl_add_u64 v[64:65], v[64:65], 0, s[38:39]
	flat_store_dword v[64:65], v66
.LBB0_158:
	s_or_b64 exec, exec, s[6:7]
	v_add_u32_e32 v80, 0x80, v170
	v_ashrrev_i32_e32 v81, 31, v80
	v_lshlrev_b64 v[86:87], 11, v[80:81]
	s_waitcnt lgkmcnt(0)
	v_lshl_add_u64 v[64:65], v[172:173], 0, v[86:87]
	global_load_dwordx4 v[82:85], v[64:65], off
	global_load_dwordx4 v[72:75], v[64:65], off offset:256
	v_add_u32_e32 v76, 0x90, v170
	v_ashrrev_i32_e32 v77, 31, v76
	v_lshlrev_b64 v[78:79], 11, v[76:77]
	v_lshl_add_u64 v[64:65], v[172:173], 0, v[78:79]
	global_load_dwordx4 v[68:71], v[64:65], off
	s_nop 0
	global_load_dwordx4 v[64:67], v[64:65], off offset:256
	s_waitcnt vmcnt(0)
	v_lshlrev_b32_e32 v88, 16, v82
	v_and_b32_e32 v89, 0xffff0000, v82
	v_lshlrev_b32_e32 v82, 16, v83
	v_and_b32_e32 v83, 0xffff0000, v83
	v_lshlrev_b32_e32 v90, 16, v84
	v_and_b32_e32 v91, 0xffff0000, v84
	v_lshlrev_b32_e32 v84, 16, v85
	v_and_b32_e32 v85, 0xffff0000, v85
	v_pk_add_f32 v[60:61], v[60:61], v[88:89]
	v_pk_add_f32 v[62:63], v[62:63], v[82:83]
	v_pk_add_f32 v[82:83], v[58:59], v[84:85]
	v_pk_add_f32 v[58:59], v[56:57], v[90:91]
	v_cvt_pk_bf16_f32 v56, v60, v61
	v_lshl_add_u64 v[60:61], s[68:69], 0, v[86:87]
	v_lshl_add_u64 v[60:61], v[168:169], 1, v[60:61]
	v_cvt_pk_bf16_f32 v57, v62, v63
	v_cvt_pk_bf16_f32 v58, v58, v59
	v_cvt_pk_bf16_f32 v59, v82, v83
	global_store_dwordx4 v[60:61], v[56:59], off
	v_lshlrev_b32_e32 v62, 16, v56
	v_and_b32_e32 v63, 0xffff0000, v74
	v_and_b32_e32 v56, 0xffff0000, v56
	v_mul_f32_e32 v56, v56, v56
	v_fmac_f32_e32 v56, v62, v62
	v_lshlrev_b32_e32 v62, 16, v57
	v_and_b32_e32 v57, 0xffff0000, v57
	v_mul_f32_e32 v57, v57, v57
	v_fmac_f32_e32 v57, v62, v62
	v_add_f32_e32 v56, v56, v57
	v_lshlrev_b32_e32 v57, 16, v58
	v_and_b32_e32 v58, 0xffff0000, v58
	v_mul_f32_e32 v58, v58, v58
	v_fmac_f32_e32 v58, v57, v57
	v_add_f32_e32 v56, v56, v58
	v_and_b32_e32 v58, 0xffff0000, v59
	v_lshlrev_b32_e32 v57, 16, v59
	v_mul_f32_e32 v58, v58, v58
	v_fmac_f32_e32 v58, v57, v57
	v_add_f32_e32 v82, v56, v58
	v_lshlrev_b32_e32 v56, 16, v72
	v_and_b32_e32 v57, 0xffff0000, v72
	v_lshlrev_b32_e32 v58, 16, v73
	v_and_b32_e32 v59, 0xffff0000, v73
	v_lshlrev_b32_e32 v62, 16, v74
	v_lshlrev_b32_e32 v72, 16, v75
	v_and_b32_e32 v73, 0xffff0000, v75
	v_pk_add_f32 v[52:53], v[52:53], v[56:57]
	v_pk_add_f32 v[56:57], v[50:51], v[72:73]
	v_pk_add_f32 v[50:51], v[48:49], v[62:63]
	v_cvt_pk_bf16_f32 v48, v52, v53
	v_pk_add_f32 v[54:55], v[54:55], v[58:59]
	v_lshlrev_b32_e32 v52, 16, v48
	v_cvt_pk_bf16_f32 v49, v54, v55
	v_cvt_pk_bf16_f32 v50, v50, v51
	v_cvt_pk_bf16_f32 v51, v56, v57
	global_store_dwordx4 v[60:61], v[48:51], off offset:256
	s_nop 1
	v_and_b32_e32 v48, 0xffff0000, v48
	v_mul_f32_e32 v48, v48, v48
	v_fmac_f32_e32 v48, v52, v52
	v_lshlrev_b32_e32 v52, 16, v49
	v_and_b32_e32 v49, 0xffff0000, v49
	v_mul_f32_e32 v49, v49, v49
	v_add_f32_e32 v48, v82, v48
	v_fmac_f32_e32 v49, v52, v52
	v_add_f32_e32 v48, v48, v49
	v_lshlrev_b32_e32 v49, 16, v50
	v_and_b32_e32 v50, 0xffff0000, v50
	v_mul_f32_e32 v50, v50, v50
	v_fmac_f32_e32 v50, v49, v49
	v_add_f32_e32 v48, v48, v50
	v_and_b32_e32 v50, 0xffff0000, v51
	v_lshlrev_b32_e32 v49, 16, v51
	v_mul_f32_e32 v50, v50, v50
	v_fmac_f32_e32 v50, v49, v49
	v_add_f32_e32 v48, v48, v50
	v_mov_b32_e32 v49, v48
	s_nop 1
	v_permlane16_swap_b32_e32 v49, v48
	s_waitcnt lgkmcnt(0)
	v_add_f32_e32 v48, v48, v49
	v_mov_b32_e32 v49, v48
	s_nop 1
	v_permlane32_swap_b32_e32 v49, v48
	s_and_saveexec_b64 s[6:7], vcc
	s_cbranch_execz .LBB0_160
	s_waitcnt lgkmcnt(0)
	v_add_f32_e32 v50, v48, v49
	v_lshlrev_b64 v[48:49], 6, v[80:81]
	v_lshl_add_u64 v[48:49], s[48:49], 0, v[48:49]
	v_lshl_add_u64 v[48:49], s[74:75], 2, v[48:49]
	s_lshl_b32 s38, s8, 2
	v_lshl_add_u64 v[48:49], v[48:49], 0, s[38:39]
	flat_store_dword v[48:49], v50
.LBB0_160:
	s_or_b64 exec, exec, s[6:7]
	v_lshlrev_b32_e32 v48, 16, v68
	s_waitcnt lgkmcnt(0)
	v_and_b32_e32 v49, 0xffff0000, v68
	v_lshlrev_b32_e32 v52, 16, v70
	v_and_b32_e32 v53, 0xffff0000, v70
	v_lshlrev_b32_e32 v54, 16, v71
	v_and_b32_e32 v55, 0xffff0000, v71
	v_pk_add_f32 v[44:45], v[44:45], v[48:49]
	v_lshlrev_b32_e32 v50, 16, v69
	v_and_b32_e32 v51, 0xffff0000, v69
	v_pk_add_f32 v[48:49], v[42:43], v[54:55]
	v_pk_add_f32 v[42:43], v[40:41], v[52:53]
	v_cvt_pk_bf16_f32 v40, v44, v45
	v_lshl_add_u64 v[44:45], s[68:69], 0, v[78:79]
	v_pk_add_f32 v[46:47], v[46:47], v[50:51]
	v_lshl_add_u64 v[44:45], v[168:169], 1, v[44:45]
	v_cvt_pk_bf16_f32 v41, v46, v47
	v_cvt_pk_bf16_f32 v42, v42, v43
	v_cvt_pk_bf16_f32 v43, v48, v49
	global_store_dwordx4 v[44:45], v[40:43], off
	v_lshlrev_b32_e32 v46, 16, v40
	v_and_b32_e32 v47, 0xffff0000, v66
	v_and_b32_e32 v40, 0xffff0000, v40
	v_mul_f32_e32 v40, v40, v40
	v_fmac_f32_e32 v40, v46, v46
	v_lshlrev_b32_e32 v46, 16, v41
	v_and_b32_e32 v41, 0xffff0000, v41
	v_mul_f32_e32 v41, v41, v41
	v_fmac_f32_e32 v41, v46, v46
	v_add_f32_e32 v40, v40, v41
	v_lshlrev_b32_e32 v41, 16, v42
	v_and_b32_e32 v42, 0xffff0000, v42
	v_mul_f32_e32 v42, v42, v42
	v_fmac_f32_e32 v42, v41, v41
	v_add_f32_e32 v40, v40, v42
	v_and_b32_e32 v42, 0xffff0000, v43
	v_lshlrev_b32_e32 v41, 16, v43
	v_mul_f32_e32 v42, v42, v42
	v_fmac_f32_e32 v42, v41, v41
	v_add_f32_e32 v50, v40, v42
	v_lshlrev_b32_e32 v40, 16, v64
	v_and_b32_e32 v41, 0xffff0000, v64
	v_lshlrev_b32_e32 v46, 16, v66
	v_lshlrev_b32_e32 v42, 16, v65
	v_and_b32_e32 v43, 0xffff0000, v65
	v_lshlrev_b32_e32 v48, 16, v67
	v_and_b32_e32 v49, 0xffff0000, v67
	v_pk_add_f32 v[36:37], v[36:37], v[40:41]
	v_pk_add_f32 v[32:33], v[32:33], v[46:47]
	v_pk_add_f32 v[38:39], v[38:39], v[42:43]
	v_pk_add_f32 v[40:41], v[34:35], v[48:49]
	v_cvt_pk_bf16_f32 v34, v36, v37
	v_cvt_pk_bf16_f32 v35, v38, v39
	v_cvt_pk_bf16_f32 v36, v32, v33
	s_nop 0
	v_and_b32_e32 v33, 0xffff0000, v34
	v_lshlrev_b32_e32 v32, 16, v34
	v_mul_f32_e32 v33, v33, v33
	v_fmac_f32_e32 v33, v32, v32
	v_and_b32_e32 v38, 0xffff0000, v35
	v_add_f32_e32 v32, v50, v33
	v_lshlrev_b32_e32 v33, 16, v35
	v_mul_f32_e32 v38, v38, v38
	v_fmac_f32_e32 v38, v33, v33
	v_add_f32_e32 v32, v32, v38
	v_and_b32_e32 v38, 0xffff0000, v36
	v_lshlrev_b32_e32 v33, 16, v36
	v_mul_f32_e32 v38, v38, v38
	v_fmac_f32_e32 v38, v33, v33
	v_cvt_pk_bf16_f32 v37, v40, v41
	v_add_f32_e32 v32, v32, v38
	v_and_b32_e32 v38, 0xffff0000, v37
	v_lshlrev_b32_e32 v33, 16, v37
	v_mul_f32_e32 v38, v38, v38
	v_fmac_f32_e32 v38, v33, v33
	v_add_f32_e32 v32, v32, v38
	v_mov_b32_e32 v33, v32
	s_nop 1
	v_permlane16_swap_b32_e32 v33, v32
	global_store_dwordx4 v[44:45], v[34:37], off offset:256
	s_waitcnt lgkmcnt(0)
	v_add_f32_e32 v32, v32, v33
	v_mov_b32_e32 v33, v32
	s_nop 1
	v_permlane32_swap_b32_e32 v33, v32
	s_and_saveexec_b64 s[6:7], vcc
	s_cbranch_execz .LBB0_162
	s_waitcnt lgkmcnt(0)
	v_add_f32_e32 v34, v32, v33
	v_lshlrev_b64 v[32:33], 6, v[76:77]
	v_lshl_add_u64 v[32:33], s[48:49], 0, v[32:33]
	v_lshl_add_u64 v[32:33], s[74:75], 2, v[32:33]
	s_lshl_b32 s38, s8, 2
	v_lshl_add_u64 v[32:33], v[32:33], 0, s[38:39]
	flat_store_dword v[32:33], v34
.LBB0_162:
	s_or_b64 exec, exec, s[6:7]
	v_add_u32_e32 v48, 0xa0, v170
	v_ashrrev_i32_e32 v49, 31, v48
	v_lshlrev_b64 v[54:55], 11, v[48:49]
	s_waitcnt lgkmcnt(0)
	v_lshl_add_u64 v[32:33], v[172:173], 0, v[54:55]
	global_load_dwordx4 v[50:53], v[32:33], off
	global_load_dwordx4 v[40:43], v[32:33], off offset:256
	v_add_u32_e32 v44, 0xb0, v170
	v_ashrrev_i32_e32 v45, 31, v44
	v_lshlrev_b64 v[46:47], 11, v[44:45]
	v_lshl_add_u64 v[32:33], v[172:173], 0, v[46:47]
	global_load_dwordx4 v[36:39], v[32:33], off
	s_nop 0
	global_load_dwordx4 v[32:35], v[32:33], off offset:256
	s_waitcnt vmcnt(0)
	v_lshlrev_b32_e32 v56, 16, v50
	v_and_b32_e32 v57, 0xffff0000, v50
	v_lshlrev_b32_e32 v50, 16, v51
	v_and_b32_e32 v51, 0xffff0000, v51
	v_lshlrev_b32_e32 v58, 16, v52
	v_and_b32_e32 v59, 0xffff0000, v52
	v_lshlrev_b32_e32 v52, 16, v53
	v_and_b32_e32 v53, 0xffff0000, v53
	v_pk_add_f32 v[28:29], v[28:29], v[56:57]
	v_pk_add_f32 v[30:31], v[30:31], v[50:51]
	v_pk_add_f32 v[50:51], v[26:27], v[52:53]
	v_pk_add_f32 v[26:27], v[24:25], v[58:59]
	v_cvt_pk_bf16_f32 v24, v28, v29
	v_lshl_add_u64 v[28:29], s[68:69], 0, v[54:55]
	v_lshl_add_u64 v[28:29], v[168:169], 1, v[28:29]
	v_cvt_pk_bf16_f32 v25, v30, v31
	v_cvt_pk_bf16_f32 v26, v26, v27
	v_cvt_pk_bf16_f32 v27, v50, v51
	global_store_dwordx4 v[28:29], v[24:27], off
	v_lshlrev_b32_e32 v30, 16, v24
	v_and_b32_e32 v31, 0xffff0000, v42
	v_and_b32_e32 v24, 0xffff0000, v24
	v_mul_f32_e32 v24, v24, v24
	v_fmac_f32_e32 v24, v30, v30
	v_lshlrev_b32_e32 v30, 16, v25
	v_and_b32_e32 v25, 0xffff0000, v25
	v_mul_f32_e32 v25, v25, v25
	v_fmac_f32_e32 v25, v30, v30
	v_add_f32_e32 v24, v24, v25
	v_lshlrev_b32_e32 v25, 16, v26
	v_and_b32_e32 v26, 0xffff0000, v26
	v_mul_f32_e32 v26, v26, v26
	v_fmac_f32_e32 v26, v25, v25
	v_add_f32_e32 v24, v24, v26
	v_and_b32_e32 v26, 0xffff0000, v27
	v_lshlrev_b32_e32 v25, 16, v27
	v_mul_f32_e32 v26, v26, v26
	v_fmac_f32_e32 v26, v25, v25
	v_add_f32_e32 v50, v24, v26
	v_lshlrev_b32_e32 v24, 16, v40
	v_and_b32_e32 v25, 0xffff0000, v40
	v_lshlrev_b32_e32 v26, 16, v41
	v_and_b32_e32 v27, 0xffff0000, v41
	v_lshlrev_b32_e32 v30, 16, v42
	v_lshlrev_b32_e32 v40, 16, v43
	v_and_b32_e32 v41, 0xffff0000, v43
	v_pk_add_f32 v[20:21], v[20:21], v[24:25]
	v_pk_add_f32 v[24:25], v[18:19], v[40:41]
	v_pk_add_f32 v[18:19], v[16:17], v[30:31]
	v_cvt_pk_bf16_f32 v16, v20, v21
	v_pk_add_f32 v[22:23], v[22:23], v[26:27]
	v_lshlrev_b32_e32 v20, 16, v16
	v_cvt_pk_bf16_f32 v17, v22, v23
	v_cvt_pk_bf16_f32 v18, v18, v19
	v_cvt_pk_bf16_f32 v19, v24, v25
	global_store_dwordx4 v[28:29], v[16:19], off offset:256
	s_nop 1
	v_and_b32_e32 v16, 0xffff0000, v16
	v_mul_f32_e32 v16, v16, v16
	v_fmac_f32_e32 v16, v20, v20
	v_lshlrev_b32_e32 v20, 16, v17
	v_and_b32_e32 v17, 0xffff0000, v17
	v_mul_f32_e32 v17, v17, v17
	v_add_f32_e32 v16, v50, v16
	v_fmac_f32_e32 v17, v20, v20
	v_add_f32_e32 v16, v16, v17
	v_lshlrev_b32_e32 v17, 16, v18
	v_and_b32_e32 v18, 0xffff0000, v18
	v_mul_f32_e32 v18, v18, v18
	v_fmac_f32_e32 v18, v17, v17
	v_add_f32_e32 v16, v16, v18
	v_and_b32_e32 v18, 0xffff0000, v19
	v_lshlrev_b32_e32 v17, 16, v19
	v_mul_f32_e32 v18, v18, v18
	v_fmac_f32_e32 v18, v17, v17
	v_add_f32_e32 v16, v16, v18
	v_mov_b32_e32 v17, v16
	s_nop 1
	v_permlane16_swap_b32_e32 v17, v16
	s_waitcnt lgkmcnt(0)
	v_add_f32_e32 v16, v16, v17
	v_mov_b32_e32 v17, v16
	s_nop 1
	v_permlane32_swap_b32_e32 v17, v16
	s_and_saveexec_b64 s[6:7], vcc
	s_cbranch_execz .LBB0_164
	s_waitcnt lgkmcnt(0)
	v_add_f32_e32 v18, v16, v17
	v_lshlrev_b64 v[16:17], 6, v[48:49]
	v_lshl_add_u64 v[16:17], s[48:49], 0, v[16:17]
	v_lshl_add_u64 v[16:17], s[74:75], 2, v[16:17]
	s_lshl_b32 s38, s8, 2
	v_lshl_add_u64 v[16:17], v[16:17], 0, s[38:39]
	flat_store_dword v[16:17], v18
.LBB0_164:
	s_or_b64 exec, exec, s[6:7]
	v_lshlrev_b32_e32 v16, 16, v36
	s_waitcnt lgkmcnt(0)
	v_and_b32_e32 v17, 0xffff0000, v36
	v_lshlrev_b32_e32 v20, 16, v38
	v_and_b32_e32 v21, 0xffff0000, v38
	v_lshlrev_b32_e32 v22, 16, v39
	v_and_b32_e32 v23, 0xffff0000, v39
	v_pk_add_f32 v[12:13], v[12:13], v[16:17]
	v_lshlrev_b32_e32 v18, 16, v37
	v_and_b32_e32 v19, 0xffff0000, v37
	v_pk_add_f32 v[16:17], v[10:11], v[22:23]
	v_pk_add_f32 v[10:11], v[8:9], v[20:21]
	v_cvt_pk_bf16_f32 v8, v12, v13
	v_lshl_add_u64 v[12:13], s[68:69], 0, v[46:47]
	v_pk_add_f32 v[14:15], v[14:15], v[18:19]
	v_lshl_add_u64 v[12:13], v[168:169], 1, v[12:13]
	v_cvt_pk_bf16_f32 v9, v14, v15
	v_cvt_pk_bf16_f32 v10, v10, v11
	v_cvt_pk_bf16_f32 v11, v16, v17
	global_store_dwordx4 v[12:13], v[8:11], off
	v_lshlrev_b32_e32 v14, 16, v8
	v_and_b32_e32 v15, 0xffff0000, v34
	v_and_b32_e32 v8, 0xffff0000, v8
	v_mul_f32_e32 v8, v8, v8
	v_fmac_f32_e32 v8, v14, v14
	v_lshlrev_b32_e32 v14, 16, v9
	v_and_b32_e32 v9, 0xffff0000, v9
	v_mul_f32_e32 v9, v9, v9
	v_fmac_f32_e32 v9, v14, v14
	v_add_f32_e32 v8, v8, v9
	v_lshlrev_b32_e32 v9, 16, v10
	v_and_b32_e32 v10, 0xffff0000, v10
	v_mul_f32_e32 v10, v10, v10
	v_fmac_f32_e32 v10, v9, v9
	v_add_f32_e32 v8, v8, v10
	v_and_b32_e32 v10, 0xffff0000, v11
	v_lshlrev_b32_e32 v9, 16, v11
	v_mul_f32_e32 v10, v10, v10
	v_fmac_f32_e32 v10, v9, v9
	v_add_f32_e32 v18, v8, v10
	v_lshlrev_b32_e32 v8, 16, v32
	v_and_b32_e32 v9, 0xffff0000, v32
	v_lshlrev_b32_e32 v14, 16, v34
	v_lshlrev_b32_e32 v10, 16, v33
	v_and_b32_e32 v11, 0xffff0000, v33
	v_lshlrev_b32_e32 v16, 16, v35
	v_and_b32_e32 v17, 0xffff0000, v35
	v_pk_add_f32 v[4:5], v[4:5], v[8:9]
	v_pk_add_f32 v[0:1], v[0:1], v[14:15]
	v_pk_add_f32 v[6:7], v[6:7], v[10:11]
	v_pk_add_f32 v[8:9], v[2:3], v[16:17]
	v_cvt_pk_bf16_f32 v2, v4, v5
	v_cvt_pk_bf16_f32 v3, v6, v7
	v_cvt_pk_bf16_f32 v4, v0, v1
	s_nop 0
	v_and_b32_e32 v1, 0xffff0000, v2
	v_lshlrev_b32_e32 v0, 16, v2
	v_mul_f32_e32 v1, v1, v1
	v_fmac_f32_e32 v1, v0, v0
	v_and_b32_e32 v6, 0xffff0000, v3
	v_add_f32_e32 v0, v18, v1
	v_lshlrev_b32_e32 v1, 16, v3
	v_mul_f32_e32 v6, v6, v6
	v_fmac_f32_e32 v6, v1, v1
	v_add_f32_e32 v0, v0, v6
	v_and_b32_e32 v6, 0xffff0000, v4
	v_lshlrev_b32_e32 v1, 16, v4
	v_mul_f32_e32 v6, v6, v6
	v_fmac_f32_e32 v6, v1, v1
	v_cvt_pk_bf16_f32 v5, v8, v9
	v_add_f32_e32 v0, v0, v6
	v_and_b32_e32 v6, 0xffff0000, v5
	v_lshlrev_b32_e32 v1, 16, v5
	v_mul_f32_e32 v6, v6, v6
	v_fmac_f32_e32 v6, v1, v1
	v_add_f32_e32 v0, v0, v6
	v_mov_b32_e32 v1, v0
	s_nop 1
	v_permlane16_swap_b32_e32 v1, v0
	global_store_dwordx4 v[12:13], v[2:5], off offset:256
	s_waitcnt lgkmcnt(0)
	v_add_f32_e32 v0, v0, v1
	v_mov_b32_e32 v1, v0
	s_nop 1
	v_permlane32_swap_b32_e32 v1, v0
	s_and_saveexec_b64 s[6:7], vcc
	s_cbranch_execz .LBB0_166
	s_waitcnt lgkmcnt(0)
	v_add_f32_e32 v2, v0, v1
	v_lshlrev_b64 v[0:1], 6, v[44:45]
	v_lshl_add_u64 v[0:1], s[48:49], 0, v[0:1]
	v_lshl_add_u64 v[0:1], s[74:75], 2, v[0:1]
	s_lshl_b32 s38, s8, 2
	v_lshl_add_u64 v[0:1], v[0:1], 0, s[38:39]
	flat_store_dword v[0:1], v2

.LBB0_336:
	s_mov_b32 s6, -1
	s_lshl_b32 s5, s5, 8
	v_mbcnt_lo_u32_b32 v128, s6, 0
	v_mbcnt_hi_u32_b32 v128, s6, v128
	s_getreg_b32 s6, hwreg(HW_REG_HW_ID, 0, 6)
	s_and_b32 s6, s6, 63
	s_lshl_b32 s6, s6, 2
	s_add_i32 s6, s6, 0
	s_add_i32 s6, s6, 0x20200
	v_mov_b32_e32 v129, s6
	ds_read_b32 v129, v129
	v_bfrev_b32_e32 v130, 0.5
	s_lshl_b32 s56, s4, 2
	s_ashr_i32 s57, s56, 31
	s_waitcnt lgkmcnt(0)
	v_readfirstlane_b32 s6, v129
	s_nop 1
	v_lshl_add_u32 v128, s6, 6, v128
	s_nop 0
	v_readfirstlane_b32 s6, v128
	s_bfe_u32 s8, s6, 0x20006
	s_ashr_i32 s6, s6, 2
	s_andn2_b32 s6, s6, 63
	s_add_i32 s6, s6, s5
	v_and_or_b32 v170, v128, 15, s6
	s_lshl_b32 s5, s4, 8
	s_lshl_b32 s6, s8, 5
	v_bfe_u32 v129, v128, 4, 2
	s_or_b32 s5, s6, s5
	v_lshl_or_b32 v168, v129, 3, s5
	v_ashrrev_i32_e32 v169, 31, v168
	v_lshlrev_b64 v[146:147], 1, v[168:169]
	v_ashrrev_i32_e32 v171, 31, v170
	v_lshlrev_b32_e32 v128, 2, v128
	v_lshl_add_u64 v[172:173], s[68:69], 0, v[146:147]
	v_lshlrev_b64 v[148:149], 11, v[170:171]
	v_bitop3_b32 v181, v128, 64, v130 bitop3:0x6c
	v_bitop3_b32 v180, v128, s84, v130 bitop3:0x6c
	v_cmp_eq_u32_e32 vcc, 0, v129
	v_lshl_add_u64 v[128:129], v[172:173], 0, v[148:149]
	global_load_dwordx4 v[142:145], v[128:129], off
	global_load_dwordx4 v[136:139], v[128:129], off offset:256
	v_or_b32_e32 v174, 16, v170
	v_ashrrev_i32_e32 v175, 31, v174
	v_lshlrev_b64 v[176:177], 11, v[174:175]
	v_lshl_add_u64 v[128:129], v[172:173], 0, v[176:177]
	global_load_dwordx4 v[132:135], v[128:129], off
	s_nop 0
	global_load_dwordx4 v[128:131], v[128:129], off offset:256
	s_waitcnt vmcnt(0)
	v_lshlrev_b32_e32 v150, 16, v142
	v_and_b32_e32 v151, 0xffff0000, v142
	v_lshlrev_b32_e32 v142, 16, v143
	v_and_b32_e32 v143, 0xffff0000, v143
	v_lshlrev_b32_e32 v152, 16, v144
	v_and_b32_e32 v153, 0xffff0000, v144
	v_lshlrev_b32_e32 v144, 16, v145
	v_and_b32_e32 v145, 0xffff0000, v145
	v_pk_add_f32 v[124:125], v[124:125], v[150:151]
	v_pk_add_f32 v[126:127], v[126:127], v[142:143]
	v_pk_add_f32 v[142:143], v[122:123], v[144:145]
	v_pk_add_f32 v[122:123], v[120:121], v[152:153]
	v_cvt_pk_bf16_f32 v120, v124, v125
	v_lshl_add_u64 v[124:125], s[68:69], 0, v[148:149]
	v_lshl_add_u64 v[124:125], v[124:125], 0, v[146:147]
	v_cvt_pk_bf16_f32 v121, v126, v127
	v_cvt_pk_bf16_f32 v122, v122, v123
	v_cvt_pk_bf16_f32 v123, v142, v143
	global_store_dwordx4 v[124:125], v[120:123], off
	v_lshlrev_b32_e32 v126, 16, v120
	v_and_b32_e32 v127, 0xffff0000, v138
	v_and_b32_e32 v120, 0xffff0000, v120
	v_mul_f32_e32 v120, v120, v120
	v_fmac_f32_e32 v120, v126, v126
	v_lshlrev_b32_e32 v126, 16, v121
	v_and_b32_e32 v121, 0xffff0000, v121
	v_mul_f32_e32 v121, v121, v121
	v_fmac_f32_e32 v121, v126, v126
	v_add_f32_e32 v120, v120, v121
	v_lshlrev_b32_e32 v121, 16, v122
	v_and_b32_e32 v122, 0xffff0000, v122
	v_mul_f32_e32 v122, v122, v122
	v_fmac_f32_e32 v122, v121, v121
	v_add_f32_e32 v120, v120, v122
	v_and_b32_e32 v122, 0xffff0000, v123
	v_lshlrev_b32_e32 v121, 16, v123
	v_mul_f32_e32 v122, v122, v122
	v_fmac_f32_e32 v122, v121, v121
	v_add_f32_e32 v142, v120, v122
	v_lshlrev_b32_e32 v120, 16, v136
	v_and_b32_e32 v121, 0xffff0000, v136
	v_lshlrev_b32_e32 v122, 16, v137
	v_and_b32_e32 v123, 0xffff0000, v137
	v_lshlrev_b32_e32 v126, 16, v138
	v_lshlrev_b32_e32 v136, 16, v139
	v_and_b32_e32 v137, 0xffff0000, v139
	v_pk_add_f32 v[116:117], v[116:117], v[120:121]
	v_pk_add_f32 v[120:121], v[114:115], v[136:137]
	v_pk_add_f32 v[114:115], v[112:113], v[126:127]
	v_cvt_pk_bf16_f32 v112, v116, v117
	v_pk_add_f32 v[118:119], v[118:119], v[122:123]
	v_lshlrev_b32_e32 v116, 16, v112
	v_cvt_pk_bf16_f32 v113, v118, v119
	v_cvt_pk_bf16_f32 v114, v114, v115
	v_cvt_pk_bf16_f32 v115, v120, v121
	global_store_dwordx4 v[124:125], v[112:115], off offset:256
	s_nop 1
	v_and_b32_e32 v112, 0xffff0000, v112
	v_mul_f32_e32 v112, v112, v112
	v_fmac_f32_e32 v112, v116, v116
	v_lshlrev_b32_e32 v116, 16, v113
	v_and_b32_e32 v113, 0xffff0000, v113
	v_mul_f32_e32 v113, v113, v113
	v_add_f32_e32 v112, v142, v112
	v_fmac_f32_e32 v113, v116, v116
	v_add_f32_e32 v112, v112, v113
	v_lshlrev_b32_e32 v113, 16, v114
	v_and_b32_e32 v114, 0xffff0000, v114
	v_mul_f32_e32 v114, v114, v114
	v_fmac_f32_e32 v114, v113, v113
	v_add_f32_e32 v112, v112, v114
	v_and_b32_e32 v114, 0xffff0000, v115
	v_lshlrev_b32_e32 v113, 16, v115
	v_mul_f32_e32 v114, v114, v114
	v_fmac_f32_e32 v114, v113, v113
	v_add_f32_e32 v112, v112, v114
	v_mov_b32_e32 v113, v112
	s_nop 1
	v_permlane16_swap_b32_e32 v113, v112
	s_waitcnt lgkmcnt(0)
	v_add_f32_e32 v112, v112, v113
	v_mov_b32_e32 v113, v112
	s_nop 1
	v_permlane32_swap_b32_e32 v113, v112
	s_and_saveexec_b64 s[6:7], vcc
	s_cbranch_execz .LBB0_338
	s_waitcnt lgkmcnt(0)
	v_add_f32_e32 v114, v112, v113
	v_lshlrev_b64 v[112:113], 6, v[170:171]
	v_lshl_add_u64 v[112:113], s[46:47], 0, v[112:113]
	v_lshl_add_u64 v[112:113], s[56:57], 2, v[112:113]
	s_lshl_b32 s38, s8, 2
	v_lshl_add_u64 v[112:113], v[112:113], 0, s[38:39]
	flat_store_dword v[112:113], v114
.LBB0_338:
	s_or_b64 exec, exec, s[6:7]
	v_lshlrev_b32_e32 v112, 16, v132
	s_waitcnt lgkmcnt(0)
	v_and_b32_e32 v113, 0xffff0000, v132
	v_lshlrev_b32_e32 v116, 16, v134
	v_and_b32_e32 v117, 0xffff0000, v134
	v_lshlrev_b32_e32 v118, 16, v135
	v_and_b32_e32 v119, 0xffff0000, v135
	v_pk_add_f32 v[108:109], v[108:109], v[112:113]
	v_lshlrev_b32_e32 v114, 16, v133
	v_and_b32_e32 v115, 0xffff0000, v133
	v_pk_add_f32 v[112:113], v[106:107], v[118:119]
	v_pk_add_f32 v[106:107], v[104:105], v[116:117]
	v_cvt_pk_bf16_f32 v104, v108, v109
	v_lshl_add_u64 v[108:109], s[68:69], 0, v[176:177]
	v_pk_add_f32 v[110:111], v[110:111], v[114:115]
	v_lshl_add_u64 v[108:109], v[168:169], 1, v[108:109]
	v_cvt_pk_bf16_f32 v105, v110, v111
	v_cvt_pk_bf16_f32 v106, v106, v107
	v_cvt_pk_bf16_f32 v107, v112, v113
	global_store_dwordx4 v[108:109], v[104:107], off
	v_lshlrev_b32_e32 v110, 16, v104
	v_and_b32_e32 v111, 0xffff0000, v130
	v_and_b32_e32 v104, 0xffff0000, v104
	v_mul_f32_e32 v104, v104, v104
	v_fmac_f32_e32 v104, v110, v110
	v_lshlrev_b32_e32 v110, 16, v105
	v_and_b32_e32 v105, 0xffff0000, v105
	v_mul_f32_e32 v105, v105, v105
	v_fmac_f32_e32 v105, v110, v110
	v_add_f32_e32 v104, v104, v105
	v_lshlrev_b32_e32 v105, 16, v106
	v_and_b32_e32 v106, 0xffff0000, v106
	v_mul_f32_e32 v106, v106, v106
	v_fmac_f32_e32 v106, v105, v105
	v_add_f32_e32 v104, v104, v106
	v_and_b32_e32 v106, 0xffff0000, v107
	v_lshlrev_b32_e32 v105, 16, v107
	v_mul_f32_e32 v106, v106, v106
	v_fmac_f32_e32 v106, v105, v105
	v_add_f32_e32 v114, v104, v106
	v_lshlrev_b32_e32 v104, 16, v128
	v_and_b32_e32 v105, 0xffff0000, v128
	v_lshlrev_b32_e32 v110, 16, v130
	v_lshlrev_b32_e32 v106, 16, v129
	v_and_b32_e32 v107, 0xffff0000, v129
	v_lshlrev_b32_e32 v112, 16, v131
	v_and_b32_e32 v113, 0xffff0000, v131
	v_pk_add_f32 v[100:101], v[100:101], v[104:105]
	v_pk_add_f32 v[96:97], v[96:97], v[110:111]
	v_pk_add_f32 v[102:103], v[102:103], v[106:107]
	v_pk_add_f32 v[104:105], v[98:99], v[112:113]
	v_cvt_pk_bf16_f32 v98, v100, v101
	v_cvt_pk_bf16_f32 v99, v102, v103
	v_cvt_pk_bf16_f32 v100, v96, v97
	s_nop 0
	v_and_b32_e32 v97, 0xffff0000, v98
	v_lshlrev_b32_e32 v96, 16, v98
	v_mul_f32_e32 v97, v97, v97
	v_fmac_f32_e32 v97, v96, v96
	v_and_b32_e32 v102, 0xffff0000, v99
	v_add_f32_e32 v96, v114, v97
	v_lshlrev_b32_e32 v97, 16, v99
	v_mul_f32_e32 v102, v102, v102
	v_fmac_f32_e32 v102, v97, v97
	v_add_f32_e32 v96, v96, v102
	v_and_b32_e32 v102, 0xffff0000, v100
	v_lshlrev_b32_e32 v97, 16, v100
	v_mul_f32_e32 v102, v102, v102
	v_fmac_f32_e32 v102, v97, v97
	v_cvt_pk_bf16_f32 v101, v104, v105
	v_add_f32_e32 v96, v96, v102
	v_and_b32_e32 v102, 0xffff0000, v101
	v_lshlrev_b32_e32 v97, 16, v101
	v_mul_f32_e32 v102, v102, v102
	v_fmac_f32_e32 v102, v97, v97
	v_add_f32_e32 v96, v96, v102
	v_mov_b32_e32 v97, v96
	s_nop 1
	v_permlane16_swap_b32_e32 v97, v96
	global_store_dwordx4 v[108:109], v[98:101], off offset:256
	s_waitcnt lgkmcnt(0)
	v_add_f32_e32 v96, v96, v97
	v_mov_b32_e32 v97, v96
	s_nop 1
	v_permlane32_swap_b32_e32 v97, v96
	s_and_saveexec_b64 s[6:7], vcc
	s_cbranch_execz .LBB0_340
	s_waitcnt lgkmcnt(0)
	v_add_f32_e32 v98, v96, v97
	v_lshlrev_b64 v[96:97], 6, v[174:175]
	v_lshl_add_u64 v[96:97], s[46:47], 0, v[96:97]
	v_lshl_add_u64 v[96:97], s[56:57], 2, v[96:97]
	s_lshl_b32 s38, s8, 2
	v_lshl_add_u64 v[96:97], v[96:97], 0, s[38:39]
	flat_store_dword v[96:97], v98
.LBB0_340:
	s_or_b64 exec, exec, s[6:7]
	v_or_b32_e32 v112, 32, v170
	v_ashrrev_i32_e32 v113, 31, v112
	v_lshlrev_b64 v[118:119], 11, v[112:113]
	s_waitcnt lgkmcnt(0)
	v_lshl_add_u64 v[96:97], v[172:173], 0, v[118:119]
	global_load_dwordx4 v[114:117], v[96:97], off
	global_load_dwordx4 v[104:107], v[96:97], off offset:256
	v_or_b32_e32 v108, 48, v170
	v_ashrrev_i32_e32 v109, 31, v108
	v_lshlrev_b64 v[110:111], 11, v[108:109]
	v_lshl_add_u64 v[96:97], v[172:173], 0, v[110:111]
	global_load_dwordx4 v[100:103], v[96:97], off
	s_nop 0
	global_load_dwordx4 v[96:99], v[96:97], off offset:256
	s_waitcnt vmcnt(0)
	v_lshlrev_b32_e32 v120, 16, v114
	v_and_b32_e32 v121, 0xffff0000, v114
	v_lshlrev_b32_e32 v114, 16, v115
	v_and_b32_e32 v115, 0xffff0000, v115
	v_lshlrev_b32_e32 v122, 16, v116
	v_and_b32_e32 v123, 0xffff0000, v116
	v_lshlrev_b32_e32 v116, 16, v117
	v_and_b32_e32 v117, 0xffff0000, v117
	v_pk_add_f32 v[92:93], v[92:93], v[120:121]
	v_pk_add_f32 v[94:95], v[94:95], v[114:115]
	v_pk_add_f32 v[114:115], v[90:91], v[116:117]
	v_pk_add_f32 v[90:91], v[88:89], v[122:123]
	v_cvt_pk_bf16_f32 v88, v92, v93
	v_lshl_add_u64 v[92:93], s[68:69], 0, v[118:119]
	v_lshl_add_u64 v[92:93], v[168:169], 1, v[92:93]
	v_cvt_pk_bf16_f32 v89, v94, v95
	v_cvt_pk_bf16_f32 v90, v90, v91
	v_cvt_pk_bf16_f32 v91, v114, v115
	global_store_dwordx4 v[92:93], v[88:91], off
	v_lshlrev_b32_e32 v94, 16, v88
	v_and_b32_e32 v95, 0xffff0000, v106
	v_and_b32_e32 v88, 0xffff0000, v88
	v_mul_f32_e32 v88, v88, v88
	v_fmac_f32_e32 v88, v94, v94
	v_lshlrev_b32_e32 v94, 16, v89
	v_and_b32_e32 v89, 0xffff0000, v89
	v_mul_f32_e32 v89, v89, v89
	v_fmac_f32_e32 v89, v94, v94
	v_add_f32_e32 v88, v88, v89
	v_lshlrev_b32_e32 v89, 16, v90
	v_and_b32_e32 v90, 0xffff0000, v90
	v_mul_f32_e32 v90, v90, v90
	v_fmac_f32_e32 v90, v89, v89
	v_add_f32_e32 v88, v88, v90
	v_and_b32_e32 v90, 0xffff0000, v91
	v_lshlrev_b32_e32 v89, 16, v91
	v_mul_f32_e32 v90, v90, v90
	v_fmac_f32_e32 v90, v89, v89
	v_add_f32_e32 v114, v88, v90
	v_lshlrev_b32_e32 v88, 16, v104
	v_and_b32_e32 v89, 0xffff0000, v104
	v_lshlrev_b32_e32 v90, 16, v105
	v_and_b32_e32 v91, 0xffff0000, v105
	v_lshlrev_b32_e32 v94, 16, v106
	v_lshlrev_b32_e32 v104, 16, v107
	v_and_b32_e32 v105, 0xffff0000, v107
	v_pk_add_f32 v[84:85], v[84:85], v[88:89]
	v_pk_add_f32 v[88:89], v[82:83], v[104:105]
	v_pk_add_f32 v[82:83], v[80:81], v[94:95]
	v_cvt_pk_bf16_f32 v80, v84, v85
	v_pk_add_f32 v[86:87], v[86:87], v[90:91]
	v_lshlrev_b32_e32 v84, 16, v80
	v_cvt_pk_bf16_f32 v81, v86, v87
	v_cvt_pk_bf16_f32 v82, v82, v83
	v_cvt_pk_bf16_f32 v83, v88, v89
	global_store_dwordx4 v[92:93], v[80:83], off offset:256
	s_nop 1
	v_and_b32_e32 v80, 0xffff0000, v80
	v_mul_f32_e32 v80, v80, v80
	v_fmac_f32_e32 v80, v84, v84
	v_lshlrev_b32_e32 v84, 16, v81
	v_and_b32_e32 v81, 0xffff0000, v81
	v_mul_f32_e32 v81, v81, v81
	v_add_f32_e32 v80, v114, v80
	v_fmac_f32_e32 v81, v84, v84
	v_add_f32_e32 v80, v80, v81
	v_lshlrev_b32_e32 v81, 16, v82
	v_and_b32_e32 v82, 0xffff0000, v82
	v_mul_f32_e32 v82, v82, v82
	v_fmac_f32_e32 v82, v81, v81
	v_add_f32_e32 v80, v80, v82
	v_and_b32_e32 v82, 0xffff0000, v83
	v_lshlrev_b32_e32 v81, 16, v83
	v_mul_f32_e32 v82, v82, v82
	v_fmac_f32_e32 v82, v81, v81
	v_add_f32_e32 v80, v80, v82
	v_mov_b32_e32 v81, v80
	s_nop 1
	v_permlane16_swap_b32_e32 v81, v80
	s_waitcnt lgkmcnt(0)
	v_add_f32_e32 v80, v80, v81
	v_mov_b32_e32 v81, v80
	s_nop 1
	v_permlane32_swap_b32_e32 v81, v80
	s_mov_b64 s[6:7], exec
	s_and_b64 s[4:5], s[6:7], vcc
	v_mov_b32_e32 v198, v216
	v_mov_b32_e32 v199, v217
	v_mov_b32_e32 v248, v218
	v_mov_b32_e32 v205, v219
	v_mov_b32_e32 v196, v220
	s_mov_b64 exec, s[4:5]
	s_cbranch_execz .LBB0_342
	s_waitcnt lgkmcnt(0)
	v_add_f32_e32 v82, v80, v81
	v_lshlrev_b64 v[80:81], 6, v[112:113]
	v_lshl_add_u64 v[80:81], s[46:47], 0, v[80:81]
	v_lshl_add_u64 v[80:81], s[56:57], 2, v[80:81]
	s_lshl_b32 s38, s8, 2
	v_lshl_add_u64 v[80:81], v[80:81], 0, s[38:39]
	flat_store_dword v[80:81], v82
.LBB0_342:
	s_or_b64 exec, exec, s[6:7]
	v_lshlrev_b32_e32 v80, 16, v100
	s_waitcnt lgkmcnt(0)
	v_and_b32_e32 v81, 0xffff0000, v100
	v_lshlrev_b32_e32 v84, 16, v102
	v_and_b32_e32 v85, 0xffff0000, v102
	v_lshlrev_b32_e32 v86, 16, v103
	v_and_b32_e32 v87, 0xffff0000, v103
	v_pk_add_f32 v[76:77], v[76:77], v[80:81]
	v_lshlrev_b32_e32 v82, 16, v101
	v_and_b32_e32 v83, 0xffff0000, v101
	v_pk_add_f32 v[80:81], v[74:75], v[86:87]
	v_pk_add_f32 v[74:75], v[72:73], v[84:85]
	v_cvt_pk_bf16_f32 v72, v76, v77
	v_lshl_add_u64 v[76:77], s[68:69], 0, v[110:111]
	v_pk_add_f32 v[78:79], v[78:79], v[82:83]
	v_lshl_add_u64 v[76:77], v[168:169], 1, v[76:77]
	v_cvt_pk_bf16_f32 v73, v78, v79
	v_cvt_pk_bf16_f32 v74, v74, v75
	v_cvt_pk_bf16_f32 v75, v80, v81
	global_store_dwordx4 v[76:77], v[72:75], off
	v_lshlrev_b32_e32 v78, 16, v72
	v_and_b32_e32 v79, 0xffff0000, v98
	v_and_b32_e32 v72, 0xffff0000, v72
	v_mul_f32_e32 v72, v72, v72
	v_fmac_f32_e32 v72, v78, v78
	v_lshlrev_b32_e32 v78, 16, v73
	v_and_b32_e32 v73, 0xffff0000, v73
	v_mul_f32_e32 v73, v73, v73
	v_fmac_f32_e32 v73, v78, v78
	v_add_f32_e32 v72, v72, v73
	v_lshlrev_b32_e32 v73, 16, v74
	v_and_b32_e32 v74, 0xffff0000, v74
	v_mul_f32_e32 v74, v74, v74
	v_fmac_f32_e32 v74, v73, v73
	v_add_f32_e32 v72, v72, v74
	v_and_b32_e32 v74, 0xffff0000, v75
	v_lshlrev_b32_e32 v73, 16, v75
	v_mul_f32_e32 v74, v74, v74
	v_fmac_f32_e32 v74, v73, v73
	v_add_f32_e32 v82, v72, v74
	v_lshlrev_b32_e32 v72, 16, v96
	v_and_b32_e32 v73, 0xffff0000, v96
	v_lshlrev_b32_e32 v78, 16, v98
	v_lshlrev_b32_e32 v74, 16, v97
	v_and_b32_e32 v75, 0xffff0000, v97
	v_lshlrev_b32_e32 v80, 16, v99
	v_and_b32_e32 v81, 0xffff0000, v99
	v_pk_add_f32 v[68:69], v[68:69], v[72:73]
	v_pk_add_f32 v[64:65], v[64:65], v[78:79]
	v_pk_add_f32 v[70:71], v[70:71], v[74:75]
	v_pk_add_f32 v[72:73], v[66:67], v[80:81]
	v_cvt_pk_bf16_f32 v66, v68, v69
	v_cvt_pk_bf16_f32 v67, v70, v71
	v_cvt_pk_bf16_f32 v68, v64, v65
	s_nop 0
	v_and_b32_e32 v65, 0xffff0000, v66
	v_lshlrev_b32_e32 v64, 16, v66
	v_mul_f32_e32 v65, v65, v65
	v_fmac_f32_e32 v65, v64, v64
	v_and_b32_e32 v70, 0xffff0000, v67
	v_add_f32_e32 v64, v82, v65
	v_lshlrev_b32_e32 v65, 16, v67
	v_mul_f32_e32 v70, v70, v70
	v_fmac_f32_e32 v70, v65, v65
	v_add_f32_e32 v64, v64, v70
	v_and_b32_e32 v70, 0xffff0000, v68
	v_lshlrev_b32_e32 v65, 16, v68
	v_mul_f32_e32 v70, v70, v70
	v_fmac_f32_e32 v70, v65, v65
	v_cvt_pk_bf16_f32 v69, v72, v73
	v_add_f32_e32 v64, v64, v70
	v_and_b32_e32 v70, 0xffff0000, v69
	v_lshlrev_b32_e32 v65, 16, v69
	v_mul_f32_e32 v70, v70, v70
	v_fmac_f32_e32 v70, v65, v65
	v_add_f32_e32 v64, v64, v70
	v_mov_b32_e32 v65, v64
	s_nop 1
	v_permlane16_swap_b32_e32 v65, v64
	global_store_dwordx4 v[76:77], v[66:69], off offset:256
	s_waitcnt lgkmcnt(0)
	v_add_f32_e32 v64, v64, v65
	v_mov_b32_e32 v65, v64
	s_nop 1
	v_permlane32_swap_b32_e32 v65, v64
	s_and_saveexec_b64 s[6:7], vcc
	s_cbranch_execz .LBB0_344
	s_waitcnt lgkmcnt(0)
	v_add_f32_e32 v66, v64, v65
	v_lshlrev_b64 v[64:65], 6, v[108:109]
	v_lshl_add_u64 v[64:65], s[46:47], 0, v[64:65]
	v_lshl_add_u64 v[64:65], s[56:57], 2, v[64:65]
	s_lshl_b32 s38, s8, 2
	v_lshl_add_u64 v[64:65], v[64:65], 0, s[38:39]
	flat_store_dword v[64:65], v66
.LBB0_344:
	s_or_b64 exec, exec, s[6:7]
	v_add_u32_e32 v80, 0x80, v170
	v_ashrrev_i32_e32 v81, 31, v80
	v_lshlrev_b64 v[86:87], 11, v[80:81]
	s_waitcnt lgkmcnt(0)
	v_lshl_add_u64 v[64:65], v[172:173], 0, v[86:87]
	global_load_dwordx4 v[82:85], v[64:65], off
	global_load_dwordx4 v[72:75], v[64:65], off offset:256
	v_add_u32_e32 v76, 0x90, v170
	v_ashrrev_i32_e32 v77, 31, v76
	v_lshlrev_b64 v[78:79], 11, v[76:77]
	v_lshl_add_u64 v[64:65], v[172:173], 0, v[78:79]
	global_load_dwordx4 v[68:71], v[64:65], off
	s_nop 0
	global_load_dwordx4 v[64:67], v[64:65], off offset:256
	s_waitcnt vmcnt(0)
	v_lshlrev_b32_e32 v88, 16, v82
	v_and_b32_e32 v89, 0xffff0000, v82
	v_lshlrev_b32_e32 v82, 16, v83
	v_and_b32_e32 v83, 0xffff0000, v83
	v_lshlrev_b32_e32 v90, 16, v84
	v_and_b32_e32 v91, 0xffff0000, v84
	v_lshlrev_b32_e32 v84, 16, v85
	v_and_b32_e32 v85, 0xffff0000, v85
	v_pk_add_f32 v[60:61], v[60:61], v[88:89]
	v_pk_add_f32 v[62:63], v[62:63], v[82:83]
	v_pk_add_f32 v[82:83], v[58:59], v[84:85]
	v_pk_add_f32 v[58:59], v[56:57], v[90:91]
	v_cvt_pk_bf16_f32 v56, v60, v61
	v_lshl_add_u64 v[60:61], s[68:69], 0, v[86:87]
	v_lshl_add_u64 v[60:61], v[168:169], 1, v[60:61]
	v_cvt_pk_bf16_f32 v57, v62, v63
	v_cvt_pk_bf16_f32 v58, v58, v59
	v_cvt_pk_bf16_f32 v59, v82, v83
	global_store_dwordx4 v[60:61], v[56:59], off
	v_lshlrev_b32_e32 v62, 16, v56
	v_and_b32_e32 v63, 0xffff0000, v74
	v_and_b32_e32 v56, 0xffff0000, v56
	v_mul_f32_e32 v56, v56, v56
	v_fmac_f32_e32 v56, v62, v62
	v_lshlrev_b32_e32 v62, 16, v57
	v_and_b32_e32 v57, 0xffff0000, v57
	v_mul_f32_e32 v57, v57, v57
	v_fmac_f32_e32 v57, v62, v62
	v_add_f32_e32 v56, v56, v57
	v_lshlrev_b32_e32 v57, 16, v58
	v_and_b32_e32 v58, 0xffff0000, v58
	v_mul_f32_e32 v58, v58, v58
	v_fmac_f32_e32 v58, v57, v57
	v_add_f32_e32 v56, v56, v58
	v_and_b32_e32 v58, 0xffff0000, v59
	v_lshlrev_b32_e32 v57, 16, v59
	v_mul_f32_e32 v58, v58, v58
	v_fmac_f32_e32 v58, v57, v57
	v_add_f32_e32 v82, v56, v58
	v_lshlrev_b32_e32 v56, 16, v72
	v_and_b32_e32 v57, 0xffff0000, v72
	v_lshlrev_b32_e32 v58, 16, v73
	v_and_b32_e32 v59, 0xffff0000, v73
	v_lshlrev_b32_e32 v62, 16, v74
	v_lshlrev_b32_e32 v72, 16, v75
	v_and_b32_e32 v73, 0xffff0000, v75
	v_pk_add_f32 v[52:53], v[52:53], v[56:57]
	v_pk_add_f32 v[56:57], v[50:51], v[72:73]
	v_pk_add_f32 v[50:51], v[48:49], v[62:63]
	v_cvt_pk_bf16_f32 v48, v52, v53
	v_pk_add_f32 v[54:55], v[54:55], v[58:59]
	v_lshlrev_b32_e32 v52, 16, v48
	v_cvt_pk_bf16_f32 v49, v54, v55
	v_cvt_pk_bf16_f32 v50, v50, v51
	v_cvt_pk_bf16_f32 v51, v56, v57
	global_store_dwordx4 v[60:61], v[48:51], off offset:256
	s_nop 1
	v_and_b32_e32 v48, 0xffff0000, v48
	v_mul_f32_e32 v48, v48, v48
	v_fmac_f32_e32 v48, v52, v52
	v_lshlrev_b32_e32 v52, 16, v49
	v_and_b32_e32 v49, 0xffff0000, v49
	v_mul_f32_e32 v49, v49, v49
	v_add_f32_e32 v48, v82, v48
	v_fmac_f32_e32 v49, v52, v52
	v_add_f32_e32 v48, v48, v49
	v_lshlrev_b32_e32 v49, 16, v50
	v_and_b32_e32 v50, 0xffff0000, v50
	v_mul_f32_e32 v50, v50, v50
	v_fmac_f32_e32 v50, v49, v49
	v_add_f32_e32 v48, v48, v50
	v_and_b32_e32 v50, 0xffff0000, v51
	v_lshlrev_b32_e32 v49, 16, v51
	v_mul_f32_e32 v50, v50, v50
	v_fmac_f32_e32 v50, v49, v49
	v_add_f32_e32 v48, v48, v50
	v_mov_b32_e32 v49, v48
	s_nop 1
	v_permlane16_swap_b32_e32 v49, v48
	s_waitcnt lgkmcnt(0)
	v_add_f32_e32 v48, v48, v49
	v_mov_b32_e32 v49, v48
	s_nop 1
	v_permlane32_swap_b32_e32 v49, v48
	s_and_saveexec_b64 s[6:7], vcc
	s_cbranch_execz .LBB0_346
	s_waitcnt lgkmcnt(0)
	v_add_f32_e32 v50, v48, v49
	v_lshlrev_b64 v[48:49], 6, v[80:81]
	v_lshl_add_u64 v[48:49], s[46:47], 0, v[48:49]
	v_lshl_add_u64 v[48:49], s[56:57], 2, v[48:49]
	s_lshl_b32 s38, s8, 2
	v_lshl_add_u64 v[48:49], v[48:49], 0, s[38:39]
	flat_store_dword v[48:49], v50
.LBB0_346:
	s_or_b64 exec, exec, s[6:7]
	v_lshlrev_b32_e32 v48, 16, v68
	s_waitcnt lgkmcnt(0)
	v_and_b32_e32 v49, 0xffff0000, v68
	v_lshlrev_b32_e32 v52, 16, v70
	v_and_b32_e32 v53, 0xffff0000, v70
	v_lshlrev_b32_e32 v54, 16, v71
	v_and_b32_e32 v55, 0xffff0000, v71
	v_pk_add_f32 v[44:45], v[44:45], v[48:49]
	v_lshlrev_b32_e32 v50, 16, v69
	v_and_b32_e32 v51, 0xffff0000, v69
	v_pk_add_f32 v[48:49], v[42:43], v[54:55]
	v_pk_add_f32 v[42:43], v[40:41], v[52:53]
	v_cvt_pk_bf16_f32 v40, v44, v45
	v_lshl_add_u64 v[44:45], s[68:69], 0, v[78:79]
	v_pk_add_f32 v[46:47], v[46:47], v[50:51]
	v_lshl_add_u64 v[44:45], v[168:169], 1, v[44:45]
	v_cvt_pk_bf16_f32 v41, v46, v47
	v_cvt_pk_bf16_f32 v42, v42, v43
	v_cvt_pk_bf16_f32 v43, v48, v49
	global_store_dwordx4 v[44:45], v[40:43], off
	v_lshlrev_b32_e32 v46, 16, v40
	v_and_b32_e32 v47, 0xffff0000, v66
	v_and_b32_e32 v40, 0xffff0000, v40
	v_mul_f32_e32 v40, v40, v40
	v_fmac_f32_e32 v40, v46, v46
	v_lshlrev_b32_e32 v46, 16, v41
	v_and_b32_e32 v41, 0xffff0000, v41
	v_mul_f32_e32 v41, v41, v41
	v_fmac_f32_e32 v41, v46, v46
	v_add_f32_e32 v40, v40, v41
	v_lshlrev_b32_e32 v41, 16, v42
	v_and_b32_e32 v42, 0xffff0000, v42
	v_mul_f32_e32 v42, v42, v42
	v_fmac_f32_e32 v42, v41, v41
	v_add_f32_e32 v40, v40, v42
	v_and_b32_e32 v42, 0xffff0000, v43
	v_lshlrev_b32_e32 v41, 16, v43
	v_mul_f32_e32 v42, v42, v42
	v_fmac_f32_e32 v42, v41, v41
	v_add_f32_e32 v50, v40, v42
	v_lshlrev_b32_e32 v40, 16, v64
	v_and_b32_e32 v41, 0xffff0000, v64
	v_lshlrev_b32_e32 v46, 16, v66
	v_lshlrev_b32_e32 v42, 16, v65
	v_and_b32_e32 v43, 0xffff0000, v65
	v_lshlrev_b32_e32 v48, 16, v67
	v_and_b32_e32 v49, 0xffff0000, v67
	v_pk_add_f32 v[36:37], v[36:37], v[40:41]
	v_pk_add_f32 v[32:33], v[32:33], v[46:47]
	v_pk_add_f32 v[38:39], v[38:39], v[42:43]
	v_pk_add_f32 v[40:41], v[34:35], v[48:49]
	v_cvt_pk_bf16_f32 v34, v36, v37
	v_cvt_pk_bf16_f32 v35, v38, v39
	v_cvt_pk_bf16_f32 v36, v32, v33
	s_nop 0
	v_and_b32_e32 v33, 0xffff0000, v34
	v_lshlrev_b32_e32 v32, 16, v34
	v_mul_f32_e32 v33, v33, v33
	v_fmac_f32_e32 v33, v32, v32
	v_and_b32_e32 v38, 0xffff0000, v35
	v_add_f32_e32 v32, v50, v33
	v_lshlrev_b32_e32 v33, 16, v35
	v_mul_f32_e32 v38, v38, v38
	v_fmac_f32_e32 v38, v33, v33
	v_add_f32_e32 v32, v32, v38
	v_and_b32_e32 v38, 0xffff0000, v36
	v_lshlrev_b32_e32 v33, 16, v36
	v_mul_f32_e32 v38, v38, v38
	v_fmac_f32_e32 v38, v33, v33
	v_cvt_pk_bf16_f32 v37, v40, v41
	v_add_f32_e32 v32, v32, v38
	v_and_b32_e32 v38, 0xffff0000, v37
	v_lshlrev_b32_e32 v33, 16, v37
	v_mul_f32_e32 v38, v38, v38
	v_fmac_f32_e32 v38, v33, v33
	v_add_f32_e32 v32, v32, v38
	v_mov_b32_e32 v33, v32
	s_nop 1
	v_permlane16_swap_b32_e32 v33, v32
	global_store_dwordx4 v[44:45], v[34:37], off offset:256
	s_waitcnt lgkmcnt(0)
	v_add_f32_e32 v32, v32, v33
	v_mov_b32_e32 v33, v32
	s_nop 1
	v_permlane32_swap_b32_e32 v33, v32
	s_and_saveexec_b64 s[6:7], vcc
	s_cbranch_execz .LBB0_348
	s_waitcnt lgkmcnt(0)
	v_add_f32_e32 v34, v32, v33
	v_lshlrev_b64 v[32:33], 6, v[76:77]
	v_lshl_add_u64 v[32:33], s[46:47], 0, v[32:33]
	v_lshl_add_u64 v[32:33], s[56:57], 2, v[32:33]
	s_lshl_b32 s38, s8, 2
	v_lshl_add_u64 v[32:33], v[32:33], 0, s[38:39]
	flat_store_dword v[32:33], v34
.LBB0_348:
	s_or_b64 exec, exec, s[6:7]
	v_add_u32_e32 v48, 0xa0, v170
	v_ashrrev_i32_e32 v49, 31, v48
	v_lshlrev_b64 v[54:55], 11, v[48:49]
	s_waitcnt lgkmcnt(0)
	v_lshl_add_u64 v[32:33], v[172:173], 0, v[54:55]
	global_load_dwordx4 v[50:53], v[32:33], off
	global_load_dwordx4 v[40:43], v[32:33], off offset:256
	v_add_u32_e32 v44, 0xb0, v170
	v_ashrrev_i32_e32 v45, 31, v44
	v_lshlrev_b64 v[46:47], 11, v[44:45]
	v_lshl_add_u64 v[32:33], v[172:173], 0, v[46:47]
	global_load_dwordx4 v[36:39], v[32:33], off
	s_nop 0
	global_load_dwordx4 v[32:35], v[32:33], off offset:256
	s_waitcnt vmcnt(0)
	v_lshlrev_b32_e32 v56, 16, v50
	v_and_b32_e32 v57, 0xffff0000, v50
	v_lshlrev_b32_e32 v50, 16, v51
	v_and_b32_e32 v51, 0xffff0000, v51
	v_lshlrev_b32_e32 v58, 16, v52
	v_and_b32_e32 v59, 0xffff0000, v52
	v_lshlrev_b32_e32 v52, 16, v53
	v_and_b32_e32 v53, 0xffff0000, v53
	v_pk_add_f32 v[28:29], v[28:29], v[56:57]
	v_pk_add_f32 v[30:31], v[30:31], v[50:51]
	v_pk_add_f32 v[50:51], v[26:27], v[52:53]
	v_pk_add_f32 v[26:27], v[24:25], v[58:59]
	v_cvt_pk_bf16_f32 v24, v28, v29
	v_lshl_add_u64 v[28:29], s[68:69], 0, v[54:55]
	v_lshl_add_u64 v[28:29], v[168:169], 1, v[28:29]
	v_cvt_pk_bf16_f32 v25, v30, v31
	v_cvt_pk_bf16_f32 v26, v26, v27
	v_cvt_pk_bf16_f32 v27, v50, v51
	global_store_dwordx4 v[28:29], v[24:27], off
	v_lshlrev_b32_e32 v30, 16, v24
	v_and_b32_e32 v31, 0xffff0000, v42
	v_and_b32_e32 v24, 0xffff0000, v24
	v_mul_f32_e32 v24, v24, v24
	v_fmac_f32_e32 v24, v30, v30
	v_lshlrev_b32_e32 v30, 16, v25
	v_and_b32_e32 v25, 0xffff0000, v25
	v_mul_f32_e32 v25, v25, v25
	v_fmac_f32_e32 v25, v30, v30
	v_add_f32_e32 v24, v24, v25
	v_lshlrev_b32_e32 v25, 16, v26
	v_and_b32_e32 v26, 0xffff0000, v26
	v_mul_f32_e32 v26, v26, v26
	v_fmac_f32_e32 v26, v25, v25
	v_add_f32_e32 v24, v24, v26
	v_and_b32_e32 v26, 0xffff0000, v27
	v_lshlrev_b32_e32 v25, 16, v27
	v_mul_f32_e32 v26, v26, v26
	v_fmac_f32_e32 v26, v25, v25
	v_add_f32_e32 v50, v24, v26
	v_lshlrev_b32_e32 v24, 16, v40
	v_and_b32_e32 v25, 0xffff0000, v40
	v_lshlrev_b32_e32 v26, 16, v41
	v_and_b32_e32 v27, 0xffff0000, v41
	v_lshlrev_b32_e32 v30, 16, v42
	v_lshlrev_b32_e32 v40, 16, v43
	v_and_b32_e32 v41, 0xffff0000, v43
	v_pk_add_f32 v[20:21], v[20:21], v[24:25]
	v_pk_add_f32 v[24:25], v[18:19], v[40:41]
	v_pk_add_f32 v[18:19], v[16:17], v[30:31]
	v_cvt_pk_bf16_f32 v16, v20, v21
	v_pk_add_f32 v[22:23], v[22:23], v[26:27]
	v_lshlrev_b32_e32 v20, 16, v16
	v_cvt_pk_bf16_f32 v17, v22, v23
	v_cvt_pk_bf16_f32 v18, v18, v19
	v_cvt_pk_bf16_f32 v19, v24, v25
	global_store_dwordx4 v[28:29], v[16:19], off offset:256
	s_nop 1
	v_and_b32_e32 v16, 0xffff0000, v16
	v_mul_f32_e32 v16, v16, v16
	v_fmac_f32_e32 v16, v20, v20
	v_lshlrev_b32_e32 v20, 16, v17
	v_and_b32_e32 v17, 0xffff0000, v17
	v_mul_f32_e32 v17, v17, v17
	v_add_f32_e32 v16, v50, v16
	v_fmac_f32_e32 v17, v20, v20
	v_add_f32_e32 v16, v16, v17
	v_lshlrev_b32_e32 v17, 16, v18
	v_and_b32_e32 v18, 0xffff0000, v18
	v_mul_f32_e32 v18, v18, v18
	v_fmac_f32_e32 v18, v17, v17
	v_add_f32_e32 v16, v16, v18
	v_and_b32_e32 v18, 0xffff0000, v19
	v_lshlrev_b32_e32 v17, 16, v19
	v_mul_f32_e32 v18, v18, v18
	v_fmac_f32_e32 v18, v17, v17
	v_add_f32_e32 v16, v16, v18
	v_mov_b32_e32 v17, v16
	s_nop 1
	v_permlane16_swap_b32_e32 v17, v16
	s_waitcnt lgkmcnt(0)
	v_add_f32_e32 v16, v16, v17
	v_mov_b32_e32 v17, v16
	s_nop 1
	v_permlane32_swap_b32_e32 v17, v16
	s_and_saveexec_b64 s[6:7], vcc
	s_cbranch_execz .LBB0_350
	s_waitcnt lgkmcnt(0)
	v_add_f32_e32 v18, v16, v17
	v_lshlrev_b64 v[16:17], 6, v[48:49]
	v_lshl_add_u64 v[16:17], s[46:47], 0, v[16:17]
	v_lshl_add_u64 v[16:17], s[56:57], 2, v[16:17]
	s_lshl_b32 s38, s8, 2
	v_lshl_add_u64 v[16:17], v[16:17], 0, s[38:39]
	flat_store_dword v[16:17], v18
.LBB0_350:
	s_or_b64 exec, exec, s[6:7]
	v_lshlrev_b32_e32 v16, 16, v36
	s_waitcnt lgkmcnt(0)
	v_and_b32_e32 v17, 0xffff0000, v36
	v_lshlrev_b32_e32 v20, 16, v38
	v_and_b32_e32 v21, 0xffff0000, v38
	v_lshlrev_b32_e32 v22, 16, v39
	v_and_b32_e32 v23, 0xffff0000, v39
	v_pk_add_f32 v[12:13], v[12:13], v[16:17]
	v_lshlrev_b32_e32 v18, 16, v37
	v_and_b32_e32 v19, 0xffff0000, v37
	v_pk_add_f32 v[16:17], v[10:11], v[22:23]
	v_pk_add_f32 v[10:11], v[8:9], v[20:21]
	v_cvt_pk_bf16_f32 v8, v12, v13
	v_lshl_add_u64 v[12:13], s[68:69], 0, v[46:47]
	v_pk_add_f32 v[14:15], v[14:15], v[18:19]
	v_lshl_add_u64 v[12:13], v[168:169], 1, v[12:13]
	v_cvt_pk_bf16_f32 v9, v14, v15
	v_cvt_pk_bf16_f32 v10, v10, v11
	v_cvt_pk_bf16_f32 v11, v16, v17
	global_store_dwordx4 v[12:13], v[8:11], off
	v_lshlrev_b32_e32 v14, 16, v8
	v_and_b32_e32 v15, 0xffff0000, v34
	v_and_b32_e32 v8, 0xffff0000, v8
	v_mul_f32_e32 v8, v8, v8
	v_fmac_f32_e32 v8, v14, v14
	v_lshlrev_b32_e32 v14, 16, v9
	v_and_b32_e32 v9, 0xffff0000, v9
	v_mul_f32_e32 v9, v9, v9
	v_fmac_f32_e32 v9, v14, v14
	v_add_f32_e32 v8, v8, v9
	v_lshlrev_b32_e32 v9, 16, v10
	v_and_b32_e32 v10, 0xffff0000, v10
	v_mul_f32_e32 v10, v10, v10
	v_fmac_f32_e32 v10, v9, v9
	v_add_f32_e32 v8, v8, v10
	v_and_b32_e32 v10, 0xffff0000, v11
	v_lshlrev_b32_e32 v9, 16, v11
	v_mul_f32_e32 v10, v10, v10
	v_fmac_f32_e32 v10, v9, v9
	v_add_f32_e32 v18, v8, v10
	v_lshlrev_b32_e32 v8, 16, v32
	v_and_b32_e32 v9, 0xffff0000, v32
	v_lshlrev_b32_e32 v14, 16, v34
	v_lshlrev_b32_e32 v10, 16, v33
	v_and_b32_e32 v11, 0xffff0000, v33
	v_lshlrev_b32_e32 v16, 16, v35
	v_and_b32_e32 v17, 0xffff0000, v35
	v_pk_add_f32 v[4:5], v[4:5], v[8:9]
	v_pk_add_f32 v[0:1], v[0:1], v[14:15]
	v_pk_add_f32 v[6:7], v[6:7], v[10:11]
	v_pk_add_f32 v[8:9], v[2:3], v[16:17]
	v_cvt_pk_bf16_f32 v2, v4, v5
	v_cvt_pk_bf16_f32 v3, v6, v7
	v_cvt_pk_bf16_f32 v4, v0, v1
	s_nop 0
	v_and_b32_e32 v1, 0xffff0000, v2
	v_lshlrev_b32_e32 v0, 16, v2
	v_mul_f32_e32 v1, v1, v1
	v_fmac_f32_e32 v1, v0, v0
	v_and_b32_e32 v6, 0xffff0000, v3
	v_add_f32_e32 v0, v18, v1
	v_lshlrev_b32_e32 v1, 16, v3
	v_mul_f32_e32 v6, v6, v6
	v_fmac_f32_e32 v6, v1, v1
	v_add_f32_e32 v0, v0, v6
	v_and_b32_e32 v6, 0xffff0000, v4
	v_lshlrev_b32_e32 v1, 16, v4
	v_mul_f32_e32 v6, v6, v6
	v_fmac_f32_e32 v6, v1, v1
	v_cvt_pk_bf16_f32 v5, v8, v9
	v_add_f32_e32 v0, v0, v6
	v_and_b32_e32 v6, 0xffff0000, v5
	v_lshlrev_b32_e32 v1, 16, v5
	v_mul_f32_e32 v6, v6, v6
	v_fmac_f32_e32 v6, v1, v1
	v_add_f32_e32 v0, v0, v6
	v_mov_b32_e32 v1, v0
	s_nop 1
	v_permlane16_swap_b32_e32 v1, v0
	global_store_dwordx4 v[12:13], v[2:5], off offset:256
	s_waitcnt lgkmcnt(0)
	v_add_f32_e32 v0, v0, v1
	v_mov_b32_e32 v1, v0
	s_nop 1
	v_permlane32_swap_b32_e32 v1, v0
	s_and_saveexec_b64 s[6:7], vcc
	s_cbranch_execz .LBB0_352
	s_waitcnt lgkmcnt(0)
	v_add_f32_e32 v2, v0, v1
	v_lshlrev_b64 v[0:1], 6, v[44:45]
	v_lshl_add_u64 v[0:1], s[46:47], 0, v[0:1]
	v_lshl_add_u64 v[0:1], s[56:57], 2, v[0:1]
	s_lshl_b32 s38, s8, 2
	v_lshl_add_u64 v[0:1], v[0:1], 0, s[38:39]
	flat_store_dword v[0:1], v2

.LBB0_378:
	s_mov_b32 s6, -1
	s_lshl_b32 s5, s5, 8
	v_mbcnt_lo_u32_b32 v128, s6, 0
	v_mbcnt_hi_u32_b32 v128, s6, v128
	s_getreg_b32 s6, hwreg(HW_REG_HW_ID, 0, 6)
	s_and_b32 s6, s6, 63
	s_lshl_b32 s6, s6, 2
	s_add_i32 s6, s6, 0
	s_add_i32 s6, s6, 0x20200
	v_mov_b32_e32 v129, s6
	ds_read_b32 v129, v129
	v_bfrev_b32_e32 v130, 0.5
	s_lshl_b32 s56, s4, 2
	s_ashr_i32 s57, s56, 31
	s_waitcnt lgkmcnt(0)
	v_readfirstlane_b32 s6, v129
	s_nop 1
	v_lshl_add_u32 v128, s6, 6, v128
	s_nop 0
	v_readfirstlane_b32 s6, v128
	s_bfe_u32 s8, s6, 0x20006
	s_ashr_i32 s6, s6, 2
	s_andn2_b32 s6, s6, 63
	s_add_i32 s6, s6, s5
	v_and_or_b32 v170, v128, 15, s6
	s_lshl_b32 s5, s4, 8
	s_lshl_b32 s6, s8, 5
	v_bfe_u32 v129, v128, 4, 2
	s_or_b32 s5, s6, s5
	v_lshl_or_b32 v168, v129, 3, s5
	v_ashrrev_i32_e32 v169, 31, v168
	v_lshlrev_b64 v[146:147], 1, v[168:169]
	v_ashrrev_i32_e32 v171, 31, v170
	v_lshlrev_b32_e32 v128, 2, v128
	v_lshl_add_u64 v[172:173], s[68:69], 0, v[146:147]
	v_lshlrev_b64 v[148:149], 11, v[170:171]
	v_bitop3_b32 v181, v128, 64, v130 bitop3:0x6c
	v_bitop3_b32 v180, v128, s84, v130 bitop3:0x6c
	v_cmp_eq_u32_e32 vcc, 0, v129
	v_lshl_add_u64 v[128:129], v[172:173], 0, v[148:149]
	global_load_dwordx4 v[142:145], v[128:129], off
	global_load_dwordx4 v[136:139], v[128:129], off offset:256
	v_or_b32_e32 v174, 16, v170
	v_ashrrev_i32_e32 v175, 31, v174
	v_lshlrev_b64 v[176:177], 11, v[174:175]
	v_lshl_add_u64 v[128:129], v[172:173], 0, v[176:177]
	global_load_dwordx4 v[132:135], v[128:129], off
	s_nop 0
	global_load_dwordx4 v[128:131], v[128:129], off offset:256
	s_waitcnt vmcnt(0)
	v_lshlrev_b32_e32 v150, 16, v142
	v_and_b32_e32 v151, 0xffff0000, v142
	v_lshlrev_b32_e32 v142, 16, v143
	v_and_b32_e32 v143, 0xffff0000, v143
	v_lshlrev_b32_e32 v152, 16, v144
	v_and_b32_e32 v153, 0xffff0000, v144
	v_lshlrev_b32_e32 v144, 16, v145
	v_and_b32_e32 v145, 0xffff0000, v145
	v_pk_add_f32 v[124:125], v[124:125], v[150:151]
	v_pk_add_f32 v[126:127], v[126:127], v[142:143]
	v_pk_add_f32 v[142:143], v[122:123], v[144:145]
	v_pk_add_f32 v[122:123], v[120:121], v[152:153]
	v_cvt_pk_bf16_f32 v120, v124, v125
	v_lshl_add_u64 v[124:125], s[68:69], 0, v[148:149]
	v_lshl_add_u64 v[124:125], v[124:125], 0, v[146:147]
	v_cvt_pk_bf16_f32 v121, v126, v127
	v_cvt_pk_bf16_f32 v122, v122, v123
	v_cvt_pk_bf16_f32 v123, v142, v143
	global_store_dwordx4 v[124:125], v[120:123], off
	v_lshlrev_b32_e32 v126, 16, v120
	v_and_b32_e32 v127, 0xffff0000, v138
	v_and_b32_e32 v120, 0xffff0000, v120
	v_mul_f32_e32 v120, v120, v120
	v_fmac_f32_e32 v120, v126, v126
	v_lshlrev_b32_e32 v126, 16, v121
	v_and_b32_e32 v121, 0xffff0000, v121
	v_mul_f32_e32 v121, v121, v121
	v_fmac_f32_e32 v121, v126, v126
	v_add_f32_e32 v120, v120, v121
	v_lshlrev_b32_e32 v121, 16, v122
	v_and_b32_e32 v122, 0xffff0000, v122
	v_mul_f32_e32 v122, v122, v122
	v_fmac_f32_e32 v122, v121, v121
	v_add_f32_e32 v120, v120, v122
	v_and_b32_e32 v122, 0xffff0000, v123
	v_lshlrev_b32_e32 v121, 16, v123
	v_mul_f32_e32 v122, v122, v122
	v_fmac_f32_e32 v122, v121, v121
	v_add_f32_e32 v142, v120, v122
	v_lshlrev_b32_e32 v120, 16, v136
	v_and_b32_e32 v121, 0xffff0000, v136
	v_lshlrev_b32_e32 v122, 16, v137
	v_and_b32_e32 v123, 0xffff0000, v137
	v_lshlrev_b32_e32 v126, 16, v138
	v_lshlrev_b32_e32 v136, 16, v139
	v_and_b32_e32 v137, 0xffff0000, v139
	v_pk_add_f32 v[116:117], v[116:117], v[120:121]
	v_pk_add_f32 v[120:121], v[114:115], v[136:137]
	v_pk_add_f32 v[114:115], v[112:113], v[126:127]
	v_cvt_pk_bf16_f32 v112, v116, v117
	v_pk_add_f32 v[118:119], v[118:119], v[122:123]
	v_lshlrev_b32_e32 v116, 16, v112
	v_cvt_pk_bf16_f32 v113, v118, v119
	v_cvt_pk_bf16_f32 v114, v114, v115
	v_cvt_pk_bf16_f32 v115, v120, v121
	global_store_dwordx4 v[124:125], v[112:115], off offset:256
	s_nop 1
	v_and_b32_e32 v112, 0xffff0000, v112
	v_mul_f32_e32 v112, v112, v112
	v_fmac_f32_e32 v112, v116, v116
	v_lshlrev_b32_e32 v116, 16, v113
	v_and_b32_e32 v113, 0xffff0000, v113
	v_mul_f32_e32 v113, v113, v113
	v_add_f32_e32 v112, v142, v112
	v_fmac_f32_e32 v113, v116, v116
	v_add_f32_e32 v112, v112, v113
	v_lshlrev_b32_e32 v113, 16, v114
	v_and_b32_e32 v114, 0xffff0000, v114
	v_mul_f32_e32 v114, v114, v114
	v_fmac_f32_e32 v114, v113, v113
	v_add_f32_e32 v112, v112, v114
	v_and_b32_e32 v114, 0xffff0000, v115
	v_lshlrev_b32_e32 v113, 16, v115
	v_mul_f32_e32 v114, v114, v114
	v_fmac_f32_e32 v114, v113, v113
	v_add_f32_e32 v112, v112, v114
	v_mov_b32_e32 v113, v112
	s_nop 1
	v_permlane16_swap_b32_e32 v113, v112
	s_waitcnt lgkmcnt(0)
	v_add_f32_e32 v112, v112, v113
	v_mov_b32_e32 v113, v112
	s_nop 1
	v_permlane32_swap_b32_e32 v113, v112
	s_and_saveexec_b64 s[6:7], vcc
	s_cbranch_execz .LBB0_380
	v_lshlrev_b64 v[114:115], 6, v[170:171]
	v_lshl_add_u64 v[114:115], s[46:47], 0, v[114:115]
	v_lshl_add_u64 v[114:115], s[56:57], 2, v[114:115]
	s_lshl_b32 s38, s8, 2
	v_lshl_add_u64 v[114:115], v[114:115], 0, s[38:39]
	s_waitcnt lgkmcnt(0)
	v_add_f32_e32 v112, v112, v113
	flat_store_dword v[114:115], v112
.LBB0_380:
	s_or_b64 exec, exec, s[6:7]
	v_lshlrev_b32_e32 v112, 16, v132
	s_waitcnt lgkmcnt(0)
	v_and_b32_e32 v113, 0xffff0000, v132
	v_lshlrev_b32_e32 v116, 16, v134
	v_and_b32_e32 v117, 0xffff0000, v134
	v_lshlrev_b32_e32 v118, 16, v135
	v_and_b32_e32 v119, 0xffff0000, v135
	v_pk_add_f32 v[108:109], v[108:109], v[112:113]
	v_lshlrev_b32_e32 v114, 16, v133
	v_and_b32_e32 v115, 0xffff0000, v133
	v_pk_add_f32 v[112:113], v[106:107], v[118:119]
	v_pk_add_f32 v[106:107], v[104:105], v[116:117]
	v_cvt_pk_bf16_f32 v104, v108, v109
	v_lshl_add_u64 v[108:109], s[68:69], 0, v[176:177]
	v_pk_add_f32 v[110:111], v[110:111], v[114:115]
	v_lshl_add_u64 v[108:109], v[168:169], 1, v[108:109]
	v_cvt_pk_bf16_f32 v105, v110, v111
	v_cvt_pk_bf16_f32 v106, v106, v107
	v_cvt_pk_bf16_f32 v107, v112, v113
	global_store_dwordx4 v[108:109], v[104:107], off
	v_lshlrev_b32_e32 v110, 16, v104
	v_and_b32_e32 v111, 0xffff0000, v130
	v_and_b32_e32 v104, 0xffff0000, v104
	v_mul_f32_e32 v104, v104, v104
	v_fmac_f32_e32 v104, v110, v110
	v_lshlrev_b32_e32 v110, 16, v105
	v_and_b32_e32 v105, 0xffff0000, v105
	v_mul_f32_e32 v105, v105, v105
	v_fmac_f32_e32 v105, v110, v110
	v_add_f32_e32 v104, v104, v105
	v_lshlrev_b32_e32 v105, 16, v106
	v_and_b32_e32 v106, 0xffff0000, v106
	v_mul_f32_e32 v106, v106, v106
	v_fmac_f32_e32 v106, v105, v105
	v_add_f32_e32 v104, v104, v106
	v_and_b32_e32 v106, 0xffff0000, v107
	v_lshlrev_b32_e32 v105, 16, v107
	v_mul_f32_e32 v106, v106, v106
	v_fmac_f32_e32 v106, v105, v105
	v_add_f32_e32 v114, v104, v106
	v_lshlrev_b32_e32 v104, 16, v128
	v_and_b32_e32 v105, 0xffff0000, v128
	v_lshlrev_b32_e32 v110, 16, v130
	v_lshlrev_b32_e32 v106, 16, v129
	v_and_b32_e32 v107, 0xffff0000, v129
	v_lshlrev_b32_e32 v112, 16, v131
	v_and_b32_e32 v113, 0xffff0000, v131
	v_pk_add_f32 v[100:101], v[100:101], v[104:105]
	v_pk_add_f32 v[96:97], v[96:97], v[110:111]
	v_pk_add_f32 v[102:103], v[102:103], v[106:107]
	v_pk_add_f32 v[104:105], v[98:99], v[112:113]
	v_cvt_pk_bf16_f32 v98, v100, v101
	v_cvt_pk_bf16_f32 v99, v102, v103
	v_cvt_pk_bf16_f32 v100, v96, v97
	s_nop 0
	v_and_b32_e32 v97, 0xffff0000, v98
	v_lshlrev_b32_e32 v96, 16, v98
	v_mul_f32_e32 v97, v97, v97
	v_fmac_f32_e32 v97, v96, v96
	v_and_b32_e32 v102, 0xffff0000, v99
	v_add_f32_e32 v96, v114, v97
	v_lshlrev_b32_e32 v97, 16, v99
	v_mul_f32_e32 v102, v102, v102
	v_fmac_f32_e32 v102, v97, v97
	v_add_f32_e32 v96, v96, v102
	v_and_b32_e32 v102, 0xffff0000, v100
	v_lshlrev_b32_e32 v97, 16, v100
	v_mul_f32_e32 v102, v102, v102
	v_fmac_f32_e32 v102, v97, v97
	v_cvt_pk_bf16_f32 v101, v104, v105
	v_add_f32_e32 v96, v96, v102
	v_and_b32_e32 v102, 0xffff0000, v101
	v_lshlrev_b32_e32 v97, 16, v101
	v_mul_f32_e32 v102, v102, v102
	v_fmac_f32_e32 v102, v97, v97
	v_add_f32_e32 v96, v96, v102
	v_mov_b32_e32 v97, v96
	s_nop 1
	v_permlane16_swap_b32_e32 v97, v96
	global_store_dwordx4 v[108:109], v[98:101], off offset:256
	s_waitcnt lgkmcnt(0)
	v_add_f32_e32 v96, v96, v97
	v_mov_b32_e32 v97, v96
	s_nop 1
	v_permlane32_swap_b32_e32 v97, v96
	s_and_saveexec_b64 s[6:7], vcc
	s_cbranch_execz .LBB0_382
	v_lshlrev_b64 v[98:99], 6, v[174:175]
	v_lshl_add_u64 v[98:99], s[46:47], 0, v[98:99]
	v_lshl_add_u64 v[98:99], s[56:57], 2, v[98:99]
	s_lshl_b32 s38, s8, 2
	v_lshl_add_u64 v[98:99], v[98:99], 0, s[38:39]
	s_waitcnt lgkmcnt(0)
	v_add_f32_e32 v96, v96, v97
	flat_store_dword v[98:99], v96
.LBB0_382:
	s_or_b64 exec, exec, s[6:7]
	v_or_b32_e32 v112, 32, v170
	v_ashrrev_i32_e32 v113, 31, v112
	v_lshlrev_b64 v[118:119], 11, v[112:113]
	s_waitcnt lgkmcnt(0)
	v_lshl_add_u64 v[96:97], v[172:173], 0, v[118:119]
	global_load_dwordx4 v[114:117], v[96:97], off
	global_load_dwordx4 v[104:107], v[96:97], off offset:256
	v_or_b32_e32 v108, 48, v170
	v_ashrrev_i32_e32 v109, 31, v108
	v_lshlrev_b64 v[110:111], 11, v[108:109]
	v_lshl_add_u64 v[96:97], v[172:173], 0, v[110:111]
	global_load_dwordx4 v[100:103], v[96:97], off
	s_nop 0
	global_load_dwordx4 v[96:99], v[96:97], off offset:256
	s_waitcnt vmcnt(0)
	v_lshlrev_b32_e32 v120, 16, v114
	v_and_b32_e32 v121, 0xffff0000, v114
	v_lshlrev_b32_e32 v114, 16, v115
	v_and_b32_e32 v115, 0xffff0000, v115
	v_lshlrev_b32_e32 v122, 16, v116
	v_and_b32_e32 v123, 0xffff0000, v116
	v_lshlrev_b32_e32 v116, 16, v117
	v_and_b32_e32 v117, 0xffff0000, v117
	v_pk_add_f32 v[92:93], v[92:93], v[120:121]
	v_pk_add_f32 v[94:95], v[94:95], v[114:115]
	v_pk_add_f32 v[114:115], v[90:91], v[116:117]
	v_pk_add_f32 v[90:91], v[88:89], v[122:123]
	v_cvt_pk_bf16_f32 v88, v92, v93
	v_lshl_add_u64 v[92:93], s[68:69], 0, v[118:119]
	v_lshl_add_u64 v[92:93], v[168:169], 1, v[92:93]
	v_cvt_pk_bf16_f32 v89, v94, v95
	v_cvt_pk_bf16_f32 v90, v90, v91
	v_cvt_pk_bf16_f32 v91, v114, v115
	global_store_dwordx4 v[92:93], v[88:91], off
	v_lshlrev_b32_e32 v94, 16, v88
	v_and_b32_e32 v95, 0xffff0000, v106
	v_and_b32_e32 v88, 0xffff0000, v88
	v_mul_f32_e32 v88, v88, v88
	v_fmac_f32_e32 v88, v94, v94
	v_lshlrev_b32_e32 v94, 16, v89
	v_and_b32_e32 v89, 0xffff0000, v89
	v_mul_f32_e32 v89, v89, v89
	v_fmac_f32_e32 v89, v94, v94
	v_add_f32_e32 v88, v88, v89
	v_lshlrev_b32_e32 v89, 16, v90
	v_and_b32_e32 v90, 0xffff0000, v90
	v_mul_f32_e32 v90, v90, v90
	v_fmac_f32_e32 v90, v89, v89
	v_add_f32_e32 v88, v88, v90
	v_and_b32_e32 v90, 0xffff0000, v91
	v_lshlrev_b32_e32 v89, 16, v91
	v_mul_f32_e32 v90, v90, v90
	v_fmac_f32_e32 v90, v89, v89
	v_add_f32_e32 v114, v88, v90
	v_lshlrev_b32_e32 v88, 16, v104
	v_and_b32_e32 v89, 0xffff0000, v104
	v_lshlrev_b32_e32 v90, 16, v105
	v_and_b32_e32 v91, 0xffff0000, v105
	v_lshlrev_b32_e32 v94, 16, v106
	v_lshlrev_b32_e32 v104, 16, v107
	v_and_b32_e32 v105, 0xffff0000, v107
	v_pk_add_f32 v[84:85], v[84:85], v[88:89]
	v_pk_add_f32 v[88:89], v[82:83], v[104:105]
	v_pk_add_f32 v[82:83], v[80:81], v[94:95]
	v_cvt_pk_bf16_f32 v80, v84, v85
	v_pk_add_f32 v[86:87], v[86:87], v[90:91]
	v_lshlrev_b32_e32 v84, 16, v80
	v_cvt_pk_bf16_f32 v81, v86, v87
	v_cvt_pk_bf16_f32 v82, v82, v83
	v_cvt_pk_bf16_f32 v83, v88, v89
	global_store_dwordx4 v[92:93], v[80:83], off offset:256
	s_nop 1
	v_and_b32_e32 v80, 0xffff0000, v80
	v_mul_f32_e32 v80, v80, v80
	v_fmac_f32_e32 v80, v84, v84
	v_lshlrev_b32_e32 v84, 16, v81
	v_and_b32_e32 v81, 0xffff0000, v81
	v_mul_f32_e32 v81, v81, v81
	v_add_f32_e32 v80, v114, v80
	v_fmac_f32_e32 v81, v84, v84
	v_add_f32_e32 v80, v80, v81
	v_lshlrev_b32_e32 v81, 16, v82
	v_and_b32_e32 v82, 0xffff0000, v82
	v_mul_f32_e32 v82, v82, v82
	v_fmac_f32_e32 v82, v81, v81
	v_add_f32_e32 v80, v80, v82
	v_and_b32_e32 v82, 0xffff0000, v83
	v_lshlrev_b32_e32 v81, 16, v83
	v_mul_f32_e32 v82, v82, v82
	v_fmac_f32_e32 v82, v81, v81
	v_add_f32_e32 v80, v80, v82
	v_mov_b32_e32 v81, v80
	s_nop 1
	v_permlane16_swap_b32_e32 v81, v80
	s_waitcnt lgkmcnt(0)
	v_add_f32_e32 v80, v80, v81
	v_mov_b32_e32 v81, v80
	s_nop 1
	v_permlane32_swap_b32_e32 v81, v80
	s_mov_b64 s[6:7], exec
	s_and_b64 s[4:5], s[6:7], vcc
	v_mov_b32_e32 v198, v220
	v_mov_b32_e32 v199, v221
	v_mov_b32_e32 v248, v222
	v_mov_b32_e32 v205, v223
	v_mov_b32_e32 v196, v224
	s_mov_b64 exec, s[4:5]
	s_cbranch_execz .LBB0_384
	v_lshlrev_b64 v[82:83], 6, v[112:113]
	v_lshl_add_u64 v[82:83], s[46:47], 0, v[82:83]
	v_lshl_add_u64 v[82:83], s[56:57], 2, v[82:83]
	s_lshl_b32 s38, s8, 2
	v_lshl_add_u64 v[82:83], v[82:83], 0, s[38:39]
	s_waitcnt lgkmcnt(0)
	v_add_f32_e32 v80, v80, v81
	flat_store_dword v[82:83], v80
.LBB0_384:
	s_or_b64 exec, exec, s[6:7]
	v_lshlrev_b32_e32 v80, 16, v100
	s_waitcnt lgkmcnt(0)
	v_and_b32_e32 v81, 0xffff0000, v100
	v_lshlrev_b32_e32 v84, 16, v102
	v_and_b32_e32 v85, 0xffff0000, v102
	v_lshlrev_b32_e32 v86, 16, v103
	v_and_b32_e32 v87, 0xffff0000, v103
	v_pk_add_f32 v[76:77], v[76:77], v[80:81]
	v_lshlrev_b32_e32 v82, 16, v101
	v_and_b32_e32 v83, 0xffff0000, v101
	v_pk_add_f32 v[80:81], v[74:75], v[86:87]
	v_pk_add_f32 v[74:75], v[72:73], v[84:85]
	v_cvt_pk_bf16_f32 v72, v76, v77
	v_lshl_add_u64 v[76:77], s[68:69], 0, v[110:111]
	v_pk_add_f32 v[78:79], v[78:79], v[82:83]
	v_lshl_add_u64 v[76:77], v[168:169], 1, v[76:77]
	v_cvt_pk_bf16_f32 v73, v78, v79
	v_cvt_pk_bf16_f32 v74, v74, v75
	v_cvt_pk_bf16_f32 v75, v80, v81
	global_store_dwordx4 v[76:77], v[72:75], off
	v_lshlrev_b32_e32 v78, 16, v72
	v_and_b32_e32 v79, 0xffff0000, v98
	v_and_b32_e32 v72, 0xffff0000, v72
	v_mul_f32_e32 v72, v72, v72
	v_fmac_f32_e32 v72, v78, v78
	v_lshlrev_b32_e32 v78, 16, v73
	v_and_b32_e32 v73, 0xffff0000, v73
	v_mul_f32_e32 v73, v73, v73
	v_fmac_f32_e32 v73, v78, v78
	v_add_f32_e32 v72, v72, v73
	v_lshlrev_b32_e32 v73, 16, v74
	v_and_b32_e32 v74, 0xffff0000, v74
	v_mul_f32_e32 v74, v74, v74
	v_fmac_f32_e32 v74, v73, v73
	v_add_f32_e32 v72, v72, v74
	v_and_b32_e32 v74, 0xffff0000, v75
	v_lshlrev_b32_e32 v73, 16, v75
	v_mul_f32_e32 v74, v74, v74
	v_fmac_f32_e32 v74, v73, v73
	v_add_f32_e32 v82, v72, v74
	v_lshlrev_b32_e32 v72, 16, v96
	v_and_b32_e32 v73, 0xffff0000, v96
	v_lshlrev_b32_e32 v78, 16, v98
	v_lshlrev_b32_e32 v74, 16, v97
	v_and_b32_e32 v75, 0xffff0000, v97
	v_lshlrev_b32_e32 v80, 16, v99
	v_and_b32_e32 v81, 0xffff0000, v99
	v_pk_add_f32 v[68:69], v[68:69], v[72:73]
	v_pk_add_f32 v[64:65], v[64:65], v[78:79]
	v_pk_add_f32 v[70:71], v[70:71], v[74:75]
	v_pk_add_f32 v[72:73], v[66:67], v[80:81]
	v_cvt_pk_bf16_f32 v66, v68, v69
	v_cvt_pk_bf16_f32 v67, v70, v71
	v_cvt_pk_bf16_f32 v68, v64, v65
	s_nop 0
	v_and_b32_e32 v65, 0xffff0000, v66
	v_lshlrev_b32_e32 v64, 16, v66
	v_mul_f32_e32 v65, v65, v65
	v_fmac_f32_e32 v65, v64, v64
	v_and_b32_e32 v70, 0xffff0000, v67
	v_add_f32_e32 v64, v82, v65
	v_lshlrev_b32_e32 v65, 16, v67
	v_mul_f32_e32 v70, v70, v70
	v_fmac_f32_e32 v70, v65, v65
	v_add_f32_e32 v64, v64, v70
	v_and_b32_e32 v70, 0xffff0000, v68
	v_lshlrev_b32_e32 v65, 16, v68
	v_mul_f32_e32 v70, v70, v70
	v_fmac_f32_e32 v70, v65, v65
	v_cvt_pk_bf16_f32 v69, v72, v73
	v_add_f32_e32 v64, v64, v70
	v_and_b32_e32 v70, 0xffff0000, v69
	v_lshlrev_b32_e32 v65, 16, v69
	v_mul_f32_e32 v70, v70, v70
	v_fmac_f32_e32 v70, v65, v65
	v_add_f32_e32 v64, v64, v70
	v_mov_b32_e32 v65, v64
	s_nop 1
	v_permlane16_swap_b32_e32 v65, v64
	global_store_dwordx4 v[76:77], v[66:69], off offset:256
	s_waitcnt lgkmcnt(0)
	v_add_f32_e32 v64, v64, v65
	v_mov_b32_e32 v65, v64
	s_nop 1
	v_permlane32_swap_b32_e32 v65, v64
	s_and_saveexec_b64 s[6:7], vcc
	s_cbranch_execz .LBB0_386
	v_lshlrev_b64 v[66:67], 6, v[108:109]
	v_lshl_add_u64 v[66:67], s[46:47], 0, v[66:67]
	v_lshl_add_u64 v[66:67], s[56:57], 2, v[66:67]
	s_lshl_b32 s38, s8, 2
	v_lshl_add_u64 v[66:67], v[66:67], 0, s[38:39]
	s_waitcnt lgkmcnt(0)
	v_add_f32_e32 v64, v64, v65
	flat_store_dword v[66:67], v64
.LBB0_386:
	s_or_b64 exec, exec, s[6:7]
	v_add_u32_e32 v80, 0x80, v170
	v_ashrrev_i32_e32 v81, 31, v80
	v_lshlrev_b64 v[86:87], 11, v[80:81]
	s_waitcnt lgkmcnt(0)
	v_lshl_add_u64 v[64:65], v[172:173], 0, v[86:87]
	global_load_dwordx4 v[82:85], v[64:65], off
	global_load_dwordx4 v[72:75], v[64:65], off offset:256
	v_add_u32_e32 v76, 0x90, v170
	v_ashrrev_i32_e32 v77, 31, v76
	v_lshlrev_b64 v[78:79], 11, v[76:77]
	v_lshl_add_u64 v[64:65], v[172:173], 0, v[78:79]
	global_load_dwordx4 v[68:71], v[64:65], off
	s_nop 0
	global_load_dwordx4 v[64:67], v[64:65], off offset:256
	s_waitcnt vmcnt(0)
	v_lshlrev_b32_e32 v88, 16, v82
	v_and_b32_e32 v89, 0xffff0000, v82
	v_lshlrev_b32_e32 v82, 16, v83
	v_and_b32_e32 v83, 0xffff0000, v83
	v_lshlrev_b32_e32 v90, 16, v84
	v_and_b32_e32 v91, 0xffff0000, v84
	v_lshlrev_b32_e32 v84, 16, v85
	v_and_b32_e32 v85, 0xffff0000, v85
	v_pk_add_f32 v[60:61], v[60:61], v[88:89]
	v_pk_add_f32 v[62:63], v[62:63], v[82:83]
	v_pk_add_f32 v[82:83], v[58:59], v[84:85]
	v_pk_add_f32 v[58:59], v[56:57], v[90:91]
	v_cvt_pk_bf16_f32 v56, v60, v61
	v_lshl_add_u64 v[60:61], s[68:69], 0, v[86:87]
	v_lshl_add_u64 v[60:61], v[168:169], 1, v[60:61]
	v_cvt_pk_bf16_f32 v57, v62, v63
	v_cvt_pk_bf16_f32 v58, v58, v59
	v_cvt_pk_bf16_f32 v59, v82, v83
	global_store_dwordx4 v[60:61], v[56:59], off
	v_lshlrev_b32_e32 v62, 16, v56
	v_and_b32_e32 v63, 0xffff0000, v74
	v_and_b32_e32 v56, 0xffff0000, v56
	v_mul_f32_e32 v56, v56, v56
	v_fmac_f32_e32 v56, v62, v62
	v_lshlrev_b32_e32 v62, 16, v57
	v_and_b32_e32 v57, 0xffff0000, v57
	v_mul_f32_e32 v57, v57, v57
	v_fmac_f32_e32 v57, v62, v62
	v_add_f32_e32 v56, v56, v57
	v_lshlrev_b32_e32 v57, 16, v58
	v_and_b32_e32 v58, 0xffff0000, v58
	v_mul_f32_e32 v58, v58, v58
	v_fmac_f32_e32 v58, v57, v57
	v_add_f32_e32 v56, v56, v58
	v_and_b32_e32 v58, 0xffff0000, v59
	v_lshlrev_b32_e32 v57, 16, v59
	v_mul_f32_e32 v58, v58, v58
	v_fmac_f32_e32 v58, v57, v57
	v_add_f32_e32 v82, v56, v58
	v_lshlrev_b32_e32 v56, 16, v72
	v_and_b32_e32 v57, 0xffff0000, v72
	v_lshlrev_b32_e32 v58, 16, v73
	v_and_b32_e32 v59, 0xffff0000, v73
	v_lshlrev_b32_e32 v62, 16, v74
	v_lshlrev_b32_e32 v72, 16, v75
	v_and_b32_e32 v73, 0xffff0000, v75
	v_pk_add_f32 v[52:53], v[52:53], v[56:57]
	v_pk_add_f32 v[56:57], v[50:51], v[72:73]
	v_pk_add_f32 v[50:51], v[48:49], v[62:63]
	v_cvt_pk_bf16_f32 v48, v52, v53
	v_pk_add_f32 v[54:55], v[54:55], v[58:59]
	v_lshlrev_b32_e32 v52, 16, v48
	v_cvt_pk_bf16_f32 v49, v54, v55
	v_cvt_pk_bf16_f32 v50, v50, v51
	v_cvt_pk_bf16_f32 v51, v56, v57
	global_store_dwordx4 v[60:61], v[48:51], off offset:256
	s_nop 1
	v_and_b32_e32 v48, 0xffff0000, v48
	v_mul_f32_e32 v48, v48, v48
	v_fmac_f32_e32 v48, v52, v52
	v_lshlrev_b32_e32 v52, 16, v49
	v_and_b32_e32 v49, 0xffff0000, v49
	v_mul_f32_e32 v49, v49, v49
	v_add_f32_e32 v48, v82, v48
	v_fmac_f32_e32 v49, v52, v52
	v_add_f32_e32 v48, v48, v49
	v_lshlrev_b32_e32 v49, 16, v50
	v_and_b32_e32 v50, 0xffff0000, v50
	v_mul_f32_e32 v50, v50, v50
	v_fmac_f32_e32 v50, v49, v49
	v_add_f32_e32 v48, v48, v50
	v_and_b32_e32 v50, 0xffff0000, v51
	v_lshlrev_b32_e32 v49, 16, v51
	v_mul_f32_e32 v50, v50, v50
	v_fmac_f32_e32 v50, v49, v49
	v_add_f32_e32 v48, v48, v50
	v_mov_b32_e32 v49, v48
	s_nop 1
	v_permlane16_swap_b32_e32 v49, v48
	s_waitcnt lgkmcnt(0)
	v_add_f32_e32 v48, v48, v49
	v_mov_b32_e32 v49, v48
	s_nop 1
	v_permlane32_swap_b32_e32 v49, v48
	s_and_saveexec_b64 s[6:7], vcc
	s_cbranch_execz .LBB0_388
	v_lshlrev_b64 v[50:51], 6, v[80:81]
	v_lshl_add_u64 v[50:51], s[46:47], 0, v[50:51]
	v_lshl_add_u64 v[50:51], s[56:57], 2, v[50:51]
	s_lshl_b32 s38, s8, 2
	v_lshl_add_u64 v[50:51], v[50:51], 0, s[38:39]
	s_waitcnt lgkmcnt(0)
	v_add_f32_e32 v48, v48, v49
	flat_store_dword v[50:51], v48
.LBB0_388:
	s_or_b64 exec, exec, s[6:7]
	v_lshlrev_b32_e32 v48, 16, v68
	s_waitcnt lgkmcnt(0)
	v_and_b32_e32 v49, 0xffff0000, v68
	v_lshlrev_b32_e32 v52, 16, v70
	v_and_b32_e32 v53, 0xffff0000, v70
	v_lshlrev_b32_e32 v54, 16, v71
	v_and_b32_e32 v55, 0xffff0000, v71
	v_pk_add_f32 v[44:45], v[44:45], v[48:49]
	v_lshlrev_b32_e32 v50, 16, v69
	v_and_b32_e32 v51, 0xffff0000, v69
	v_pk_add_f32 v[48:49], v[42:43], v[54:55]
	v_pk_add_f32 v[42:43], v[40:41], v[52:53]
	v_cvt_pk_bf16_f32 v40, v44, v45
	v_lshl_add_u64 v[44:45], s[68:69], 0, v[78:79]
	v_pk_add_f32 v[46:47], v[46:47], v[50:51]
	v_lshl_add_u64 v[44:45], v[168:169], 1, v[44:45]
	v_cvt_pk_bf16_f32 v41, v46, v47
	v_cvt_pk_bf16_f32 v42, v42, v43
	v_cvt_pk_bf16_f32 v43, v48, v49
	global_store_dwordx4 v[44:45], v[40:43], off
	v_lshlrev_b32_e32 v46, 16, v40
	v_and_b32_e32 v47, 0xffff0000, v66
	v_and_b32_e32 v40, 0xffff0000, v40
	v_mul_f32_e32 v40, v40, v40
	v_fmac_f32_e32 v40, v46, v46
	v_lshlrev_b32_e32 v46, 16, v41
	v_and_b32_e32 v41, 0xffff0000, v41
	v_mul_f32_e32 v41, v41, v41
	v_fmac_f32_e32 v41, v46, v46
	v_add_f32_e32 v40, v40, v41
	v_lshlrev_b32_e32 v41, 16, v42
	v_and_b32_e32 v42, 0xffff0000, v42
	v_mul_f32_e32 v42, v42, v42
	v_fmac_f32_e32 v42, v41, v41
	v_add_f32_e32 v40, v40, v42
	v_and_b32_e32 v42, 0xffff0000, v43
	v_lshlrev_b32_e32 v41, 16, v43
	v_mul_f32_e32 v42, v42, v42
	v_fmac_f32_e32 v42, v41, v41
	v_add_f32_e32 v50, v40, v42
	v_lshlrev_b32_e32 v40, 16, v64
	v_and_b32_e32 v41, 0xffff0000, v64
	v_lshlrev_b32_e32 v46, 16, v66
	v_lshlrev_b32_e32 v42, 16, v65
	v_and_b32_e32 v43, 0xffff0000, v65
	v_lshlrev_b32_e32 v48, 16, v67
	v_and_b32_e32 v49, 0xffff0000, v67
	v_pk_add_f32 v[36:37], v[36:37], v[40:41]
	v_pk_add_f32 v[32:33], v[32:33], v[46:47]
	v_pk_add_f32 v[38:39], v[38:39], v[42:43]
	v_pk_add_f32 v[40:41], v[34:35], v[48:49]
	v_cvt_pk_bf16_f32 v34, v36, v37
	v_cvt_pk_bf16_f32 v35, v38, v39
	v_cvt_pk_bf16_f32 v36, v32, v33
	s_nop 0
	v_and_b32_e32 v33, 0xffff0000, v34
	v_lshlrev_b32_e32 v32, 16, v34
	v_mul_f32_e32 v33, v33, v33
	v_fmac_f32_e32 v33, v32, v32
	v_and_b32_e32 v38, 0xffff0000, v35
	v_add_f32_e32 v32, v50, v33
	v_lshlrev_b32_e32 v33, 16, v35
	v_mul_f32_e32 v38, v38, v38
	v_fmac_f32_e32 v38, v33, v33
	v_add_f32_e32 v32, v32, v38
	v_and_b32_e32 v38, 0xffff0000, v36
	v_lshlrev_b32_e32 v33, 16, v36
	v_mul_f32_e32 v38, v38, v38
	v_fmac_f32_e32 v38, v33, v33
	v_cvt_pk_bf16_f32 v37, v40, v41
	v_add_f32_e32 v32, v32, v38
	v_and_b32_e32 v38, 0xffff0000, v37
	v_lshlrev_b32_e32 v33, 16, v37
	v_mul_f32_e32 v38, v38, v38
	v_fmac_f32_e32 v38, v33, v33
	v_add_f32_e32 v32, v32, v38
	v_mov_b32_e32 v33, v32
	s_nop 1
	v_permlane16_swap_b32_e32 v33, v32
	global_store_dwordx4 v[44:45], v[34:37], off offset:256
	s_waitcnt lgkmcnt(0)
	v_add_f32_e32 v32, v32, v33
	v_mov_b32_e32 v33, v32
	s_nop 1
	v_permlane32_swap_b32_e32 v33, v32
	s_and_saveexec_b64 s[6:7], vcc
	s_cbranch_execz .LBB0_390
	v_lshlrev_b64 v[34:35], 6, v[76:77]
	v_lshl_add_u64 v[34:35], s[46:47], 0, v[34:35]
	v_lshl_add_u64 v[34:35], s[56:57], 2, v[34:35]
	s_lshl_b32 s38, s8, 2
	v_lshl_add_u64 v[34:35], v[34:35], 0, s[38:39]
	s_waitcnt lgkmcnt(0)
	v_add_f32_e32 v32, v32, v33
	flat_store_dword v[34:35], v32
.LBB0_390:
	s_or_b64 exec, exec, s[6:7]
	v_add_u32_e32 v48, 0xa0, v170
	v_ashrrev_i32_e32 v49, 31, v48
	v_lshlrev_b64 v[54:55], 11, v[48:49]
	s_waitcnt lgkmcnt(0)
	v_lshl_add_u64 v[32:33], v[172:173], 0, v[54:55]
	global_load_dwordx4 v[50:53], v[32:33], off
	global_load_dwordx4 v[40:43], v[32:33], off offset:256
	v_add_u32_e32 v44, 0xb0, v170
	v_ashrrev_i32_e32 v45, 31, v44
	v_lshlrev_b64 v[46:47], 11, v[44:45]
	v_lshl_add_u64 v[32:33], v[172:173], 0, v[46:47]
	global_load_dwordx4 v[36:39], v[32:33], off
	s_nop 0
	global_load_dwordx4 v[32:35], v[32:33], off offset:256
	s_waitcnt vmcnt(0)
	v_lshlrev_b32_e32 v56, 16, v50
	v_and_b32_e32 v57, 0xffff0000, v50
	v_lshlrev_b32_e32 v50, 16, v51
	v_and_b32_e32 v51, 0xffff0000, v51
	v_lshlrev_b32_e32 v58, 16, v52
	v_and_b32_e32 v59, 0xffff0000, v52
	v_lshlrev_b32_e32 v52, 16, v53
	v_and_b32_e32 v53, 0xffff0000, v53
	v_pk_add_f32 v[28:29], v[28:29], v[56:57]
	v_pk_add_f32 v[30:31], v[30:31], v[50:51]
	v_pk_add_f32 v[50:51], v[26:27], v[52:53]
	v_pk_add_f32 v[26:27], v[24:25], v[58:59]
	v_cvt_pk_bf16_f32 v24, v28, v29
	v_lshl_add_u64 v[28:29], s[68:69], 0, v[54:55]
	v_lshl_add_u64 v[28:29], v[168:169], 1, v[28:29]
	v_cvt_pk_bf16_f32 v25, v30, v31
	v_cvt_pk_bf16_f32 v26, v26, v27
	v_cvt_pk_bf16_f32 v27, v50, v51
	global_store_dwordx4 v[28:29], v[24:27], off
	v_lshlrev_b32_e32 v30, 16, v24
	v_and_b32_e32 v31, 0xffff0000, v42
	v_and_b32_e32 v24, 0xffff0000, v24
	v_mul_f32_e32 v24, v24, v24
	v_fmac_f32_e32 v24, v30, v30
	v_lshlrev_b32_e32 v30, 16, v25
	v_and_b32_e32 v25, 0xffff0000, v25
	v_mul_f32_e32 v25, v25, v25
	v_fmac_f32_e32 v25, v30, v30
	v_add_f32_e32 v24, v24, v25
	v_lshlrev_b32_e32 v25, 16, v26
	v_and_b32_e32 v26, 0xffff0000, v26
	v_mul_f32_e32 v26, v26, v26
	v_fmac_f32_e32 v26, v25, v25
	v_add_f32_e32 v24, v24, v26
	v_and_b32_e32 v26, 0xffff0000, v27
	v_lshlrev_b32_e32 v25, 16, v27
	v_mul_f32_e32 v26, v26, v26
	v_fmac_f32_e32 v26, v25, v25
	v_add_f32_e32 v50, v24, v26
	v_lshlrev_b32_e32 v24, 16, v40
	v_and_b32_e32 v25, 0xffff0000, v40
	v_lshlrev_b32_e32 v26, 16, v41
	v_and_b32_e32 v27, 0xffff0000, v41
	v_lshlrev_b32_e32 v30, 16, v42
	v_lshlrev_b32_e32 v40, 16, v43
	v_and_b32_e32 v41, 0xffff0000, v43
	v_pk_add_f32 v[20:21], v[20:21], v[24:25]
	v_pk_add_f32 v[24:25], v[18:19], v[40:41]
	v_pk_add_f32 v[18:19], v[16:17], v[30:31]
	v_cvt_pk_bf16_f32 v16, v20, v21
	v_pk_add_f32 v[22:23], v[22:23], v[26:27]
	v_lshlrev_b32_e32 v20, 16, v16
	v_cvt_pk_bf16_f32 v17, v22, v23
	v_cvt_pk_bf16_f32 v18, v18, v19
	v_cvt_pk_bf16_f32 v19, v24, v25
	global_store_dwordx4 v[28:29], v[16:19], off offset:256
	s_nop 1
	v_and_b32_e32 v16, 0xffff0000, v16
	v_mul_f32_e32 v16, v16, v16
	v_fmac_f32_e32 v16, v20, v20
	v_lshlrev_b32_e32 v20, 16, v17
	v_and_b32_e32 v17, 0xffff0000, v17
	v_mul_f32_e32 v17, v17, v17
	v_add_f32_e32 v16, v50, v16
	v_fmac_f32_e32 v17, v20, v20
	v_add_f32_e32 v16, v16, v17
	v_lshlrev_b32_e32 v17, 16, v18
	v_and_b32_e32 v18, 0xffff0000, v18
	v_mul_f32_e32 v18, v18, v18
	v_fmac_f32_e32 v18, v17, v17
	v_add_f32_e32 v16, v16, v18
	v_and_b32_e32 v18, 0xffff0000, v19
	v_lshlrev_b32_e32 v17, 16, v19
	v_mul_f32_e32 v18, v18, v18
	v_fmac_f32_e32 v18, v17, v17
	v_add_f32_e32 v16, v16, v18
	v_mov_b32_e32 v17, v16
	s_nop 1
	v_permlane16_swap_b32_e32 v17, v16
	s_waitcnt lgkmcnt(0)
	v_add_f32_e32 v16, v16, v17
	v_mov_b32_e32 v17, v16
	s_nop 1
	v_permlane32_swap_b32_e32 v17, v16
	s_and_saveexec_b64 s[6:7], vcc
	s_cbranch_execz .LBB0_392
	v_lshlrev_b64 v[18:19], 6, v[48:49]
	v_lshl_add_u64 v[18:19], s[46:47], 0, v[18:19]
	v_lshl_add_u64 v[18:19], s[56:57], 2, v[18:19]
	s_lshl_b32 s38, s8, 2
	v_lshl_add_u64 v[18:19], v[18:19], 0, s[38:39]
	s_waitcnt lgkmcnt(0)
	v_add_f32_e32 v16, v16, v17
	flat_store_dword v[18:19], v16
.LBB0_392:
	s_or_b64 exec, exec, s[6:7]
	v_lshlrev_b32_e32 v16, 16, v36
	s_waitcnt lgkmcnt(0)
	v_and_b32_e32 v17, 0xffff0000, v36
	v_lshlrev_b32_e32 v20, 16, v38
	v_and_b32_e32 v21, 0xffff0000, v38
	v_lshlrev_b32_e32 v22, 16, v39
	v_and_b32_e32 v23, 0xffff0000, v39
	v_pk_add_f32 v[12:13], v[12:13], v[16:17]
	v_lshlrev_b32_e32 v18, 16, v37
	v_and_b32_e32 v19, 0xffff0000, v37
	v_pk_add_f32 v[16:17], v[10:11], v[22:23]
	v_pk_add_f32 v[10:11], v[8:9], v[20:21]
	v_cvt_pk_bf16_f32 v8, v12, v13
	v_lshl_add_u64 v[12:13], s[68:69], 0, v[46:47]
	v_pk_add_f32 v[14:15], v[14:15], v[18:19]
	v_lshl_add_u64 v[12:13], v[168:169], 1, v[12:13]
	v_cvt_pk_bf16_f32 v9, v14, v15
	v_cvt_pk_bf16_f32 v10, v10, v11
	v_cvt_pk_bf16_f32 v11, v16, v17
	global_store_dwordx4 v[12:13], v[8:11], off
	v_lshlrev_b32_e32 v14, 16, v8
	v_and_b32_e32 v15, 0xffff0000, v34
	v_and_b32_e32 v8, 0xffff0000, v8
	v_mul_f32_e32 v8, v8, v8
	v_fmac_f32_e32 v8, v14, v14
	v_lshlrev_b32_e32 v14, 16, v9
	v_and_b32_e32 v9, 0xffff0000, v9
	v_mul_f32_e32 v9, v9, v9
	v_fmac_f32_e32 v9, v14, v14
	v_add_f32_e32 v8, v8, v9
	v_lshlrev_b32_e32 v9, 16, v10
	v_and_b32_e32 v10, 0xffff0000, v10
	v_mul_f32_e32 v10, v10, v10
	v_fmac_f32_e32 v10, v9, v9
	v_add_f32_e32 v8, v8, v10
	v_and_b32_e32 v10, 0xffff0000, v11
	v_lshlrev_b32_e32 v9, 16, v11
	v_mul_f32_e32 v10, v10, v10
	v_fmac_f32_e32 v10, v9, v9
	v_add_f32_e32 v18, v8, v10
	v_lshlrev_b32_e32 v8, 16, v32
	v_and_b32_e32 v9, 0xffff0000, v32
	v_lshlrev_b32_e32 v14, 16, v34
	v_lshlrev_b32_e32 v10, 16, v33
	v_and_b32_e32 v11, 0xffff0000, v33
	v_lshlrev_b32_e32 v16, 16, v35
	v_and_b32_e32 v17, 0xffff0000, v35
	v_pk_add_f32 v[4:5], v[4:5], v[8:9]
	v_pk_add_f32 v[0:1], v[0:1], v[14:15]
	v_pk_add_f32 v[6:7], v[6:7], v[10:11]
	v_pk_add_f32 v[8:9], v[2:3], v[16:17]
	v_cvt_pk_bf16_f32 v2, v4, v5
	v_cvt_pk_bf16_f32 v3, v6, v7
	v_cvt_pk_bf16_f32 v4, v0, v1
	s_nop 0
	v_and_b32_e32 v1, 0xffff0000, v2
	v_lshlrev_b32_e32 v0, 16, v2
	v_mul_f32_e32 v1, v1, v1
	v_fmac_f32_e32 v1, v0, v0
	v_and_b32_e32 v6, 0xffff0000, v3
	v_add_f32_e32 v0, v18, v1
	v_lshlrev_b32_e32 v1, 16, v3
	v_mul_f32_e32 v6, v6, v6
	v_fmac_f32_e32 v6, v1, v1
	v_add_f32_e32 v0, v0, v6
	v_and_b32_e32 v6, 0xffff0000, v4
	v_lshlrev_b32_e32 v1, 16, v4
	v_mul_f32_e32 v6, v6, v6
	v_fmac_f32_e32 v6, v1, v1
	v_cvt_pk_bf16_f32 v5, v8, v9
	v_add_f32_e32 v0, v0, v6
	v_and_b32_e32 v6, 0xffff0000, v5
	v_lshlrev_b32_e32 v1, 16, v5
	v_mul_f32_e32 v6, v6, v6
	v_fmac_f32_e32 v6, v1, v1
	v_add_f32_e32 v0, v0, v6
	v_mov_b32_e32 v1, v0
	s_nop 1
	v_permlane16_swap_b32_e32 v1, v0
	global_store_dwordx4 v[12:13], v[2:5], off offset:256
	s_waitcnt lgkmcnt(0)
	v_add_f32_e32 v0, v0, v1
	v_mov_b32_e32 v1, v0
	s_nop 1
	v_permlane32_swap_b32_e32 v1, v0
	s_and_saveexec_b64 s[6:7], vcc
	s_cbranch_execz .LBB0_394
	v_lshlrev_b64 v[2:3], 6, v[44:45]
	v_lshl_add_u64 v[2:3], s[46:47], 0, v[2:3]
	v_lshl_add_u64 v[2:3], s[56:57], 2, v[2:3]
	s_lshl_b32 s38, s8, 2
	v_lshl_add_u64 v[2:3], v[2:3], 0, s[38:39]
	s_waitcnt lgkmcnt(0)
	v_add_f32_e32 v0, v0, v1
	flat_store_dword v[2:3], v0

.LBB0_419:
	s_mov_b32 s6, -1
	s_lshl_b32 s5, s5, 8
	v_mbcnt_lo_u32_b32 v112, s6, 0
	v_mbcnt_hi_u32_b32 v112, s6, v112
	s_getreg_b32 s6, hwreg(HW_REG_HW_ID, 0, 6)
	s_and_b32 s6, s6, 63
	s_lshl_b32 s6, s6, 2
	s_add_i32 s6, s6, 0
	s_add_i32 s6, s6, 0x20200
	v_mov_b32_e32 v113, s6
	ds_read_b32 v113, v113
	v_bfrev_b32_e32 v114, 0.5
	s_movk_i32 s84, 0x80
	s_lshl_b32 s58, s4, 2
	s_ashr_i32 s59, s58, 31
	s_waitcnt lgkmcnt(0)
	v_readfirstlane_b32 s6, v113
	s_nop 1
	v_lshl_add_u32 v112, s6, 6, v112
	s_nop 0
	v_readfirstlane_b32 s6, v112
	s_bfe_u32 s8, s6, 0x20006
	s_ashr_i32 s6, s6, 2
	s_andn2_b32 s6, s6, 63
	s_add_i32 s6, s6, s5
	v_and_or_b32 v166, v112, 15, s6
	s_lshl_b32 s5, s4, 8
	s_lshl_b32 s6, s8, 5
	v_bfe_u32 v113, v112, 4, 2
	s_or_b32 s5, s6, s5
	v_lshl_or_b32 v164, v113, 3, s5
	v_ashrrev_i32_e32 v165, 31, v164
	v_lshlrev_b64 v[146:147], 1, v[164:165]
	v_ashrrev_i32_e32 v167, 31, v166
	v_lshlrev_b32_e32 v112, 2, v112
	v_lshl_add_u64 v[168:169], s[68:69], 0, v[146:147]
	v_lshlrev_b64 v[148:149], 11, v[166:167]
	v_bitop3_b32 v176, v112, 64, v114 bitop3:0x6c
	v_bitop3_b32 v177, v112, s84, v114 bitop3:0x6c
	v_cmp_eq_u32_e32 vcc, 0, v113
	v_lshl_add_u64 v[112:113], v[168:169], 0, v[148:149]
	global_load_dwordx4 v[142:145], v[112:113], off
	global_load_dwordx4 v[128:131], v[112:113], off offset:256
	v_or_b32_e32 v170, 16, v166
	v_ashrrev_i32_e32 v171, 31, v170
	v_lshlrev_b64 v[172:173], 11, v[170:171]
	v_lshl_add_u64 v[112:113], v[168:169], 0, v[172:173]
	global_load_dwordx4 v[116:119], v[112:113], off
	s_nop 0
	global_load_dwordx4 v[112:115], v[112:113], off offset:256
	s_waitcnt vmcnt(0)
	v_lshlrev_b32_e32 v150, 16, v142
	v_and_b32_e32 v151, 0xffff0000, v142
	v_lshlrev_b32_e32 v142, 16, v143
	v_and_b32_e32 v143, 0xffff0000, v143
	v_lshlrev_b32_e32 v152, 16, v144
	v_and_b32_e32 v153, 0xffff0000, v144
	v_pk_add_f32 v[134:135], v[134:135], v[142:143]
	v_pk_add_f32 v[132:133], v[132:133], v[150:151]
	v_pk_add_f32 v[136:137], v[136:137], v[152:153]
	v_lshlrev_b32_e32 v144, 16, v145
	v_and_b32_e32 v145, 0xffff0000, v145
	v_cvt_pk_bf16_f32 v132, v132, v133
	v_cvt_pk_bf16_f32 v133, v134, v135
	v_cvt_pk_bf16_f32 v134, v136, v137
	v_lshl_add_u64 v[136:137], s[68:69], 0, v[148:149]
	v_pk_add_f32 v[138:139], v[138:139], v[144:145]
	v_lshl_add_u64 v[136:137], v[136:137], 0, v[146:147]
	v_cvt_pk_bf16_f32 v135, v138, v139
	global_store_dwordx4 v[136:137], v[132:135], off
	v_lshlrev_b32_e32 v138, 16, v132
	s_nop 0
	v_and_b32_e32 v132, 0xffff0000, v132
	v_mul_f32_e32 v132, v132, v132
	v_fmac_f32_e32 v132, v138, v138
	v_lshlrev_b32_e32 v138, 16, v133
	v_and_b32_e32 v133, 0xffff0000, v133
	v_mul_f32_e32 v133, v133, v133
	v_fmac_f32_e32 v133, v138, v138
	v_add_f32_e32 v132, v132, v133
	v_lshlrev_b32_e32 v133, 16, v134
	v_and_b32_e32 v134, 0xffff0000, v134
	v_mul_f32_e32 v134, v134, v134
	v_fmac_f32_e32 v134, v133, v133
	v_add_f32_e32 v132, v132, v134
	v_and_b32_e32 v134, 0xffff0000, v135
	v_lshlrev_b32_e32 v133, 16, v135
	v_mul_f32_e32 v134, v134, v134
	v_fmac_f32_e32 v134, v133, v133
	v_add_f32_e32 v138, v132, v134
	v_lshlrev_b32_e32 v132, 16, v128
	v_and_b32_e32 v133, 0xffff0000, v128
	v_lshlrev_b32_e32 v128, 16, v129
	v_and_b32_e32 v129, 0xffff0000, v129
	v_lshlrev_b32_e32 v134, 16, v130
	v_and_b32_e32 v135, 0xffff0000, v130
	v_lshlrev_b32_e32 v130, 16, v131
	v_and_b32_e32 v131, 0xffff0000, v131
	v_pk_add_f32 v[126:127], v[126:127], v[128:129]
	v_pk_add_f32 v[124:125], v[124:125], v[132:133]
	v_pk_add_f32 v[128:129], v[122:123], v[130:131]
	v_pk_add_f32 v[122:123], v[120:121], v[134:135]
	v_cvt_pk_bf16_f32 v120, v124, v125
	v_cvt_pk_bf16_f32 v121, v126, v127
	s_nop 0
	v_cvt_pk_bf16_f32 v122, v122, v123
	v_cvt_pk_bf16_f32 v123, v128, v129
	global_store_dwordx4 v[136:137], v[120:123], off offset:256
	v_lshlrev_b32_e32 v124, 16, v120
	s_nop 0
	v_and_b32_e32 v120, 0xffff0000, v120
	v_mul_f32_e32 v120, v120, v120
	v_fmac_f32_e32 v120, v124, v124
	v_lshlrev_b32_e32 v124, 16, v121
	v_and_b32_e32 v121, 0xffff0000, v121
	v_mul_f32_e32 v121, v121, v121
	v_add_f32_e32 v120, v138, v120
	v_fmac_f32_e32 v121, v124, v124
	v_add_f32_e32 v120, v120, v121
	v_lshlrev_b32_e32 v121, 16, v122
	v_and_b32_e32 v122, 0xffff0000, v122
	v_mul_f32_e32 v122, v122, v122
	v_fmac_f32_e32 v122, v121, v121
	v_add_f32_e32 v120, v120, v122
	v_and_b32_e32 v122, 0xffff0000, v123
	v_lshlrev_b32_e32 v121, 16, v123
	v_mul_f32_e32 v122, v122, v122
	v_fmac_f32_e32 v122, v121, v121
	v_add_f32_e32 v120, v120, v122
	v_mov_b32_e32 v121, v120
	s_nop 1
	v_permlane16_swap_b32_e32 v121, v120
	s_waitcnt lgkmcnt(0)
	v_add_f32_e32 v120, v120, v121
	v_mov_b32_e32 v121, v120
	s_nop 1
	v_permlane32_swap_b32_e32 v121, v120
	s_and_saveexec_b64 s[6:7], vcc
	s_cbranch_execz .LBB0_421
	s_waitcnt lgkmcnt(0)
	v_add_f32_e32 v122, v120, v121
	v_lshlrev_b64 v[120:121], 6, v[166:167]
	v_lshl_add_u64 v[120:121], s[46:47], 0, v[120:121]
	v_lshl_add_u64 v[120:121], s[58:59], 2, v[120:121]
	s_lshl_b32 s38, s8, 2
	v_lshl_add_u64 v[120:121], v[120:121], 0, s[38:39]
	flat_store_dword v[120:121], v122
.LBB0_421:
	s_or_b64 exec, exec, s[6:7]
	v_lshlrev_b32_e32 v120, 16, v116
	s_waitcnt lgkmcnt(0)
	v_and_b32_e32 v121, 0xffff0000, v116
	v_lshlrev_b32_e32 v116, 16, v117
	v_and_b32_e32 v117, 0xffff0000, v117
	v_lshlrev_b32_e32 v122, 16, v118
	v_and_b32_e32 v123, 0xffff0000, v118
	v_lshlrev_b32_e32 v118, 16, v119
	v_and_b32_e32 v119, 0xffff0000, v119
	v_pk_add_f32 v[108:109], v[108:109], v[120:121]
	v_pk_add_f32 v[110:111], v[110:111], v[116:117]
	v_pk_add_f32 v[116:117], v[106:107], v[118:119]
	v_pk_add_f32 v[106:107], v[104:105], v[122:123]
	v_cvt_pk_bf16_f32 v104, v108, v109
	v_lshl_add_u64 v[108:109], s[68:69], 0, v[172:173]
	v_lshl_add_u64 v[108:109], v[164:165], 1, v[108:109]
	v_cvt_pk_bf16_f32 v105, v110, v111
	v_cvt_pk_bf16_f32 v106, v106, v107
	v_cvt_pk_bf16_f32 v107, v116, v117
	global_store_dwordx4 v[108:109], v[104:107], off
	v_lshlrev_b32_e32 v110, 16, v104
	v_and_b32_e32 v111, 0xffff0000, v114
	v_and_b32_e32 v104, 0xffff0000, v104
	v_mul_f32_e32 v104, v104, v104
	v_fmac_f32_e32 v104, v110, v110
	v_lshlrev_b32_e32 v110, 16, v105
	v_and_b32_e32 v105, 0xffff0000, v105
	v_mul_f32_e32 v105, v105, v105
	v_fmac_f32_e32 v105, v110, v110
	v_add_f32_e32 v104, v104, v105
	v_lshlrev_b32_e32 v105, 16, v106
	v_and_b32_e32 v106, 0xffff0000, v106
	v_mul_f32_e32 v106, v106, v106
	v_fmac_f32_e32 v106, v105, v105
	v_add_f32_e32 v104, v104, v106
	v_and_b32_e32 v106, 0xffff0000, v107
	v_lshlrev_b32_e32 v105, 16, v107
	v_mul_f32_e32 v106, v106, v106
	v_fmac_f32_e32 v106, v105, v105
	v_add_f32_e32 v116, v104, v106
	v_lshlrev_b32_e32 v104, 16, v112
	v_and_b32_e32 v105, 0xffff0000, v112
	v_lshlrev_b32_e32 v110, 16, v114
	v_lshlrev_b32_e32 v106, 16, v113
	v_and_b32_e32 v107, 0xffff0000, v113
	v_lshlrev_b32_e32 v112, 16, v115
	v_and_b32_e32 v113, 0xffff0000, v115
	v_pk_add_f32 v[100:101], v[100:101], v[104:105]
	v_pk_add_f32 v[96:97], v[96:97], v[110:111]
	v_pk_add_f32 v[102:103], v[102:103], v[106:107]
	v_pk_add_f32 v[104:105], v[98:99], v[112:113]
	v_cvt_pk_bf16_f32 v98, v100, v101
	v_cvt_pk_bf16_f32 v99, v102, v103
	v_cvt_pk_bf16_f32 v100, v96, v97
	s_nop 0
	v_and_b32_e32 v97, 0xffff0000, v98
	v_lshlrev_b32_e32 v96, 16, v98
	v_mul_f32_e32 v97, v97, v97
	v_fmac_f32_e32 v97, v96, v96
	v_and_b32_e32 v102, 0xffff0000, v99
	v_add_f32_e32 v96, v116, v97
	v_lshlrev_b32_e32 v97, 16, v99
	v_mul_f32_e32 v102, v102, v102
	v_fmac_f32_e32 v102, v97, v97
	v_add_f32_e32 v96, v96, v102
	v_and_b32_e32 v102, 0xffff0000, v100
	v_lshlrev_b32_e32 v97, 16, v100
	v_mul_f32_e32 v102, v102, v102
	v_fmac_f32_e32 v102, v97, v97
	v_cvt_pk_bf16_f32 v101, v104, v105
	v_add_f32_e32 v96, v96, v102
	v_and_b32_e32 v102, 0xffff0000, v101
	v_lshlrev_b32_e32 v97, 16, v101
	v_mul_f32_e32 v102, v102, v102
	v_fmac_f32_e32 v102, v97, v97
	v_add_f32_e32 v96, v96, v102
	v_mov_b32_e32 v97, v96
	s_nop 1
	v_permlane16_swap_b32_e32 v97, v96
	global_store_dwordx4 v[108:109], v[98:101], off offset:256
	s_waitcnt lgkmcnt(0)
	v_add_f32_e32 v96, v96, v97
	v_mov_b32_e32 v97, v96
	s_nop 1
	v_permlane32_swap_b32_e32 v97, v96
	s_mov_b64 s[6:7], exec
	s_and_b64 s[4:5], s[6:7], vcc
	v_mov_b32_e32 v198, v246
	v_mov_b32_e32 v199, v247
	v_mov_b32_e32 v205, v249
	v_mov_b32_e32 v196, v251
	v_mov_b32_e32 v251, 0x260
	s_mov_b64 exec, s[4:5]
	s_cbranch_execz .LBB0_423
	s_waitcnt lgkmcnt(0)
	v_add_f32_e32 v98, v96, v97
	v_lshlrev_b64 v[96:97], 6, v[170:171]
	v_lshl_add_u64 v[96:97], s[46:47], 0, v[96:97]
	v_lshl_add_u64 v[96:97], s[58:59], 2, v[96:97]
	s_lshl_b32 s38, s8, 2
	v_lshl_add_u64 v[96:97], v[96:97], 0, s[38:39]
	flat_store_dword v[96:97], v98
.LBB0_423:
	s_or_b64 exec, exec, s[6:7]
	v_or_b32_e32 v112, 32, v166
	v_ashrrev_i32_e32 v113, 31, v112
	v_lshlrev_b64 v[118:119], 11, v[112:113]
	s_waitcnt lgkmcnt(0)
	v_lshl_add_u64 v[96:97], v[168:169], 0, v[118:119]
	global_load_dwordx4 v[114:117], v[96:97], off
	global_load_dwordx4 v[104:107], v[96:97], off offset:256
	v_or_b32_e32 v108, 48, v166
	v_ashrrev_i32_e32 v109, 31, v108
	v_lshlrev_b64 v[110:111], 11, v[108:109]
	v_lshl_add_u64 v[96:97], v[168:169], 0, v[110:111]
	global_load_dwordx4 v[100:103], v[96:97], off
	s_nop 0
	global_load_dwordx4 v[96:99], v[96:97], off offset:256
	s_waitcnt vmcnt(0)
	v_lshlrev_b32_e32 v120, 16, v114
	v_and_b32_e32 v121, 0xffff0000, v114
	v_lshlrev_b32_e32 v114, 16, v115
	v_and_b32_e32 v115, 0xffff0000, v115
	v_lshlrev_b32_e32 v122, 16, v116
	v_and_b32_e32 v123, 0xffff0000, v116
	v_pk_add_f32 v[90:91], v[90:91], v[114:115]
	v_pk_add_f32 v[88:89], v[88:89], v[120:121]
	v_pk_add_f32 v[92:93], v[92:93], v[122:123]
	v_lshlrev_b32_e32 v116, 16, v117
	v_and_b32_e32 v117, 0xffff0000, v117
	v_cvt_pk_bf16_f32 v88, v88, v89
	v_cvt_pk_bf16_f32 v89, v90, v91
	v_cvt_pk_bf16_f32 v90, v92, v93
	v_lshl_add_u64 v[92:93], s[68:69], 0, v[118:119]
	v_pk_add_f32 v[94:95], v[94:95], v[116:117]
	v_lshl_add_u64 v[92:93], v[164:165], 1, v[92:93]
	v_cvt_pk_bf16_f32 v91, v94, v95
	global_store_dwordx4 v[92:93], v[88:91], off
	v_lshlrev_b32_e32 v94, 16, v88
	v_and_b32_e32 v95, 0xffff0000, v106
	v_and_b32_e32 v88, 0xffff0000, v88
	v_mul_f32_e32 v88, v88, v88
	v_fmac_f32_e32 v88, v94, v94
	v_lshlrev_b32_e32 v94, 16, v89
	v_and_b32_e32 v89, 0xffff0000, v89
	v_mul_f32_e32 v89, v89, v89
	v_fmac_f32_e32 v89, v94, v94
	v_add_f32_e32 v88, v88, v89
	v_lshlrev_b32_e32 v89, 16, v90
	v_and_b32_e32 v90, 0xffff0000, v90
	v_mul_f32_e32 v90, v90, v90
	v_fmac_f32_e32 v90, v89, v89
	v_add_f32_e32 v88, v88, v90
	v_and_b32_e32 v90, 0xffff0000, v91
	v_lshlrev_b32_e32 v89, 16, v91
	v_mul_f32_e32 v90, v90, v90
	v_fmac_f32_e32 v90, v89, v89
	v_add_f32_e32 v114, v88, v90
	v_lshlrev_b32_e32 v88, 16, v104
	v_and_b32_e32 v89, 0xffff0000, v104
	v_lshlrev_b32_e32 v90, 16, v105
	v_and_b32_e32 v91, 0xffff0000, v105
	v_lshlrev_b32_e32 v94, 16, v106
	v_lshlrev_b32_e32 v104, 16, v107
	v_and_b32_e32 v105, 0xffff0000, v107
	v_pk_add_f32 v[84:85], v[84:85], v[88:89]
	v_pk_add_f32 v[88:89], v[82:83], v[104:105]
	v_pk_add_f32 v[82:83], v[80:81], v[94:95]
	v_cvt_pk_bf16_f32 v80, v84, v85
	v_pk_add_f32 v[86:87], v[86:87], v[90:91]
	v_lshlrev_b32_e32 v84, 16, v80
	v_cvt_pk_bf16_f32 v81, v86, v87
	v_cvt_pk_bf16_f32 v82, v82, v83
	v_cvt_pk_bf16_f32 v83, v88, v89
	global_store_dwordx4 v[92:93], v[80:83], off offset:256
	s_nop 1
	v_and_b32_e32 v80, 0xffff0000, v80
	v_mul_f32_e32 v80, v80, v80
	v_fmac_f32_e32 v80, v84, v84
	v_lshlrev_b32_e32 v84, 16, v81
	v_and_b32_e32 v81, 0xffff0000, v81
	v_mul_f32_e32 v81, v81, v81
	v_add_f32_e32 v80, v114, v80
	v_fmac_f32_e32 v81, v84, v84
	v_add_f32_e32 v80, v80, v81
	v_lshlrev_b32_e32 v81, 16, v82
	v_and_b32_e32 v82, 0xffff0000, v82
	v_mul_f32_e32 v82, v82, v82
	v_fmac_f32_e32 v82, v81, v81
	v_add_f32_e32 v80, v80, v82
	v_and_b32_e32 v82, 0xffff0000, v83
	v_lshlrev_b32_e32 v81, 16, v83
	v_mul_f32_e32 v82, v82, v82
	v_fmac_f32_e32 v82, v81, v81
	v_add_f32_e32 v80, v80, v82
	v_mov_b32_e32 v81, v80
	s_nop 1
	v_permlane16_swap_b32_e32 v81, v80
	s_waitcnt lgkmcnt(0)
	v_add_f32_e32 v80, v80, v81
	v_mov_b32_e32 v81, v80
	s_nop 1
	v_permlane32_swap_b32_e32 v81, v80
	s_and_saveexec_b64 s[6:7], vcc
	s_cbranch_execz .LBB0_425
	s_waitcnt lgkmcnt(0)
	v_add_f32_e32 v82, v80, v81
	v_lshlrev_b64 v[80:81], 6, v[112:113]
	v_lshl_add_u64 v[80:81], s[46:47], 0, v[80:81]
	v_lshl_add_u64 v[80:81], s[58:59], 2, v[80:81]
	s_lshl_b32 s38, s8, 2
	v_lshl_add_u64 v[80:81], v[80:81], 0, s[38:39]
	flat_store_dword v[80:81], v82
.LBB0_425:
	s_or_b64 exec, exec, s[6:7]
	v_lshlrev_b32_e32 v80, 16, v100
	s_waitcnt lgkmcnt(0)
	v_and_b32_e32 v81, 0xffff0000, v100
	v_lshlrev_b32_e32 v84, 16, v102
	v_and_b32_e32 v85, 0xffff0000, v102
	v_lshlrev_b32_e32 v86, 16, v103
	v_and_b32_e32 v87, 0xffff0000, v103
	v_pk_add_f32 v[76:77], v[76:77], v[80:81]
	v_lshlrev_b32_e32 v82, 16, v101
	v_and_b32_e32 v83, 0xffff0000, v101
	v_pk_add_f32 v[80:81], v[74:75], v[86:87]
	v_pk_add_f32 v[74:75], v[72:73], v[84:85]
	v_cvt_pk_bf16_f32 v72, v76, v77
	v_lshl_add_u64 v[76:77], s[68:69], 0, v[110:111]
	v_pk_add_f32 v[78:79], v[78:79], v[82:83]
	v_lshl_add_u64 v[76:77], v[164:165], 1, v[76:77]
	v_cvt_pk_bf16_f32 v73, v78, v79
	v_cvt_pk_bf16_f32 v74, v74, v75
	v_cvt_pk_bf16_f32 v75, v80, v81
	global_store_dwordx4 v[76:77], v[72:75], off
	v_lshlrev_b32_e32 v78, 16, v72
	v_and_b32_e32 v79, 0xffff0000, v98
	v_and_b32_e32 v72, 0xffff0000, v72
	v_mul_f32_e32 v72, v72, v72
	v_fmac_f32_e32 v72, v78, v78
	v_lshlrev_b32_e32 v78, 16, v73
	v_and_b32_e32 v73, 0xffff0000, v73
	v_mul_f32_e32 v73, v73, v73
	v_fmac_f32_e32 v73, v78, v78
	v_add_f32_e32 v72, v72, v73
	v_lshlrev_b32_e32 v73, 16, v74
	v_and_b32_e32 v74, 0xffff0000, v74
	v_mul_f32_e32 v74, v74, v74
	v_fmac_f32_e32 v74, v73, v73
	v_add_f32_e32 v72, v72, v74
	v_and_b32_e32 v74, 0xffff0000, v75
	v_lshlrev_b32_e32 v73, 16, v75
	v_mul_f32_e32 v74, v74, v74
	v_fmac_f32_e32 v74, v73, v73
	v_add_f32_e32 v82, v72, v74
	v_lshlrev_b32_e32 v72, 16, v96
	v_and_b32_e32 v73, 0xffff0000, v96
	v_lshlrev_b32_e32 v78, 16, v98
	v_lshlrev_b32_e32 v74, 16, v97
	v_and_b32_e32 v75, 0xffff0000, v97
	v_lshlrev_b32_e32 v80, 16, v99
	v_and_b32_e32 v81, 0xffff0000, v99
	v_pk_add_f32 v[68:69], v[68:69], v[72:73]
	v_pk_add_f32 v[64:65], v[64:65], v[78:79]
	v_pk_add_f32 v[70:71], v[70:71], v[74:75]
	v_pk_add_f32 v[72:73], v[66:67], v[80:81]
	v_cvt_pk_bf16_f32 v66, v68, v69
	v_cvt_pk_bf16_f32 v67, v70, v71
	v_cvt_pk_bf16_f32 v68, v64, v65
	s_nop 0
	v_and_b32_e32 v65, 0xffff0000, v66
	v_lshlrev_b32_e32 v64, 16, v66
	v_mul_f32_e32 v65, v65, v65
	v_fmac_f32_e32 v65, v64, v64
	v_and_b32_e32 v70, 0xffff0000, v67
	v_add_f32_e32 v64, v82, v65
	v_lshlrev_b32_e32 v65, 16, v67
	v_mul_f32_e32 v70, v70, v70
	v_fmac_f32_e32 v70, v65, v65
	v_add_f32_e32 v64, v64, v70
	v_and_b32_e32 v70, 0xffff0000, v68
	v_lshlrev_b32_e32 v65, 16, v68
	v_mul_f32_e32 v70, v70, v70
	v_fmac_f32_e32 v70, v65, v65
	v_cvt_pk_bf16_f32 v69, v72, v73
	v_add_f32_e32 v64, v64, v70
	v_and_b32_e32 v70, 0xffff0000, v69
	v_lshlrev_b32_e32 v65, 16, v69
	v_mul_f32_e32 v70, v70, v70
	v_fmac_f32_e32 v70, v65, v65
	v_add_f32_e32 v64, v64, v70
	v_mov_b32_e32 v65, v64
	s_nop 1
	v_permlane16_swap_b32_e32 v65, v64
	global_store_dwordx4 v[76:77], v[66:69], off offset:256
	s_waitcnt lgkmcnt(0)
	v_add_f32_e32 v64, v64, v65
	v_mov_b32_e32 v65, v64
	s_nop 1
	v_permlane32_swap_b32_e32 v65, v64
	s_and_saveexec_b64 s[6:7], vcc
	s_cbranch_execz .LBB0_427
	s_waitcnt lgkmcnt(0)
	v_add_f32_e32 v66, v64, v65
	v_lshlrev_b64 v[64:65], 6, v[108:109]
	v_lshl_add_u64 v[64:65], s[46:47], 0, v[64:65]
	v_lshl_add_u64 v[64:65], s[58:59], 2, v[64:65]
	s_lshl_b32 s38, s8, 2
	v_lshl_add_u64 v[64:65], v[64:65], 0, s[38:39]
	flat_store_dword v[64:65], v66
.LBB0_427:
	s_or_b64 exec, exec, s[6:7]
	v_add_u32_e32 v80, 0x80, v166
	v_ashrrev_i32_e32 v81, 31, v80
	v_lshlrev_b64 v[86:87], 11, v[80:81]
	s_waitcnt lgkmcnt(0)
	v_lshl_add_u64 v[64:65], v[168:169], 0, v[86:87]
	global_load_dwordx4 v[82:85], v[64:65], off
	global_load_dwordx4 v[72:75], v[64:65], off offset:256
	v_add_u32_e32 v76, 0x90, v166
	v_ashrrev_i32_e32 v77, 31, v76
	v_lshlrev_b64 v[78:79], 11, v[76:77]
	v_lshl_add_u64 v[64:65], v[168:169], 0, v[78:79]
	global_load_dwordx4 v[68:71], v[64:65], off
	s_nop 0
	global_load_dwordx4 v[64:67], v[64:65], off offset:256
	s_waitcnt vmcnt(0)
	v_lshlrev_b32_e32 v88, 16, v82
	v_and_b32_e32 v89, 0xffff0000, v82
	v_lshlrev_b32_e32 v82, 16, v83
	v_and_b32_e32 v83, 0xffff0000, v83
	v_lshlrev_b32_e32 v90, 16, v84
	v_and_b32_e32 v91, 0xffff0000, v84
	v_pk_add_f32 v[58:59], v[58:59], v[82:83]
	v_pk_add_f32 v[56:57], v[56:57], v[88:89]
	v_pk_add_f32 v[60:61], v[60:61], v[90:91]
	v_lshlrev_b32_e32 v84, 16, v85
	v_and_b32_e32 v85, 0xffff0000, v85
	v_cvt_pk_bf16_f32 v56, v56, v57
	v_cvt_pk_bf16_f32 v57, v58, v59
	v_cvt_pk_bf16_f32 v58, v60, v61
	v_lshl_add_u64 v[60:61], s[68:69], 0, v[86:87]
	v_pk_add_f32 v[62:63], v[62:63], v[84:85]
	v_lshl_add_u64 v[60:61], v[164:165], 1, v[60:61]
	v_cvt_pk_bf16_f32 v59, v62, v63
	global_store_dwordx4 v[60:61], v[56:59], off
	v_lshlrev_b32_e32 v62, 16, v56
	v_and_b32_e32 v63, 0xffff0000, v74
	v_and_b32_e32 v56, 0xffff0000, v56
	v_mul_f32_e32 v56, v56, v56
	v_fmac_f32_e32 v56, v62, v62
	v_lshlrev_b32_e32 v62, 16, v57
	v_and_b32_e32 v57, 0xffff0000, v57
	v_mul_f32_e32 v57, v57, v57
	v_fmac_f32_e32 v57, v62, v62
	v_add_f32_e32 v56, v56, v57
	v_lshlrev_b32_e32 v57, 16, v58
	v_and_b32_e32 v58, 0xffff0000, v58
	v_mul_f32_e32 v58, v58, v58
	v_fmac_f32_e32 v58, v57, v57
	v_add_f32_e32 v56, v56, v58
	v_and_b32_e32 v58, 0xffff0000, v59
	v_lshlrev_b32_e32 v57, 16, v59
	v_mul_f32_e32 v58, v58, v58
	v_fmac_f32_e32 v58, v57, v57
	v_add_f32_e32 v82, v56, v58
	v_lshlrev_b32_e32 v56, 16, v72
	v_and_b32_e32 v57, 0xffff0000, v72
	v_lshlrev_b32_e32 v58, 16, v73
	v_and_b32_e32 v59, 0xffff0000, v73
	v_lshlrev_b32_e32 v62, 16, v74
	v_lshlrev_b32_e32 v72, 16, v75
	v_and_b32_e32 v73, 0xffff0000, v75
	v_pk_add_f32 v[52:53], v[52:53], v[56:57]
	v_pk_add_f32 v[56:57], v[50:51], v[72:73]
	v_pk_add_f32 v[50:51], v[48:49], v[62:63]
	v_cvt_pk_bf16_f32 v48, v52, v53
	v_pk_add_f32 v[54:55], v[54:55], v[58:59]
	v_lshlrev_b32_e32 v52, 16, v48
	v_cvt_pk_bf16_f32 v49, v54, v55
	v_cvt_pk_bf16_f32 v50, v50, v51
	v_cvt_pk_bf16_f32 v51, v56, v57
	global_store_dwordx4 v[60:61], v[48:51], off offset:256
	s_nop 1
	v_and_b32_e32 v48, 0xffff0000, v48
	v_mul_f32_e32 v48, v48, v48
	v_fmac_f32_e32 v48, v52, v52
	v_lshlrev_b32_e32 v52, 16, v49
	v_and_b32_e32 v49, 0xffff0000, v49
	v_mul_f32_e32 v49, v49, v49
	v_add_f32_e32 v48, v82, v48
	v_fmac_f32_e32 v49, v52, v52
	v_add_f32_e32 v48, v48, v49
	v_lshlrev_b32_e32 v49, 16, v50
	v_and_b32_e32 v50, 0xffff0000, v50
	v_mul_f32_e32 v50, v50, v50
	v_fmac_f32_e32 v50, v49, v49
	v_add_f32_e32 v48, v48, v50
	v_and_b32_e32 v50, 0xffff0000, v51
	v_lshlrev_b32_e32 v49, 16, v51
	v_mul_f32_e32 v50, v50, v50
	v_fmac_f32_e32 v50, v49, v49
	v_add_f32_e32 v48, v48, v50
	v_mov_b32_e32 v49, v48
	s_nop 1
	v_permlane16_swap_b32_e32 v49, v48
	s_waitcnt lgkmcnt(0)
	v_add_f32_e32 v48, v48, v49
	v_mov_b32_e32 v49, v48
	s_nop 1
	v_permlane32_swap_b32_e32 v49, v48
	s_and_saveexec_b64 s[6:7], vcc
	s_cbranch_execz .LBB0_429
	s_waitcnt lgkmcnt(0)
	v_add_f32_e32 v50, v48, v49
	v_lshlrev_b64 v[48:49], 6, v[80:81]
	v_lshl_add_u64 v[48:49], s[46:47], 0, v[48:49]
	v_lshl_add_u64 v[48:49], s[58:59], 2, v[48:49]
	s_lshl_b32 s38, s8, 2
	v_lshl_add_u64 v[48:49], v[48:49], 0, s[38:39]
	flat_store_dword v[48:49], v50
.LBB0_429:
	s_or_b64 exec, exec, s[6:7]
	v_lshlrev_b32_e32 v48, 16, v68
	s_waitcnt lgkmcnt(0)
	v_and_b32_e32 v49, 0xffff0000, v68
	v_lshlrev_b32_e32 v52, 16, v70
	v_and_b32_e32 v53, 0xffff0000, v70
	v_lshlrev_b32_e32 v54, 16, v71
	v_and_b32_e32 v55, 0xffff0000, v71
	v_pk_add_f32 v[44:45], v[44:45], v[48:49]
	v_lshlrev_b32_e32 v50, 16, v69
	v_and_b32_e32 v51, 0xffff0000, v69
	v_pk_add_f32 v[48:49], v[42:43], v[54:55]
	v_pk_add_f32 v[42:43], v[40:41], v[52:53]
	v_cvt_pk_bf16_f32 v40, v44, v45
	v_lshl_add_u64 v[44:45], s[68:69], 0, v[78:79]
	v_pk_add_f32 v[46:47], v[46:47], v[50:51]
	v_lshl_add_u64 v[44:45], v[164:165], 1, v[44:45]
	v_cvt_pk_bf16_f32 v41, v46, v47
	v_cvt_pk_bf16_f32 v42, v42, v43
	v_cvt_pk_bf16_f32 v43, v48, v49
	global_store_dwordx4 v[44:45], v[40:43], off
	v_lshlrev_b32_e32 v46, 16, v40
	v_and_b32_e32 v47, 0xffff0000, v66
	v_and_b32_e32 v40, 0xffff0000, v40
	v_mul_f32_e32 v40, v40, v40
	v_fmac_f32_e32 v40, v46, v46
	v_lshlrev_b32_e32 v46, 16, v41
	v_and_b32_e32 v41, 0xffff0000, v41
	v_mul_f32_e32 v41, v41, v41
	v_fmac_f32_e32 v41, v46, v46
	v_add_f32_e32 v40, v40, v41
	v_lshlrev_b32_e32 v41, 16, v42
	v_and_b32_e32 v42, 0xffff0000, v42
	v_mul_f32_e32 v42, v42, v42
	v_fmac_f32_e32 v42, v41, v41
	v_add_f32_e32 v40, v40, v42
	v_and_b32_e32 v42, 0xffff0000, v43
	v_lshlrev_b32_e32 v41, 16, v43
	v_mul_f32_e32 v42, v42, v42
	v_fmac_f32_e32 v42, v41, v41
	v_add_f32_e32 v50, v40, v42
	v_lshlrev_b32_e32 v40, 16, v64
	v_and_b32_e32 v41, 0xffff0000, v64
	v_lshlrev_b32_e32 v46, 16, v66
	v_lshlrev_b32_e32 v42, 16, v65
	v_and_b32_e32 v43, 0xffff0000, v65
	v_lshlrev_b32_e32 v48, 16, v67
	v_and_b32_e32 v49, 0xffff0000, v67
	v_pk_add_f32 v[36:37], v[36:37], v[40:41]
	v_pk_add_f32 v[32:33], v[32:33], v[46:47]
	v_pk_add_f32 v[38:39], v[38:39], v[42:43]
	v_pk_add_f32 v[40:41], v[34:35], v[48:49]
	v_cvt_pk_bf16_f32 v34, v36, v37
	v_cvt_pk_bf16_f32 v35, v38, v39
	v_cvt_pk_bf16_f32 v36, v32, v33
	s_nop 0
	v_and_b32_e32 v33, 0xffff0000, v34
	v_lshlrev_b32_e32 v32, 16, v34
	v_mul_f32_e32 v33, v33, v33
	v_fmac_f32_e32 v33, v32, v32
	v_and_b32_e32 v38, 0xffff0000, v35
	v_add_f32_e32 v32, v50, v33
	v_lshlrev_b32_e32 v33, 16, v35
	v_mul_f32_e32 v38, v38, v38
	v_fmac_f32_e32 v38, v33, v33
	v_add_f32_e32 v32, v32, v38
	v_and_b32_e32 v38, 0xffff0000, v36
	v_lshlrev_b32_e32 v33, 16, v36
	v_mul_f32_e32 v38, v38, v38
	v_fmac_f32_e32 v38, v33, v33
	v_cvt_pk_bf16_f32 v37, v40, v41
	v_add_f32_e32 v32, v32, v38
	v_and_b32_e32 v38, 0xffff0000, v37
	v_lshlrev_b32_e32 v33, 16, v37
	v_mul_f32_e32 v38, v38, v38
	v_fmac_f32_e32 v38, v33, v33
	v_add_f32_e32 v32, v32, v38
	v_mov_b32_e32 v33, v32
	s_nop 1
	v_permlane16_swap_b32_e32 v33, v32
	global_store_dwordx4 v[44:45], v[34:37], off offset:256
	s_waitcnt lgkmcnt(0)
	v_add_f32_e32 v32, v32, v33
	v_mov_b32_e32 v33, v32
	s_nop 1
	v_permlane32_swap_b32_e32 v33, v32
	s_and_saveexec_b64 s[6:7], vcc
	s_cbranch_execz .LBB0_431
	s_waitcnt lgkmcnt(0)
	v_add_f32_e32 v34, v32, v33
	v_lshlrev_b64 v[32:33], 6, v[76:77]
	v_lshl_add_u64 v[32:33], s[46:47], 0, v[32:33]
	v_lshl_add_u64 v[32:33], s[58:59], 2, v[32:33]
	s_lshl_b32 s38, s8, 2
	v_lshl_add_u64 v[32:33], v[32:33], 0, s[38:39]
	flat_store_dword v[32:33], v34
.LBB0_431:
	s_or_b64 exec, exec, s[6:7]
	v_add_u32_e32 v48, 0xa0, v166
	v_ashrrev_i32_e32 v49, 31, v48
	v_lshlrev_b64 v[54:55], 11, v[48:49]
	s_waitcnt lgkmcnt(0)
	v_lshl_add_u64 v[32:33], v[168:169], 0, v[54:55]
	global_load_dwordx4 v[50:53], v[32:33], off
	global_load_dwordx4 v[40:43], v[32:33], off offset:256
	v_add_u32_e32 v44, 0xb0, v166
	v_ashrrev_i32_e32 v45, 31, v44
	v_lshlrev_b64 v[46:47], 11, v[44:45]
	v_lshl_add_u64 v[32:33], v[168:169], 0, v[46:47]
	global_load_dwordx4 v[36:39], v[32:33], off
	s_nop 0
	global_load_dwordx4 v[32:35], v[32:33], off offset:256
	s_waitcnt vmcnt(0)
	v_lshlrev_b32_e32 v56, 16, v50
	v_and_b32_e32 v57, 0xffff0000, v50
	v_lshlrev_b32_e32 v50, 16, v51
	v_and_b32_e32 v51, 0xffff0000, v51
	v_lshlrev_b32_e32 v58, 16, v52
	v_and_b32_e32 v59, 0xffff0000, v52
	v_pk_add_f32 v[26:27], v[26:27], v[50:51]
	v_pk_add_f32 v[24:25], v[24:25], v[56:57]
	v_pk_add_f32 v[28:29], v[28:29], v[58:59]
	v_lshlrev_b32_e32 v52, 16, v53
	v_and_b32_e32 v53, 0xffff0000, v53
	v_cvt_pk_bf16_f32 v24, v24, v25
	v_cvt_pk_bf16_f32 v25, v26, v27
	v_cvt_pk_bf16_f32 v26, v28, v29
	v_lshl_add_u64 v[28:29], s[68:69], 0, v[54:55]
	v_pk_add_f32 v[30:31], v[30:31], v[52:53]
	v_lshl_add_u64 v[28:29], v[164:165], 1, v[28:29]
	v_cvt_pk_bf16_f32 v27, v30, v31
	global_store_dwordx4 v[28:29], v[24:27], off
	v_lshlrev_b32_e32 v30, 16, v24
	v_and_b32_e32 v31, 0xffff0000, v42
	v_and_b32_e32 v24, 0xffff0000, v24
	v_mul_f32_e32 v24, v24, v24
	v_fmac_f32_e32 v24, v30, v30
	v_lshlrev_b32_e32 v30, 16, v25
	v_and_b32_e32 v25, 0xffff0000, v25
	v_mul_f32_e32 v25, v25, v25
	v_fmac_f32_e32 v25, v30, v30
	v_add_f32_e32 v24, v24, v25
	v_lshlrev_b32_e32 v25, 16, v26
	v_and_b32_e32 v26, 0xffff0000, v26
	v_mul_f32_e32 v26, v26, v26
	v_fmac_f32_e32 v26, v25, v25
	v_add_f32_e32 v24, v24, v26
	v_and_b32_e32 v26, 0xffff0000, v27
	v_lshlrev_b32_e32 v25, 16, v27
	v_mul_f32_e32 v26, v26, v26
	v_fmac_f32_e32 v26, v25, v25
	v_add_f32_e32 v50, v24, v26
	v_lshlrev_b32_e32 v24, 16, v40
	v_and_b32_e32 v25, 0xffff0000, v40
	v_lshlrev_b32_e32 v26, 16, v41
	v_and_b32_e32 v27, 0xffff0000, v41
	v_lshlrev_b32_e32 v30, 16, v42
	v_lshlrev_b32_e32 v40, 16, v43
	v_and_b32_e32 v41, 0xffff0000, v43
	v_pk_add_f32 v[20:21], v[20:21], v[24:25]
	v_pk_add_f32 v[24:25], v[18:19], v[40:41]
	v_pk_add_f32 v[18:19], v[16:17], v[30:31]
	v_cvt_pk_bf16_f32 v16, v20, v21
	v_pk_add_f32 v[22:23], v[22:23], v[26:27]
	v_lshlrev_b32_e32 v20, 16, v16
	v_cvt_pk_bf16_f32 v17, v22, v23
	v_cvt_pk_bf16_f32 v18, v18, v19
	v_cvt_pk_bf16_f32 v19, v24, v25
	global_store_dwordx4 v[28:29], v[16:19], off offset:256
	s_nop 1
	v_and_b32_e32 v16, 0xffff0000, v16
	v_mul_f32_e32 v16, v16, v16
	v_fmac_f32_e32 v16, v20, v20
	v_lshlrev_b32_e32 v20, 16, v17
	v_and_b32_e32 v17, 0xffff0000, v17
	v_mul_f32_e32 v17, v17, v17
	v_add_f32_e32 v16, v50, v16
	v_fmac_f32_e32 v17, v20, v20
	v_add_f32_e32 v16, v16, v17
	v_lshlrev_b32_e32 v17, 16, v18
	v_and_b32_e32 v18, 0xffff0000, v18
	v_mul_f32_e32 v18, v18, v18
	v_fmac_f32_e32 v18, v17, v17
	v_add_f32_e32 v16, v16, v18
	v_and_b32_e32 v18, 0xffff0000, v19
	v_lshlrev_b32_e32 v17, 16, v19
	v_mul_f32_e32 v18, v18, v18
	v_fmac_f32_e32 v18, v17, v17
	v_add_f32_e32 v16, v16, v18
	v_mov_b32_e32 v17, v16
	s_nop 1
	v_permlane16_swap_b32_e32 v17, v16
	s_waitcnt lgkmcnt(0)
	v_add_f32_e32 v16, v16, v17
	v_mov_b32_e32 v17, v16
	s_nop 1
	v_permlane32_swap_b32_e32 v17, v16
	s_and_saveexec_b64 s[6:7], vcc
	s_cbranch_execz .LBB0_433
	s_waitcnt lgkmcnt(0)
	v_add_f32_e32 v18, v16, v17
	v_lshlrev_b64 v[16:17], 6, v[48:49]
	v_lshl_add_u64 v[16:17], s[46:47], 0, v[16:17]
	v_lshl_add_u64 v[16:17], s[58:59], 2, v[16:17]
	s_lshl_b32 s38, s8, 2
	v_lshl_add_u64 v[16:17], v[16:17], 0, s[38:39]
	flat_store_dword v[16:17], v18
.LBB0_433:
	s_or_b64 exec, exec, s[6:7]
	v_lshlrev_b32_e32 v16, 16, v36
	s_waitcnt lgkmcnt(0)
	v_and_b32_e32 v17, 0xffff0000, v36
	v_lshlrev_b32_e32 v20, 16, v38
	v_and_b32_e32 v21, 0xffff0000, v38
	v_lshlrev_b32_e32 v22, 16, v39
	v_and_b32_e32 v23, 0xffff0000, v39
	v_pk_add_f32 v[12:13], v[12:13], v[16:17]
	v_lshlrev_b32_e32 v18, 16, v37
	v_and_b32_e32 v19, 0xffff0000, v37
	v_pk_add_f32 v[16:17], v[10:11], v[22:23]
	v_pk_add_f32 v[10:11], v[8:9], v[20:21]
	v_cvt_pk_bf16_f32 v8, v12, v13
	v_lshl_add_u64 v[12:13], s[68:69], 0, v[46:47]
	v_pk_add_f32 v[14:15], v[14:15], v[18:19]
	v_lshl_add_u64 v[12:13], v[164:165], 1, v[12:13]
	v_cvt_pk_bf16_f32 v9, v14, v15
	v_cvt_pk_bf16_f32 v10, v10, v11
	v_cvt_pk_bf16_f32 v11, v16, v17
	global_store_dwordx4 v[12:13], v[8:11], off
	v_lshlrev_b32_e32 v14, 16, v8
	v_and_b32_e32 v15, 0xffff0000, v34
	v_and_b32_e32 v8, 0xffff0000, v8
	v_mul_f32_e32 v8, v8, v8
	v_fmac_f32_e32 v8, v14, v14
	v_lshlrev_b32_e32 v14, 16, v9
	v_and_b32_e32 v9, 0xffff0000, v9
	v_mul_f32_e32 v9, v9, v9
	v_fmac_f32_e32 v9, v14, v14
	v_add_f32_e32 v8, v8, v9
	v_lshlrev_b32_e32 v9, 16, v10
	v_and_b32_e32 v10, 0xffff0000, v10
	v_mul_f32_e32 v10, v10, v10
	v_fmac_f32_e32 v10, v9, v9
	v_add_f32_e32 v8, v8, v10
	v_and_b32_e32 v10, 0xffff0000, v11
	v_lshlrev_b32_e32 v9, 16, v11
	v_mul_f32_e32 v10, v10, v10
	v_fmac_f32_e32 v10, v9, v9
	v_add_f32_e32 v18, v8, v10
	v_lshlrev_b32_e32 v8, 16, v32
	v_and_b32_e32 v9, 0xffff0000, v32
	v_lshlrev_b32_e32 v14, 16, v34
	v_lshlrev_b32_e32 v10, 16, v33
	v_and_b32_e32 v11, 0xffff0000, v33
	v_lshlrev_b32_e32 v16, 16, v35
	v_and_b32_e32 v17, 0xffff0000, v35
	v_pk_add_f32 v[4:5], v[4:5], v[8:9]
	v_pk_add_f32 v[0:1], v[0:1], v[14:15]
	v_pk_add_f32 v[6:7], v[6:7], v[10:11]
	v_pk_add_f32 v[8:9], v[2:3], v[16:17]
	v_cvt_pk_bf16_f32 v2, v4, v5
	v_cvt_pk_bf16_f32 v3, v6, v7
	v_cvt_pk_bf16_f32 v4, v0, v1
	s_nop 0
	v_and_b32_e32 v1, 0xffff0000, v2
	v_lshlrev_b32_e32 v0, 16, v2
	v_mul_f32_e32 v1, v1, v1
	v_fmac_f32_e32 v1, v0, v0
	v_and_b32_e32 v6, 0xffff0000, v3
	v_add_f32_e32 v0, v18, v1
	v_lshlrev_b32_e32 v1, 16, v3
	v_mul_f32_e32 v6, v6, v6
	v_fmac_f32_e32 v6, v1, v1
	v_add_f32_e32 v0, v0, v6
	v_and_b32_e32 v6, 0xffff0000, v4
	v_lshlrev_b32_e32 v1, 16, v4
	v_mul_f32_e32 v6, v6, v6
	v_fmac_f32_e32 v6, v1, v1
	v_cvt_pk_bf16_f32 v5, v8, v9
	v_add_f32_e32 v0, v0, v6
	v_and_b32_e32 v6, 0xffff0000, v5
	v_lshlrev_b32_e32 v1, 16, v5
	v_mul_f32_e32 v6, v6, v6
	v_fmac_f32_e32 v6, v1, v1
	v_add_f32_e32 v0, v0, v6
	v_mov_b32_e32 v1, v0
	s_nop 1
	v_permlane16_swap_b32_e32 v1, v0
	global_store_dwordx4 v[12:13], v[2:5], off offset:256
	s_waitcnt lgkmcnt(0)
	v_add_f32_e32 v0, v0, v1
	v_mov_b32_e32 v1, v0
	s_nop 1
	v_permlane32_swap_b32_e32 v1, v0
	s_and_saveexec_b64 s[6:7], vcc
	s_cbranch_execz .LBB0_435
	s_waitcnt lgkmcnt(0)
	v_add_f32_e32 v2, v0, v1
	v_lshlrev_b64 v[0:1], 6, v[44:45]
	v_lshl_add_u64 v[0:1], s[46:47], 0, v[0:1]
	v_lshl_add_u64 v[0:1], s[58:59], 2, v[0:1]
	s_lshl_b32 s38, s8, 2
	v_lshl_add_u64 v[0:1], v[0:1], 0, s[38:39]
	flat_store_dword v[0:1], v2

.LBB0_459:
	s_mov_b32 s6, -1
	s_lshl_b32 s5, s5, 8
	v_mbcnt_lo_u32_b32 v134, s6, 0
	v_mbcnt_hi_u32_b32 v134, s6, v134
	s_getreg_b32 s6, hwreg(HW_REG_HW_ID, 0, 6)
	s_and_b32 s6, s6, 63
	s_lshl_b32 s6, s6, 2
	s_add_i32 s6, s6, 0
	s_add_i32 s6, s6, 0x20200
	v_mov_b32_e32 v135, s6
	ds_read_b32 v135, v135
	v_bfrev_b32_e32 v143, 0.5
	s_movk_i32 s84, 0x80
	s_waitcnt lgkmcnt(0)
	v_readfirstlane_b32 s6, v135
	s_nop 1
	v_lshl_add_u32 v137, s6, 6, v134
	s_nop 0
	v_readfirstlane_b32 s6, v137
	s_bfe_u32 s10, s6, 0x20006
	s_ashr_i32 s6, s6, 2
	s_andn2_b32 s6, s6, 63
	s_add_i32 s6, s6, s5
	v_bfe_u32 v142, v137, 4, 2
	v_and_or_b32 v136, v137, 15, s6
	s_lshl_b32 s5, s4, 8
	s_lshl_b32 s6, s10, 5
	v_lshlrev_b32_e32 v137, 2, v137
	s_or_b32 s5, s6, s5
	v_bitop3_b32 v158, v137, 64, v143 bitop3:0x6c
	v_bitop3_b32 v159, v137, s84, v143 bitop3:0x6c
	v_ashrrev_i32_e32 v137, 31, v136
	v_lshl_or_b32 v134, v142, 3, s5
	v_cmp_eq_u32_e32 vcc, 0, v142
	v_lshlrev_b64 v[142:143], 12, v[136:137]
	v_ashrrev_i32_e32 v135, 31, v134
	v_lshl_add_u64 v[142:143], s[44:45], 0, v[142:143]
	v_lshl_add_u64 v[154:155], v[134:135], 2, v[142:143]
	v_mov_b32_e32 v162, v154
	v_mov_b32_e32 v163, v155
	global_load_dwordx4 v[142:145], v[154:155], off offset:16
	global_load_dwordx4 v[146:149], v[154:155], off
	global_load_dwordx4 v[150:153], v[154:155], off offset:528
	s_nop 0
	global_load_dwordx4 v[154:157], v[154:155], off offset:512
	s_mov_b64 s[100:101], 0x10000
	v_lshl_add_u64 v[164:165], v[162:163], 0, s[100:101]
	global_load_dwordx4 v[168:171], v[164:165], off
	global_load_dwordx4 v[172:175], v[164:165], off offset:16
	global_load_dwordx4 v[176:179], v[164:165], off offset:512
	global_load_dwordx4 v[180:183], v[164:165], off offset:528
	s_mov_b64 s[100:101], 0x20000
	v_lshl_add_u64 v[164:165], v[162:163], 0, s[100:101]
	global_load_dwordx4 v[184:187], v[164:165], off
	global_load_dwordx4 v[188:191], v[164:165], off offset:16
	global_load_dwordx4 v[192:195], v[164:165], off offset:512
	global_load_dwordx4 v[208:211], v[164:165], off offset:528
	s_mov_b64 s[100:101], 0x30000
	v_lshl_add_u64 v[164:165], v[162:163], 0, s[100:101]
	global_load_dwordx4 v[212:215], v[164:165], off
	global_load_dwordx4 v[216:219], v[164:165], off offset:16
	global_load_dwordx4 v[220:223], v[164:165], off offset:512
	global_load_dwordx4 v[224:227], v[164:165], off offset:528
	s_mov_b64 s[100:101], 0x80000
	v_lshl_add_u64 v[164:165], v[162:163], 0, s[100:101]
	global_load_dwordx4 v[228:231], v[164:165], off
	global_load_dwordx4 v[232:235], v[164:165], off offset:16
	global_load_dwordx4 v[236:239], v[164:165], off offset:512
	global_load_dwordx4 v[240:243], v[164:165], off offset:528
	v_lshlrev_b64 v[160:161], 11, v[136:137]
	s_lshl_b32 s6, s4, 2
	s_ashr_i32 s7, s6, 31
	s_waitcnt vmcnt(16)
	v_pk_add_f32 v[124:125], v[124:125], v[142:143]
	v_pk_add_f32 v[122:123], v[122:123], v[148:149]
	v_pk_add_f32 v[120:121], v[120:121], v[146:147]
	v_pk_add_f32 v[126:127], v[126:127], v[144:145]
	v_cvt_pk_bf16_f32 v120, v120, v121
	v_cvt_pk_bf16_f32 v121, v122, v123
	v_cvt_pk_bf16_f32 v122, v124, v125
	v_lshl_add_u64 v[124:125], s[68:69], 0, v[160:161]
	v_lshl_add_u64 v[124:125], v[134:135], 1, v[124:125]
	v_cvt_pk_bf16_f32 v123, v126, v127
	global_store_dwordx4 v[124:125], v[120:123], off
	v_lshlrev_b32_e32 v126, 16, v120
	v_pk_add_f32 v[116:117], v[116:117], v[154:155]
	v_and_b32_e32 v120, 0xffff0000, v120
	v_mul_f32_e32 v120, v120, v120
	v_fmac_f32_e32 v120, v126, v126
	v_lshlrev_b32_e32 v126, 16, v121
	v_and_b32_e32 v121, 0xffff0000, v121
	v_mul_f32_e32 v121, v121, v121
	v_fmac_f32_e32 v121, v126, v126
	v_add_f32_e32 v120, v120, v121
	v_lshlrev_b32_e32 v121, 16, v122
	v_and_b32_e32 v122, 0xffff0000, v122
	v_mul_f32_e32 v122, v122, v122
	v_fmac_f32_e32 v122, v121, v121
	v_add_f32_e32 v120, v120, v122
	v_and_b32_e32 v122, 0xffff0000, v123
	v_lshlrev_b32_e32 v121, 16, v123
	v_mul_f32_e32 v122, v122, v122
	v_fmac_f32_e32 v122, v121, v121
	v_add_f32_e32 v122, v120, v122
	v_pk_add_f32 v[120:121], v[114:115], v[152:153]
	v_pk_add_f32 v[114:115], v[112:113], v[150:151]
	v_cvt_pk_bf16_f32 v112, v116, v117
	v_pk_add_f32 v[118:119], v[118:119], v[156:157]
	v_lshlrev_b32_e32 v116, 16, v112
	v_cvt_pk_bf16_f32 v113, v118, v119
	v_cvt_pk_bf16_f32 v114, v114, v115
	v_cvt_pk_bf16_f32 v115, v120, v121
	global_store_dwordx4 v[124:125], v[112:115], off offset:256
	s_nop 1
	v_and_b32_e32 v112, 0xffff0000, v112
	v_mul_f32_e32 v112, v112, v112
	v_fmac_f32_e32 v112, v116, v116
	v_lshlrev_b32_e32 v116, 16, v113
	v_and_b32_e32 v113, 0xffff0000, v113
	v_mul_f32_e32 v113, v113, v113
	v_add_f32_e32 v112, v122, v112
	v_fmac_f32_e32 v113, v116, v116
	v_add_f32_e32 v112, v112, v113
	v_lshlrev_b32_e32 v113, 16, v114
	v_and_b32_e32 v114, 0xffff0000, v114
	v_mul_f32_e32 v114, v114, v114
	v_fmac_f32_e32 v114, v113, v113
	v_add_f32_e32 v112, v112, v114
	v_and_b32_e32 v114, 0xffff0000, v115
	v_lshlrev_b32_e32 v113, 16, v115
	v_mul_f32_e32 v114, v114, v114
	v_fmac_f32_e32 v114, v113, v113
	v_add_f32_e32 v112, v112, v114
	v_mov_b32_e32 v113, v112
	s_nop 1
	v_permlane16_swap_b32_e32 v113, v112
	s_waitcnt lgkmcnt(0)
	v_add_f32_e32 v112, v112, v113
	v_mov_b32_e32 v113, v112
	s_nop 1
	v_permlane32_swap_b32_e32 v113, v112
	s_and_saveexec_b64 s[8:9], vcc
	s_cbranch_execz .LBB0_461
	v_lshlrev_b64 v[114:115], 6, v[136:137]
	v_lshl_add_u64 v[114:115], s[66:67], 0, v[114:115]
	v_lshl_add_u64 v[114:115], s[6:7], 2, v[114:115]
	s_lshl_b32 s38, s10, 2
	v_lshl_add_u64 v[114:115], v[114:115], 0, s[38:39]
	s_waitcnt lgkmcnt(0)
	v_add_f32_e32 v112, v112, v113
	global_store_dword v[114:115], v112, off
.LBB0_461:
	s_or_b64 exec, exec, s[8:9]
	v_or_b32_e32 v112, 16, v136
	s_waitcnt lgkmcnt(0)
	v_ashrrev_i32_e32 v113, 31, v112
	v_lshlrev_b64 v[114:115], 12, v[112:113]
	v_lshl_add_u64 v[114:115], s[44:45], 0, v[114:115]
	v_lshl_add_u64 v[126:127], v[134:135], 2, v[114:115]
	v_lshlrev_b64 v[126:127], 11, v[112:113]
	v_lshl_add_u64 v[126:127], s[68:69], 0, v[126:127]
	v_lshl_add_u64 v[126:127], v[134:135], 1, v[126:127]
	s_waitcnt vmcnt(15)
	v_mov_b32_e32 v114, v168
	v_mov_b32_e32 v115, v169
	v_mov_b32_e32 v116, v170
	v_mov_b32_e32 v117, v171
	v_mov_b32_e32 v118, v172
	v_mov_b32_e32 v119, v173
	v_mov_b32_e32 v120, v174
	v_mov_b32_e32 v121, v175
	v_mov_b32_e32 v122, v176
	v_mov_b32_e32 v123, v177
	v_mov_b32_e32 v124, v178
	v_mov_b32_e32 v125, v179
	v_mov_b32_e32 v142, v180
	v_mov_b32_e32 v143, v181
	v_mov_b32_e32 v144, v182
	v_mov_b32_e32 v145, v183
	s_mov_b64 s[100:101], 0x90000
	v_lshl_add_u64 v[164:165], v[162:163], 0, s[100:101]
	global_load_dwordx4 v[168:171], v[164:165], off
	global_load_dwordx4 v[172:175], v[164:165], off offset:16
	global_load_dwordx4 v[176:179], v[164:165], off offset:512
	global_load_dwordx4 v[180:183], v[164:165], off offset:528
	v_pk_add_f32 v[106:107], v[106:107], v[116:117]
	v_pk_add_f32 v[104:105], v[104:105], v[114:115]
	s_nop 0
	v_pk_add_f32 v[110:111], v[110:111], v[120:121]
	s_nop 0
	v_pk_add_f32 v[116:117], v[96:97], v[142:143]
	v_cvt_pk_bf16_f32 v96, v104, v105
	v_cvt_pk_bf16_f32 v97, v106, v107
	v_pk_add_f32 v[108:109], v[108:109], v[118:119]
	v_pk_add_f32 v[114:115], v[98:99], v[144:145]
	v_cvt_pk_bf16_f32 v98, v108, v109
	v_cvt_pk_bf16_f32 v99, v110, v111
	global_store_dwordx4 v[126:127], v[96:99], off
	v_lshlrev_b32_e32 v104, 16, v96
	v_lshlrev_b32_e32 v105, 16, v97
	v_and_b32_e32 v96, 0xffff0000, v96
	v_and_b32_e32 v97, 0xffff0000, v97
	v_pk_add_f32 v[102:103], v[102:103], v[124:125]
	v_and_b32_e32 v107, 0xffff0000, v98
	v_mul_f32_e32 v96, v96, v96
	v_mul_f32_e32 v97, v97, v97
	v_pk_add_f32 v[100:101], v[100:101], v[122:123]
	v_lshlrev_b32_e32 v106, 16, v98
	v_lshlrev_b32_e32 v108, 16, v99
	v_and_b32_e32 v109, 0xffff0000, v99
	v_cvt_pk_bf16_f32 v98, v100, v101
	v_cvt_pk_bf16_f32 v99, v102, v103
	v_mul_f32_e32 v102, v107, v107
	v_fmac_f32_e32 v96, v104, v104
	v_fmac_f32_e32 v97, v105, v105
	v_mul_f32_e32 v103, v109, v109
	v_and_b32_e32 v109, 0xffff0000, v98
	v_fmac_f32_e32 v102, v106, v106
	v_add_f32_e32 v96, v96, v97
	v_lshlrev_b32_e32 v107, 16, v98
	v_and_b32_e32 v111, 0xffff0000, v99
	v_fmac_f32_e32 v103, v108, v108
	v_mul_f32_e32 v104, v109, v109
	v_add_f32_e32 v96, v96, v102
	v_cvt_pk_bf16_f32 v100, v116, v117
	v_cvt_pk_bf16_f32 v101, v114, v115
	v_lshlrev_b32_e32 v110, 16, v99
	v_and_b32_e32 v115, 0xffff0000, v100
	v_mul_f32_e32 v105, v111, v111
	v_fmac_f32_e32 v104, v107, v107
	v_add_f32_e32 v96, v96, v103
	v_lshlrev_b32_e32 v114, 16, v100
	v_and_b32_e32 v117, 0xffff0000, v101
	v_mul_f32_e32 v106, v115, v115
	v_fmac_f32_e32 v105, v110, v110
	v_add_f32_e32 v96, v96, v104
	v_lshlrev_b32_e32 v116, 16, v101
	v_mul_f32_e32 v108, v117, v117
	v_fmac_f32_e32 v106, v114, v114
	v_add_f32_e32 v96, v96, v105
	v_add_f32_e32 v96, v96, v106
	v_fmac_f32_e32 v108, v116, v116
	v_add_f32_e32 v96, v96, v108
	v_mov_b32_e32 v97, v96
	s_nop 1
	v_permlane16_swap_b32_e32 v97, v96
	global_store_dwordx4 v[126:127], v[98:101], off offset:256
	s_waitcnt lgkmcnt(0)
	v_add_f32_e32 v96, v96, v97
	v_mov_b32_e32 v97, v96
	s_nop 1
	v_permlane32_swap_b32_e32 v97, v96
	s_mov_b64 s[8:9], exec
	s_and_b64 s[4:5], s[8:9], vcc
	v_mov_b32_e32 v198, v246
	v_mov_b32_e32 v199, v247
	v_mov_b32_e32 v205, v249
	v_mov_b32_e32 v196, v251
	v_mov_b32_e32 v251, 0x260
	s_mov_b64 exec, s[4:5]
	s_cbranch_execz .LBB0_463
	v_lshlrev_b64 v[98:99], 6, v[112:113]
	v_lshl_add_u64 v[98:99], s[66:67], 0, v[98:99]
	v_lshl_add_u64 v[98:99], s[6:7], 2, v[98:99]
	s_lshl_b32 s38, s10, 2
	v_lshl_add_u64 v[98:99], v[98:99], 0, s[38:39]
	s_waitcnt lgkmcnt(0)
	v_add_f32_e32 v96, v96, v97
	global_store_dword v[98:99], v96, off
.LBB0_463:
	s_or_b64 exec, exec, s[8:9]
	v_or_b32_e32 v96, 32, v136
	s_waitcnt lgkmcnt(0)
	v_ashrrev_i32_e32 v97, 31, v96
	v_lshlrev_b64 v[98:99], 12, v[96:97]
	v_lshl_add_u64 v[98:99], s[44:45], 0, v[98:99]
	v_lshl_add_u64 v[110:111], v[134:135], 2, v[98:99]
	s_nop 0
	v_lshlrev_b64 v[114:115], 11, v[96:97]
	v_lshl_add_u64 v[114:115], s[68:69], 0, v[114:115]
	v_lshl_add_u64 v[114:115], v[134:135], 1, v[114:115]
	s_waitcnt vmcnt(18)
	v_mov_b32_e32 v98, v184
	v_mov_b32_e32 v99, v185
	v_mov_b32_e32 v100, v186
	v_mov_b32_e32 v101, v187
	v_mov_b32_e32 v102, v188
	v_mov_b32_e32 v103, v189
	v_mov_b32_e32 v104, v190
	v_mov_b32_e32 v105, v191
	v_mov_b32_e32 v106, v192
	v_mov_b32_e32 v107, v193
	v_mov_b32_e32 v108, v194
	v_mov_b32_e32 v109, v195
	v_mov_b32_e32 v110, v208
	v_mov_b32_e32 v111, v209
	v_mov_b32_e32 v112, v210
	v_mov_b32_e32 v113, v211
	s_mov_b64 s[100:101], 0xa0000
	v_lshl_add_u64 v[164:165], v[162:163], 0, s[100:101]
	global_load_dwordx4 v[184:187], v[164:165], off
	global_load_dwordx4 v[188:191], v[164:165], off offset:16
	global_load_dwordx4 v[192:195], v[164:165], off offset:512
	global_load_dwordx4 v[208:211], v[164:165], off offset:528
	v_pk_add_f32 v[90:91], v[90:91], v[100:101]
	v_pk_add_f32 v[88:89], v[88:89], v[98:99]
	s_nop 0
	v_pk_add_f32 v[94:95], v[94:95], v[104:105]
	s_nop 0
	v_pk_add_f32 v[100:101], v[80:81], v[110:111]
	v_cvt_pk_bf16_f32 v80, v88, v89
	v_cvt_pk_bf16_f32 v81, v90, v91
	v_pk_add_f32 v[92:93], v[92:93], v[102:103]
	v_pk_add_f32 v[98:99], v[82:83], v[112:113]
	v_cvt_pk_bf16_f32 v82, v92, v93
	v_cvt_pk_bf16_f32 v83, v94, v95
	global_store_dwordx4 v[114:115], v[80:83], off
	v_lshlrev_b32_e32 v88, 16, v80
	v_lshlrev_b32_e32 v89, 16, v81
	v_and_b32_e32 v80, 0xffff0000, v80
	v_and_b32_e32 v81, 0xffff0000, v81
	v_pk_add_f32 v[86:87], v[86:87], v[108:109]
	v_and_b32_e32 v91, 0xffff0000, v82
	v_mul_f32_e32 v80, v80, v80
	v_mul_f32_e32 v81, v81, v81
	v_pk_add_f32 v[84:85], v[84:85], v[106:107]
	v_lshlrev_b32_e32 v90, 16, v82
	v_lshlrev_b32_e32 v92, 16, v83
	v_and_b32_e32 v93, 0xffff0000, v83
	v_cvt_pk_bf16_f32 v82, v84, v85
	v_cvt_pk_bf16_f32 v83, v86, v87
	v_mul_f32_e32 v86, v91, v91
	v_fmac_f32_e32 v80, v88, v88
	v_fmac_f32_e32 v81, v89, v89
	v_mul_f32_e32 v87, v93, v93
	v_and_b32_e32 v93, 0xffff0000, v82
	v_fmac_f32_e32 v86, v90, v90
	v_add_f32_e32 v80, v80, v81
	v_lshlrev_b32_e32 v91, 16, v82
	v_and_b32_e32 v95, 0xffff0000, v83
	v_fmac_f32_e32 v87, v92, v92
	v_mul_f32_e32 v88, v93, v93
	v_add_f32_e32 v80, v80, v86
	v_cvt_pk_bf16_f32 v84, v100, v101
	v_cvt_pk_bf16_f32 v85, v98, v99
	v_lshlrev_b32_e32 v94, 16, v83
	v_and_b32_e32 v99, 0xffff0000, v84
	v_mul_f32_e32 v89, v95, v95
	v_fmac_f32_e32 v88, v91, v91
	v_add_f32_e32 v80, v80, v87
	v_lshlrev_b32_e32 v98, 16, v84
	v_and_b32_e32 v101, 0xffff0000, v85
	v_mul_f32_e32 v90, v99, v99
	v_fmac_f32_e32 v89, v94, v94
	v_add_f32_e32 v80, v80, v88
	v_lshlrev_b32_e32 v100, 16, v85
	v_mul_f32_e32 v92, v101, v101
	v_fmac_f32_e32 v90, v98, v98
	v_add_f32_e32 v80, v80, v89
	v_add_f32_e32 v80, v80, v90
	v_fmac_f32_e32 v92, v100, v100
	v_add_f32_e32 v80, v80, v92
	v_mov_b32_e32 v81, v80
	s_nop 1
	v_permlane16_swap_b32_e32 v81, v80
	global_store_dwordx4 v[114:115], v[82:85], off offset:256
	s_waitcnt lgkmcnt(0)
	v_add_f32_e32 v80, v80, v81
	v_mov_b32_e32 v81, v80
	s_nop 1
	v_permlane32_swap_b32_e32 v81, v80
	s_and_saveexec_b64 s[8:9], vcc
	s_cbranch_execz .LBB0_465
	v_lshlrev_b64 v[82:83], 6, v[96:97]
	v_lshl_add_u64 v[82:83], s[66:67], 0, v[82:83]
	v_lshl_add_u64 v[82:83], s[6:7], 2, v[82:83]
	s_lshl_b32 s38, s10, 2
	v_lshl_add_u64 v[82:83], v[82:83], 0, s[38:39]
	s_waitcnt lgkmcnt(0)
	v_add_f32_e32 v80, v80, v81
	global_store_dword v[82:83], v80, off
.LBB0_465:
	s_or_b64 exec, exec, s[8:9]
	v_or_b32_e32 v80, 48, v136
	s_waitcnt lgkmcnt(0)
	v_ashrrev_i32_e32 v81, 31, v80
	v_lshlrev_b64 v[82:83], 12, v[80:81]
	v_lshl_add_u64 v[82:83], s[44:45], 0, v[82:83]
	v_lshl_add_u64 v[94:95], v[134:135], 2, v[82:83]
	s_nop 0
	v_lshlrev_b64 v[98:99], 11, v[80:81]
	v_lshl_add_u64 v[98:99], s[68:69], 0, v[98:99]
	v_lshl_add_u64 v[98:99], v[134:135], 1, v[98:99]
	s_waitcnt vmcnt(21)
	v_mov_b32_e32 v82, v212
	v_mov_b32_e32 v83, v213
	v_mov_b32_e32 v84, v214
	v_mov_b32_e32 v85, v215
	v_mov_b32_e32 v86, v216
	v_mov_b32_e32 v87, v217
	v_mov_b32_e32 v88, v218
	v_mov_b32_e32 v89, v219
	v_mov_b32_e32 v90, v220
	v_mov_b32_e32 v91, v221
	v_mov_b32_e32 v92, v222
	v_mov_b32_e32 v93, v223
	v_mov_b32_e32 v94, v224
	v_mov_b32_e32 v95, v225
	v_mov_b32_e32 v96, v226
	v_mov_b32_e32 v97, v227
	s_mov_b64 s[100:101], 0xb0000
	v_lshl_add_u64 v[164:165], v[162:163], 0, s[100:101]
	global_load_dwordx4 v[212:215], v[164:165], off
	global_load_dwordx4 v[216:219], v[164:165], off offset:16
	global_load_dwordx4 v[220:223], v[164:165], off offset:512
	global_load_dwordx4 v[224:227], v[164:165], off offset:528
	v_pk_add_f32 v[74:75], v[74:75], v[84:85]
	v_pk_add_f32 v[72:73], v[72:73], v[82:83]
	s_nop 0
	v_pk_add_f32 v[78:79], v[78:79], v[88:89]
	s_nop 0
	v_pk_add_f32 v[84:85], v[64:65], v[94:95]
	v_cvt_pk_bf16_f32 v64, v72, v73
	v_cvt_pk_bf16_f32 v65, v74, v75
	v_pk_add_f32 v[76:77], v[76:77], v[86:87]
	v_pk_add_f32 v[82:83], v[66:67], v[96:97]
	v_cvt_pk_bf16_f32 v66, v76, v77
	v_cvt_pk_bf16_f32 v67, v78, v79
	global_store_dwordx4 v[98:99], v[64:67], off
	v_lshlrev_b32_e32 v72, 16, v64
	v_lshlrev_b32_e32 v73, 16, v65
	v_and_b32_e32 v64, 0xffff0000, v64
	v_and_b32_e32 v65, 0xffff0000, v65
	v_pk_add_f32 v[70:71], v[70:71], v[92:93]
	v_and_b32_e32 v75, 0xffff0000, v66
	v_mul_f32_e32 v64, v64, v64
	v_mul_f32_e32 v65, v65, v65
	v_pk_add_f32 v[68:69], v[68:69], v[90:91]
	v_lshlrev_b32_e32 v74, 16, v66
	v_lshlrev_b32_e32 v76, 16, v67
	v_and_b32_e32 v77, 0xffff0000, v67
	v_cvt_pk_bf16_f32 v66, v68, v69
	v_cvt_pk_bf16_f32 v67, v70, v71
	v_mul_f32_e32 v70, v75, v75
	v_fmac_f32_e32 v64, v72, v72
	v_fmac_f32_e32 v65, v73, v73
	v_mul_f32_e32 v71, v77, v77
	v_and_b32_e32 v77, 0xffff0000, v66
	v_fmac_f32_e32 v70, v74, v74
	v_add_f32_e32 v64, v64, v65
	v_lshlrev_b32_e32 v75, 16, v66
	v_and_b32_e32 v79, 0xffff0000, v67
	v_fmac_f32_e32 v71, v76, v76
	v_mul_f32_e32 v72, v77, v77
	v_add_f32_e32 v64, v64, v70
	v_cvt_pk_bf16_f32 v68, v84, v85
	v_cvt_pk_bf16_f32 v69, v82, v83
	v_lshlrev_b32_e32 v78, 16, v67
	v_and_b32_e32 v83, 0xffff0000, v68
	v_mul_f32_e32 v73, v79, v79
	v_fmac_f32_e32 v72, v75, v75
	v_add_f32_e32 v64, v64, v71
	v_lshlrev_b32_e32 v82, 16, v68
	v_and_b32_e32 v85, 0xffff0000, v69
	v_mul_f32_e32 v74, v83, v83
	v_fmac_f32_e32 v73, v78, v78
	v_add_f32_e32 v64, v64, v72
	v_lshlrev_b32_e32 v84, 16, v69
	v_mul_f32_e32 v76, v85, v85
	v_fmac_f32_e32 v74, v82, v82
	v_add_f32_e32 v64, v64, v73
	v_add_f32_e32 v64, v64, v74
	v_fmac_f32_e32 v76, v84, v84
	v_add_f32_e32 v64, v64, v76
	v_mov_b32_e32 v65, v64
	s_nop 1
	v_permlane16_swap_b32_e32 v65, v64
	global_store_dwordx4 v[98:99], v[66:69], off offset:256
	s_waitcnt lgkmcnt(0)
	v_add_f32_e32 v64, v64, v65
	v_mov_b32_e32 v65, v64
	s_nop 1
	v_permlane32_swap_b32_e32 v65, v64
	s_and_saveexec_b64 s[8:9], vcc
	s_cbranch_execz .LBB0_467
	v_lshlrev_b64 v[66:67], 6, v[80:81]
	v_lshl_add_u64 v[66:67], s[66:67], 0, v[66:67]
	v_lshl_add_u64 v[66:67], s[6:7], 2, v[66:67]
	s_lshl_b32 s38, s10, 2
	v_lshl_add_u64 v[66:67], v[66:67], 0, s[38:39]
	s_waitcnt lgkmcnt(0)
	v_add_f32_e32 v64, v64, v65
	global_store_dword v[66:67], v64, off
.LBB0_467:
	s_or_b64 exec, exec, s[8:9]
	v_add_u32_e32 v64, 0x80, v136
	s_waitcnt lgkmcnt(0)
	v_ashrrev_i32_e32 v65, 31, v64
	v_lshlrev_b64 v[66:67], 12, v[64:65]
	v_lshl_add_u64 v[66:67], s[44:45], 0, v[66:67]
	v_lshl_add_u64 v[78:79], v[134:135], 2, v[66:67]
	s_nop 0
	v_lshlrev_b64 v[82:83], 11, v[64:65]
	v_lshl_add_u64 v[82:83], s[68:69], 0, v[82:83]
	v_lshl_add_u64 v[82:83], v[134:135], 1, v[82:83]
	s_waitcnt vmcnt(24)
	v_mov_b32_e32 v66, v228
	v_mov_b32_e32 v67, v229
	v_mov_b32_e32 v68, v230
	v_mov_b32_e32 v69, v231
	v_mov_b32_e32 v70, v232
	v_mov_b32_e32 v71, v233
	v_mov_b32_e32 v72, v234
	v_mov_b32_e32 v73, v235
	v_mov_b32_e32 v74, v236
	v_mov_b32_e32 v75, v237
	v_mov_b32_e32 v76, v238
	v_mov_b32_e32 v77, v239
	v_mov_b32_e32 v78, v240
	v_mov_b32_e32 v79, v241
	v_mov_b32_e32 v80, v242
	v_mov_b32_e32 v81, v243
	v_pk_add_f32 v[58:59], v[58:59], v[68:69]
	v_pk_add_f32 v[56:57], v[56:57], v[66:67]
	s_nop 0
	v_pk_add_f32 v[62:63], v[62:63], v[72:73]
	s_nop 0
	v_pk_add_f32 v[68:69], v[48:49], v[78:79]
	v_cvt_pk_bf16_f32 v48, v56, v57
	v_cvt_pk_bf16_f32 v49, v58, v59
	v_pk_add_f32 v[60:61], v[60:61], v[70:71]
	v_pk_add_f32 v[66:67], v[50:51], v[80:81]
	v_cvt_pk_bf16_f32 v50, v60, v61
	v_cvt_pk_bf16_f32 v51, v62, v63
	global_store_dwordx4 v[82:83], v[48:51], off
	v_lshlrev_b32_e32 v56, 16, v48
	v_lshlrev_b32_e32 v57, 16, v49
	v_and_b32_e32 v48, 0xffff0000, v48
	v_and_b32_e32 v49, 0xffff0000, v49
	v_pk_add_f32 v[54:55], v[54:55], v[76:77]
	v_and_b32_e32 v59, 0xffff0000, v50
	v_mul_f32_e32 v48, v48, v48
	v_mul_f32_e32 v49, v49, v49
	v_pk_add_f32 v[52:53], v[52:53], v[74:75]
	v_lshlrev_b32_e32 v58, 16, v50
	v_lshlrev_b32_e32 v60, 16, v51
	v_and_b32_e32 v61, 0xffff0000, v51
	v_cvt_pk_bf16_f32 v50, v52, v53
	v_cvt_pk_bf16_f32 v51, v54, v55
	v_mul_f32_e32 v54, v59, v59
	v_fmac_f32_e32 v48, v56, v56
	v_fmac_f32_e32 v49, v57, v57
	v_mul_f32_e32 v55, v61, v61
	v_and_b32_e32 v61, 0xffff0000, v50
	v_fmac_f32_e32 v54, v58, v58
	v_add_f32_e32 v48, v48, v49
	v_lshlrev_b32_e32 v59, 16, v50
	v_and_b32_e32 v63, 0xffff0000, v51
	v_fmac_f32_e32 v55, v60, v60
	v_mul_f32_e32 v56, v61, v61
	v_add_f32_e32 v48, v48, v54
	v_cvt_pk_bf16_f32 v52, v68, v69
	v_cvt_pk_bf16_f32 v53, v66, v67
	v_lshlrev_b32_e32 v62, 16, v51
	v_and_b32_e32 v67, 0xffff0000, v52
	v_mul_f32_e32 v57, v63, v63
	v_fmac_f32_e32 v56, v59, v59
	v_add_f32_e32 v48, v48, v55
	v_lshlrev_b32_e32 v66, 16, v52
	v_and_b32_e32 v69, 0xffff0000, v53
	v_mul_f32_e32 v58, v67, v67
	v_fmac_f32_e32 v57, v62, v62
	v_add_f32_e32 v48, v48, v56
	v_lshlrev_b32_e32 v68, 16, v53
	v_mul_f32_e32 v60, v69, v69
	v_fmac_f32_e32 v58, v66, v66
	v_add_f32_e32 v48, v48, v57
	v_add_f32_e32 v48, v48, v58
	v_fmac_f32_e32 v60, v68, v68
	v_add_f32_e32 v48, v48, v60
	v_mov_b32_e32 v49, v48
	s_nop 1
	v_permlane16_swap_b32_e32 v49, v48
	global_store_dwordx4 v[82:83], v[50:53], off offset:256
	s_waitcnt lgkmcnt(0)
	v_add_f32_e32 v48, v48, v49
	v_mov_b32_e32 v49, v48
	s_nop 1
	v_permlane32_swap_b32_e32 v49, v48
	s_and_saveexec_b64 s[8:9], vcc
	s_cbranch_execz .LBB0_469
	v_lshlrev_b64 v[50:51], 6, v[64:65]
	v_lshl_add_u64 v[50:51], s[66:67], 0, v[50:51]
	v_lshl_add_u64 v[50:51], s[6:7], 2, v[50:51]
	s_lshl_b32 s38, s10, 2
	v_lshl_add_u64 v[50:51], v[50:51], 0, s[38:39]
	s_waitcnt lgkmcnt(0)
	v_add_f32_e32 v48, v48, v49
	global_store_dword v[50:51], v48, off
.LBB0_469:
	s_or_b64 exec, exec, s[8:9]
	v_add_u32_e32 v48, 0x90, v136
	s_waitcnt lgkmcnt(0)
	v_ashrrev_i32_e32 v49, 31, v48
	v_lshlrev_b64 v[50:51], 12, v[48:49]
	v_lshl_add_u64 v[50:51], s[44:45], 0, v[50:51]
	v_lshl_add_u64 v[62:63], v[134:135], 2, v[50:51]
	s_nop 0
	v_lshlrev_b64 v[66:67], 11, v[48:49]
	v_lshl_add_u64 v[66:67], s[68:69], 0, v[66:67]
	v_lshl_add_u64 v[66:67], v[134:135], 1, v[66:67]
	s_waitcnt vmcnt(20)
	v_mov_b32_e32 v50, v168
	v_mov_b32_e32 v51, v169
	v_mov_b32_e32 v52, v170
	v_mov_b32_e32 v53, v171
	v_mov_b32_e32 v54, v172
	v_mov_b32_e32 v55, v173
	v_mov_b32_e32 v56, v174
	v_mov_b32_e32 v57, v175
	v_mov_b32_e32 v58, v176
	v_mov_b32_e32 v59, v177
	v_mov_b32_e32 v60, v178
	v_mov_b32_e32 v61, v179
	v_mov_b32_e32 v62, v180
	v_mov_b32_e32 v63, v181
	v_mov_b32_e32 v64, v182
	v_mov_b32_e32 v65, v183
	v_pk_add_f32 v[42:43], v[42:43], v[52:53]
	v_pk_add_f32 v[40:41], v[40:41], v[50:51]
	s_nop 0
	v_pk_add_f32 v[46:47], v[46:47], v[56:57]
	s_nop 0
	v_pk_add_f32 v[52:53], v[32:33], v[62:63]
	v_cvt_pk_bf16_f32 v32, v40, v41
	v_cvt_pk_bf16_f32 v33, v42, v43
	v_pk_add_f32 v[44:45], v[44:45], v[54:55]
	v_pk_add_f32 v[50:51], v[34:35], v[64:65]
	v_cvt_pk_bf16_f32 v34, v44, v45
	v_cvt_pk_bf16_f32 v35, v46, v47
	global_store_dwordx4 v[66:67], v[32:35], off
	v_lshlrev_b32_e32 v40, 16, v32
	v_lshlrev_b32_e32 v41, 16, v33
	v_and_b32_e32 v32, 0xffff0000, v32
	v_and_b32_e32 v33, 0xffff0000, v33
	v_pk_add_f32 v[38:39], v[38:39], v[60:61]
	v_and_b32_e32 v43, 0xffff0000, v34
	v_mul_f32_e32 v32, v32, v32
	v_mul_f32_e32 v33, v33, v33
	v_pk_add_f32 v[36:37], v[36:37], v[58:59]
	v_lshlrev_b32_e32 v42, 16, v34
	v_lshlrev_b32_e32 v44, 16, v35
	v_and_b32_e32 v45, 0xffff0000, v35
	v_cvt_pk_bf16_f32 v34, v36, v37
	v_cvt_pk_bf16_f32 v35, v38, v39
	v_mul_f32_e32 v38, v43, v43
	v_fmac_f32_e32 v32, v40, v40
	v_fmac_f32_e32 v33, v41, v41
	v_mul_f32_e32 v39, v45, v45
	v_and_b32_e32 v45, 0xffff0000, v34
	v_fmac_f32_e32 v38, v42, v42
	v_add_f32_e32 v32, v32, v33
	v_lshlrev_b32_e32 v43, 16, v34
	v_and_b32_e32 v47, 0xffff0000, v35
	v_fmac_f32_e32 v39, v44, v44
	v_mul_f32_e32 v40, v45, v45
	v_add_f32_e32 v32, v32, v38
	v_cvt_pk_bf16_f32 v36, v52, v53
	v_cvt_pk_bf16_f32 v37, v50, v51
	v_lshlrev_b32_e32 v46, 16, v35
	v_and_b32_e32 v51, 0xffff0000, v36
	v_mul_f32_e32 v41, v47, v47
	v_fmac_f32_e32 v40, v43, v43
	v_add_f32_e32 v32, v32, v39
	v_lshlrev_b32_e32 v50, 16, v36
	v_and_b32_e32 v53, 0xffff0000, v37
	v_mul_f32_e32 v42, v51, v51
	v_fmac_f32_e32 v41, v46, v46
	v_add_f32_e32 v32, v32, v40
	v_lshlrev_b32_e32 v52, 16, v37
	v_mul_f32_e32 v44, v53, v53
	v_fmac_f32_e32 v42, v50, v50
	v_add_f32_e32 v32, v32, v41
	v_add_f32_e32 v32, v32, v42
	v_fmac_f32_e32 v44, v52, v52
	v_add_f32_e32 v32, v32, v44
	v_mov_b32_e32 v33, v32
	s_nop 1
	v_permlane16_swap_b32_e32 v33, v32
	global_store_dwordx4 v[66:67], v[34:37], off offset:256
	s_waitcnt lgkmcnt(0)
	v_add_f32_e32 v32, v32, v33
	v_mov_b32_e32 v33, v32
	s_nop 1
	v_permlane32_swap_b32_e32 v33, v32
	s_and_saveexec_b64 s[8:9], vcc
	s_cbranch_execz .LBB0_471
	v_lshlrev_b64 v[34:35], 6, v[48:49]
	v_lshl_add_u64 v[34:35], s[66:67], 0, v[34:35]
	v_lshl_add_u64 v[34:35], s[6:7], 2, v[34:35]
	s_lshl_b32 s38, s10, 2
	v_lshl_add_u64 v[34:35], v[34:35], 0, s[38:39]
	s_waitcnt lgkmcnt(0)
	v_add_f32_e32 v32, v32, v33
	global_store_dword v[34:35], v32, off
.LBB0_471:
	s_or_b64 exec, exec, s[8:9]
	v_add_u32_e32 v32, 0xa0, v136
	s_waitcnt lgkmcnt(0)
	v_ashrrev_i32_e32 v33, 31, v32
	v_lshlrev_b64 v[34:35], 12, v[32:33]
	v_lshl_add_u64 v[34:35], s[44:45], 0, v[34:35]
	v_lshl_add_u64 v[46:47], v[134:135], 2, v[34:35]
	s_nop 0
	v_lshlrev_b64 v[50:51], 11, v[32:33]
	v_lshl_add_u64 v[50:51], s[68:69], 0, v[50:51]
	v_lshl_add_u64 v[50:51], v[134:135], 1, v[50:51]
	s_waitcnt vmcnt(16)
	v_mov_b32_e32 v34, v184
	v_mov_b32_e32 v35, v185
	v_mov_b32_e32 v36, v186
	v_mov_b32_e32 v37, v187
	v_mov_b32_e32 v38, v188
	v_mov_b32_e32 v39, v189
	v_mov_b32_e32 v40, v190
	v_mov_b32_e32 v41, v191
	v_mov_b32_e32 v42, v192
	v_mov_b32_e32 v43, v193
	v_mov_b32_e32 v44, v194
	v_mov_b32_e32 v45, v195
	v_mov_b32_e32 v46, v208
	v_mov_b32_e32 v47, v209
	v_mov_b32_e32 v48, v210
	v_mov_b32_e32 v49, v211
	v_pk_add_f32 v[26:27], v[26:27], v[36:37]
	v_pk_add_f32 v[24:25], v[24:25], v[34:35]
	s_nop 0
	v_pk_add_f32 v[30:31], v[30:31], v[40:41]
	s_nop 0
	v_pk_add_f32 v[36:37], v[16:17], v[46:47]
	v_cvt_pk_bf16_f32 v16, v24, v25
	v_cvt_pk_bf16_f32 v17, v26, v27
	v_pk_add_f32 v[28:29], v[28:29], v[38:39]
	v_pk_add_f32 v[34:35], v[18:19], v[48:49]
	v_cvt_pk_bf16_f32 v18, v28, v29
	v_cvt_pk_bf16_f32 v19, v30, v31
	global_store_dwordx4 v[50:51], v[16:19], off
	v_lshlrev_b32_e32 v24, 16, v16
	v_lshlrev_b32_e32 v25, 16, v17
	v_and_b32_e32 v16, 0xffff0000, v16
	v_and_b32_e32 v17, 0xffff0000, v17
	v_pk_add_f32 v[22:23], v[22:23], v[44:45]
	v_and_b32_e32 v27, 0xffff0000, v18
	v_mul_f32_e32 v16, v16, v16
	v_mul_f32_e32 v17, v17, v17
	v_pk_add_f32 v[20:21], v[20:21], v[42:43]
	v_lshlrev_b32_e32 v26, 16, v18
	v_lshlrev_b32_e32 v28, 16, v19
	v_and_b32_e32 v29, 0xffff0000, v19
	v_cvt_pk_bf16_f32 v18, v20, v21
	v_cvt_pk_bf16_f32 v19, v22, v23
	v_mul_f32_e32 v22, v27, v27
	v_fmac_f32_e32 v16, v24, v24
	v_fmac_f32_e32 v17, v25, v25
	v_mul_f32_e32 v23, v29, v29
	v_and_b32_e32 v29, 0xffff0000, v18
	v_fmac_f32_e32 v22, v26, v26
	v_add_f32_e32 v16, v16, v17
	v_lshlrev_b32_e32 v27, 16, v18
	v_and_b32_e32 v31, 0xffff0000, v19
	v_fmac_f32_e32 v23, v28, v28
	v_mul_f32_e32 v24, v29, v29
	v_add_f32_e32 v16, v16, v22
	v_cvt_pk_bf16_f32 v20, v36, v37
	v_cvt_pk_bf16_f32 v21, v34, v35
	v_lshlrev_b32_e32 v30, 16, v19
	v_and_b32_e32 v35, 0xffff0000, v20
	v_mul_f32_e32 v25, v31, v31
	v_fmac_f32_e32 v24, v27, v27
	v_add_f32_e32 v16, v16, v23
	v_lshlrev_b32_e32 v34, 16, v20
	v_and_b32_e32 v37, 0xffff0000, v21
	v_mul_f32_e32 v26, v35, v35
	v_fmac_f32_e32 v25, v30, v30
	v_add_f32_e32 v16, v16, v24
	v_lshlrev_b32_e32 v36, 16, v21
	v_mul_f32_e32 v28, v37, v37
	v_fmac_f32_e32 v26, v34, v34
	v_add_f32_e32 v16, v16, v25
	v_add_f32_e32 v16, v16, v26
	v_fmac_f32_e32 v28, v36, v36
	v_add_f32_e32 v16, v16, v28
	v_mov_b32_e32 v17, v16
	s_nop 1
	v_permlane16_swap_b32_e32 v17, v16
	global_store_dwordx4 v[50:51], v[18:21], off offset:256
	s_waitcnt lgkmcnt(0)
	v_add_f32_e32 v16, v16, v17
	v_mov_b32_e32 v17, v16
	s_nop 1
	v_permlane32_swap_b32_e32 v17, v16
	s_and_saveexec_b64 s[8:9], vcc
	s_cbranch_execz .LBB0_473
	v_lshlrev_b64 v[18:19], 6, v[32:33]
	v_lshl_add_u64 v[18:19], s[66:67], 0, v[18:19]
	v_lshl_add_u64 v[18:19], s[6:7], 2, v[18:19]
	s_lshl_b32 s38, s10, 2
	v_lshl_add_u64 v[18:19], v[18:19], 0, s[38:39]
	s_waitcnt lgkmcnt(0)
	v_add_f32_e32 v16, v16, v17
	global_store_dword v[18:19], v16, off
.LBB0_473:
	s_or_b64 exec, exec, s[8:9]
	v_add_u32_e32 v16, 0xb0, v136
	s_waitcnt lgkmcnt(0)
	v_ashrrev_i32_e32 v17, 31, v16
	v_lshlrev_b64 v[18:19], 12, v[16:17]
	v_lshl_add_u64 v[18:19], s[44:45], 0, v[18:19]
	v_lshl_add_u64 v[30:31], v[134:135], 2, v[18:19]
	s_nop 0
	v_lshlrev_b64 v[34:35], 11, v[16:17]
	v_lshl_add_u64 v[34:35], s[68:69], 0, v[34:35]
	v_lshl_add_u64 v[34:35], v[134:135], 1, v[34:35]
	s_waitcnt vmcnt(12)
	v_mov_b32_e32 v18, v212
	v_mov_b32_e32 v19, v213
	v_mov_b32_e32 v20, v214
	v_mov_b32_e32 v21, v215
	v_mov_b32_e32 v22, v216
	v_mov_b32_e32 v23, v217
	v_mov_b32_e32 v24, v218
	v_mov_b32_e32 v25, v219
	v_mov_b32_e32 v26, v220
	v_mov_b32_e32 v27, v221
	v_mov_b32_e32 v28, v222
	v_mov_b32_e32 v29, v223
	v_mov_b32_e32 v30, v224
	v_mov_b32_e32 v31, v225
	v_mov_b32_e32 v32, v226
	v_mov_b32_e32 v33, v227
	v_pk_add_f32 v[10:11], v[10:11], v[20:21]
	v_pk_add_f32 v[8:9], v[8:9], v[18:19]
	s_nop 0
	v_pk_add_f32 v[14:15], v[14:15], v[24:25]
	s_nop 0
	v_pk_add_f32 v[20:21], v[0:1], v[30:31]
	v_cvt_pk_bf16_f32 v0, v8, v9
	v_cvt_pk_bf16_f32 v1, v10, v11
	v_pk_add_f32 v[12:13], v[12:13], v[22:23]
	v_pk_add_f32 v[18:19], v[2:3], v[32:33]
	v_cvt_pk_bf16_f32 v2, v12, v13
	v_cvt_pk_bf16_f32 v3, v14, v15
	global_store_dwordx4 v[34:35], v[0:3], off
	v_lshlrev_b32_e32 v8, 16, v0
	v_lshlrev_b32_e32 v9, 16, v1
	v_and_b32_e32 v0, 0xffff0000, v0
	v_and_b32_e32 v1, 0xffff0000, v1
	v_pk_add_f32 v[6:7], v[6:7], v[28:29]
	v_and_b32_e32 v11, 0xffff0000, v2
	v_mul_f32_e32 v0, v0, v0
	v_mul_f32_e32 v1, v1, v1
	v_pk_add_f32 v[4:5], v[4:5], v[26:27]
	v_lshlrev_b32_e32 v10, 16, v2
	v_lshlrev_b32_e32 v12, 16, v3
	v_and_b32_e32 v13, 0xffff0000, v3
	v_cvt_pk_bf16_f32 v2, v4, v5
	v_cvt_pk_bf16_f32 v3, v6, v7
	v_mul_f32_e32 v6, v11, v11
	v_fmac_f32_e32 v0, v8, v8
	v_fmac_f32_e32 v1, v9, v9
	v_mul_f32_e32 v7, v13, v13
	v_and_b32_e32 v13, 0xffff0000, v2
	v_fmac_f32_e32 v6, v10, v10
	v_add_f32_e32 v0, v0, v1
	v_lshlrev_b32_e32 v11, 16, v2
	v_and_b32_e32 v15, 0xffff0000, v3
	v_fmac_f32_e32 v7, v12, v12
	v_mul_f32_e32 v8, v13, v13
	v_add_f32_e32 v0, v0, v6
	v_cvt_pk_bf16_f32 v4, v20, v21
	v_cvt_pk_bf16_f32 v5, v18, v19
	v_lshlrev_b32_e32 v14, 16, v3
	v_and_b32_e32 v19, 0xffff0000, v4
	v_mul_f32_e32 v9, v15, v15
	v_fmac_f32_e32 v8, v11, v11
	v_add_f32_e32 v0, v0, v7
	v_lshlrev_b32_e32 v18, 16, v4
	v_and_b32_e32 v21, 0xffff0000, v5
	v_mul_f32_e32 v10, v19, v19
	v_fmac_f32_e32 v9, v14, v14
	v_add_f32_e32 v0, v0, v8
	v_lshlrev_b32_e32 v20, 16, v5
	v_mul_f32_e32 v12, v21, v21
	v_fmac_f32_e32 v10, v18, v18
	v_add_f32_e32 v0, v0, v9
	v_add_f32_e32 v0, v0, v10
	v_fmac_f32_e32 v12, v20, v20
	v_add_f32_e32 v0, v0, v12
	v_mov_b32_e32 v1, v0
	s_nop 1
	v_permlane16_swap_b32_e32 v1, v0
	global_store_dwordx4 v[34:35], v[2:5], off offset:256
	s_waitcnt lgkmcnt(0)
	v_add_f32_e32 v0, v0, v1
	v_mov_b32_e32 v1, v0
	s_nop 1
	v_permlane32_swap_b32_e32 v1, v0
	s_and_saveexec_b64 s[8:9], vcc
	s_cbranch_execz .LBB0_475
	v_lshlrev_b64 v[2:3], 6, v[16:17]
	v_lshl_add_u64 v[2:3], s[66:67], 0, v[2:3]
	v_lshl_add_u64 v[2:3], s[6:7], 2, v[2:3]
	s_lshl_b32 s38, s10, 2
	v_lshl_add_u64 v[2:3], v[2:3], 0, s[38:39]
	s_waitcnt lgkmcnt(0)
	v_add_f32_e32 v0, v0, v1
	global_store_dword v[2:3], v0, off
